# GEMM K loops: per-lane LDS fragment-read bases (row + swizzle) precomputed once per tile, halving the address VALU ops issued between MFMAs (8 to 4 per K step)
# speedup vs baseline: 1.0253x; 1.0022x over previous
; #define LAS __attribute__((address_space(3)))
;     ...
;   const int lane = tid & 63, wid = __builtin_amdgcn_readfirstlane(tid >> 6), wr = wid >> 1, wc = wid & 1;
;   const int m0 = mt * 128, n0 = nt * 256;
;   const int r = lane & 31, h = lane >> 5, key = (r >> 2) & 3;
;   constexpr int STG = 24576;
;   const int rowl = lane >> 2, cch = (lane & 3) ^ ((lane >> 4) & 3);
;   const unsigned voffA = (unsigned)(rowl * lda * 2 + cch * 16), voffB = (unsigned)(rowl * K * 2 + cch * 16);
;   const char* Abase = (const char*)(A + (size_t)m0 * lda) + (size_t)(wid * 2) * 32 * lda;
;   const char* Bbase = (const char*)(Bt + (size_t)n0 * K) + (size_t)(wid * 4) * 32 * K;
;   const size_t ablk = (size_t)32 * lda, bblk = (size_t)32 * K;
;   LAS char* lds = (LAS char*)smem;
;   LAS char* ldsA = lds + (wid * 2) * 1024;
;   LAS char* ldsB = lds + 8192 + (wid * 4) * 1024;
;     ...
;   const int x0 = ((0 + h) ^ key) * 16, x1 = ((2 + h) ^ key) * 16;
;   const int a_rd = (wr * 64 + r) * 64, b_rd = 8192 + (wc * 128 + r) * 64;
;   f32x16 acc[2][4];
; #pragma unroll
;   for (int i = 0; i < 2; ++i)
; #pragma unroll
;     for (int j = 0; j < 4; ++j)
; #pragma unroll
;       for (int e = 0; e < 16; ++e) acc[i][j][e] = 0.f;
;   const int nk = K >> 5;
;   DMA_STEP_(0, 0);
;   DMA_STEP_(1, STG);
;   asm volatile("s_waitcnt vmcnt(6)" ::: "memory");
;   __builtin_amdgcn_s_barrier();
;   asm volatile("" ::: "memory");
;   int s0 = 0, s2 = 2 * STG;
;   for (int kt = 0; kt < nk; ++kt) {
;     const int kn = (kt + 2 < nk) ? (kt + 2) : (nk - 1);
;     const LAS char* cur = lds + s0;
;     bf16x8 af[2][2], bfr[2][4];
; #pragma unroll
;     for (int kk = 0; kk < 2; ++kk) {
;       const int xo = kk ? x1 : x0;
;       af[kk][0] = *(const LAS bf16x8*)(cur + a_rd + xo);
;       bfr[kk][0] = *(const LAS bf16x8*)(cur + b_rd + xo);
;       bfr[kk][1] = *(const LAS bf16x8*)(cur + b_rd + 2048 + xo);
;       af[kk][1] = *(const LAS bf16x8*)(cur + a_rd + 2048 + xo);
;       bfr[kk][2] = *(const LAS bf16x8*)(cur + b_rd + 4096 + xo);
;       bfr[kk][3] = *(const LAS bf16x8*)(cur + b_rd + 6144 + xo);
;     }
;     DMA_STEP_(kn, s2);
.LBB0_20:
	s_ashr_i32 s10, s23, 31
	s_lshr_b32 s10, s10, 27
	s_add_i32 s10, s23, s10
	s_ashr_i32 s10, s10, 5
	v_readlane_b32 s11, v252, 18
	v_mov_b32_e32 v189, v188
	s_lshl_b32 s11, s10, s11
	v_readlane_b32 s12, v252, 41
	s_add_i32 s11, s11, s12
	v_readfirstlane_b32 s44, v189
	s_ashr_i32 s46, s44, 6
	s_lshl_b32 s12, s23, 7
	s_lshl_b32 s11, s11, 10
	s_and_b32 s12, s12, 0x380
	s_lshl_b32 s28, s46, 1
	s_or_b32 s12, s11, s12
	s_lshl_b32 s10, s10, 10
	s_lshl_b32 s11, s23, 5
	s_ashr_i32 s29, s28, 31
	s_sub_i32 s10, s11, s10
	s_lshl_b64 s[40:41], s[28:29], 15
	s_lshl_b32 s28, s46, 2
	s_ashr_i32 s11, s44, 1
	s_and_b32 s14, s10, 0xffffff00
	v_and_b32_e32 v0, 31, v189
	s_ashr_i32 s29, s28, 31
	s_lshl_b32 s10, s46, 12
	s_andn2_b32 s11, s11, 63
	v_lshlrev_b32_e32 v2, 4, v189
	s_ashr_i32 s13, s12, 31
	s_lshl_b64 s[42:43], s[28:29], 10
	s_add_i32 s29, s10, 16
	v_or_b32_e32 v197, s11, v0
	s_lshl_b32 s11, s46, 7
	v_bitop3_b32 v2, v2, 48, v189 bitop3:0x48
	v_lshlrev_b32_e32 v3, 9, v189
	s_ashr_i32 s15, s14, 31
	s_add_i32 s10, s29, 0x2000
	s_and_b32 s28, s11, 0x80
	s_movk_i32 s11, 0x7800
	s_lshl_b64 s[44:45], s[12:13], 11
	v_or_b32_e32 v4, s28, v0
	v_and_or_b32 v0, v3, s11, v2
	v_lshlrev_b32_e32 v10, 4, v189
	v_and_b32_e32 v10, 0x3c0, v10
	v_or_b32_e32 v10, v10, v2
	v_mov_b32_e32 v11, 0
	s_add_u32 s11, s21, s44
	s_addc_u32 s13, s22, s45
	s_add_u32 s40, s11, s40
	s_addc_u32 s41, s13, s41
	s_lshl_b64 s[44:45], s[14:15], 6
	s_add_u32 s11, s17, s44
	s_addc_u32 s13, s18, s45
	s_add_u32 s42, s11, s42
	s_addc_u32 s43, s13, s43
	s_lshl_b32 s11, s46, 11
	s_sub_i32 s13, s29, s11
	v_lshl_add_u64 v[192:193], s[40:41], 0, v[0:1]
	s_mov_b32 m0, s13
	v_lshl_add_u64 v[2:3], v[192:193], 0, s[72:73]
	global_load_lds_dwordx4 v0, s[40:41]
	s_add_i32 m0, s13, 0x400
	v_lshl_add_u64 v[194:195], s[42:43], 0, v[10:11]
	global_load_lds_dwordx4 v[2:3], off
	s_mov_b32 m0, s10
	s_nop 0
	global_load_lds_dwordx4 v[194:195], off
	global_load_lds_dwordx4 v[194:195], off offset:1024
	global_load_lds_dwordx4 v[194:195], off offset:2048
	global_load_lds_dwordx4 v[194:195], off offset:3072
	s_mov_b64 s[10:11], 0x10000
	s_mov_b64 s[10:11], 0x18000
	s_mov_b64 s[10:11], 0x8040
	s_add_i32 m0, s13, 0x6000
	v_lshl_add_u64 v[2:3], v[192:193], 0, 64
	global_load_lds_dwordx4 v[2:3], off
	v_lshl_add_u64 v[2:3], v[192:193], 0, s[10:11]
	s_add_i32 m0, s13, 0x6400
	v_bfe_u32 v196, v189, 5, 1
	global_load_lds_dwordx4 v[2:3], off
	s_add_i32 m0, s29, 0x8000
	s_mov_b32 s100, 0x10000
	v_lshl_add_u64 v[2:3], v[194:195], 0, s[100:101]
	global_load_lds_dwordx4 v[2:3], off
	global_load_lds_dwordx4 v[2:3], off offset:1024
	global_load_lds_dwordx4 v[2:3], off offset:2048
	global_load_lds_dwordx4 v[2:3], off offset:3072
	s_mov_b64 s[10:11], 0x10040
	s_mov_b64 s[10:11], 0x18040
	v_lshlrev_b32_e32 v218, 6, v4
	v_bfe_u32 v4, v189, 2, 2
	v_lshrrev_b32_e32 v5, 5, v189
	s_lshl_b32 s100, s100, 1
	v_lshl_add_u64 v[194:195], v[194:195], 0, s[100:101]
	s_waitcnt vmcnt(6)
	s_barrier
	v_bitop3_b32 v2, v196, v4, 2 bitop3:0x36
	v_bitop3_b32 v0, v5, v4, 1 bitop3:0x6c
	v_lshlrev_b32_e32 v220, 4, v2
	v_mov_b32_e32 v2, 0
	v_lshlrev_b32_e32 v219, 6, v197
	v_lshlrev_b32_e32 v0, 4, v0
	s_mov_b32 s41, 0xc000
	s_mov_b32 s40, 0
	s_mov_b32 s42, 0
	v_mov_b32_e32 v3, v2
	v_mov_b32_e32 v4, v2
	v_mov_b32_e32 v5, v2
	v_mov_b32_e32 v6, v2
	v_mov_b32_e32 v7, v2
	v_mov_b32_e32 v8, v2
	v_mov_b32_e32 v9, v2
	v_mov_b32_e32 v10, v2
	v_mov_b32_e32 v11, v2
	v_mov_b32_e32 v12, v2
	v_mov_b32_e32 v13, v2
	v_mov_b32_e32 v14, v2
	v_mov_b32_e32 v15, v2
	v_mov_b32_e32 v16, v2
	v_mov_b32_e32 v17, v2
	v_mov_b32_e32 v18, v2
	v_mov_b32_e32 v19, v2
	v_mov_b32_e32 v20, v2
	v_mov_b32_e32 v21, v2
	v_mov_b32_e32 v22, v2
	v_mov_b32_e32 v23, v2
	v_mov_b32_e32 v24, v2
	v_mov_b32_e32 v25, v2
	v_mov_b32_e32 v26, v2
	v_mov_b32_e32 v27, v2
	v_mov_b32_e32 v28, v2
	v_mov_b32_e32 v29, v2
	v_mov_b32_e32 v30, v2
	v_mov_b32_e32 v31, v2
	v_mov_b32_e32 v32, v2
	v_mov_b32_e32 v33, v2
	v_mov_b32_e32 v50, v2
	v_mov_b32_e32 v51, v2
	v_mov_b32_e32 v52, v2
	v_mov_b32_e32 v53, v2
	v_mov_b32_e32 v54, v2
	v_mov_b32_e32 v55, v2
	v_mov_b32_e32 v56, v2
	v_mov_b32_e32 v57, v2
	v_mov_b32_e32 v58, v2
	v_mov_b32_e32 v59, v2
	v_mov_b32_e32 v60, v2
	v_mov_b32_e32 v61, v2
	v_mov_b32_e32 v62, v2
	v_mov_b32_e32 v63, v2
	v_mov_b32_e32 v64, v2
	v_mov_b32_e32 v65, v2
	v_mov_b32_e32 v82, v2
	v_mov_b32_e32 v83, v2
	v_mov_b32_e32 v84, v2
	v_mov_b32_e32 v85, v2
	v_mov_b32_e32 v86, v2
	v_mov_b32_e32 v87, v2
	v_mov_b32_e32 v88, v2
	v_mov_b32_e32 v89, v2
	s_waitcnt vmcnt(0)
	v_mov_b32_e32 v90, v2
	v_mov_b32_e32 v91, v2
	v_mov_b32_e32 v92, v2
	v_mov_b32_e32 v93, v2
	v_mov_b32_e32 v94, v2
	v_mov_b32_e32 v95, v2
	v_mov_b32_e32 v96, v2
	v_mov_b32_e32 v97, v2
	v_mov_b32_e32 v34, v2
	v_mov_b32_e32 v35, v2
	v_mov_b32_e32 v36, v2
	v_mov_b32_e32 v37, v2
	v_mov_b32_e32 v38, v2
	v_mov_b32_e32 v39, v2
	v_mov_b32_e32 v40, v2
	v_mov_b32_e32 v41, v2
	v_mov_b32_e32 v42, v2
	v_mov_b32_e32 v43, v2
	v_mov_b32_e32 v44, v2
	v_mov_b32_e32 v45, v2
	v_mov_b32_e32 v46, v2
	v_mov_b32_e32 v47, v2
	v_mov_b32_e32 v48, v2
	v_mov_b32_e32 v49, v2
	v_mov_b32_e32 v66, v2
	v_mov_b32_e32 v67, v2
	v_mov_b32_e32 v68, v2
	v_mov_b32_e32 v69, v2
	v_mov_b32_e32 v70, v2
	v_mov_b32_e32 v71, v2
	v_mov_b32_e32 v72, v2
	v_mov_b32_e32 v73, v2
	v_mov_b32_e32 v74, v2
	v_mov_b32_e32 v75, v2
	v_mov_b32_e32 v76, v2
	v_mov_b32_e32 v77, v2
	v_mov_b32_e32 v78, v2
	v_mov_b32_e32 v79, v2
	v_mov_b32_e32 v80, v2
	v_mov_b32_e32 v81, v2
	v_mov_b32_e32 v98, v2
	v_mov_b32_e32 v99, v2
	v_mov_b32_e32 v100, v2
	v_mov_b32_e32 v101, v2
	v_mov_b32_e32 v102, v2
	v_mov_b32_e32 v103, v2
	v_mov_b32_e32 v104, v2
	v_mov_b32_e32 v105, v2
	v_mov_b32_e32 v106, v2
	v_mov_b32_e32 v107, v2
	v_mov_b32_e32 v108, v2
	v_mov_b32_e32 v109, v2
	v_mov_b32_e32 v110, v2
	v_mov_b32_e32 v111, v2
	v_mov_b32_e32 v112, v2
	v_mov_b32_e32 v113, v2
	v_mov_b32_e32 v114, v2
	v_mov_b32_e32 v115, v2
	v_mov_b32_e32 v116, v2
	v_mov_b32_e32 v117, v2
	v_mov_b32_e32 v118, v2
	v_mov_b32_e32 v119, v2
	v_mov_b32_e32 v120, v2
	v_mov_b32_e32 v121, v2
	v_mov_b32_e32 v122, v2
	v_mov_b32_e32 v123, v2
	v_mov_b32_e32 v124, v2
	v_mov_b32_e32 v125, v2
	v_mov_b32_e32 v126, v2
	v_mov_b32_e32 v127, v2
	v_mov_b32_e32 v128, v2
	v_mov_b32_e32 v129, v2
	v_add_u32_e32 v226, v219, v0
	v_add_u32_e32 v227, v218, v0
	v_add_u32_e32 v228, v219, v220
	v_add_u32_e32 v229, v218, v220
	v_add_u32_e32 v158, 16, v226
	v_add_u32_e32 v170, 16, v227
	ds_read_b128 v[154:157], v158
	ds_read_b128 v[182:185], v170 offset:8192
	ds_read_b128 v[178:181], v170 offset:10240
	ds_read_b128 v[158:161], v158 offset:2048
	ds_read_b128 v[174:177], v170 offset:12288
	ds_read_b128 v[170:173], v170 offset:14336
	s_setprio 1
; #define LAS __attribute__((address_space(3)))
; DI f32x16 mfma32(bf16x8 a, bf16x8 b, f32x16 c) { return __builtin_amdgcn_mfma_f32_32x32x16_bf16(a, b, c, 0, 0, 0); }
;     ...
;   for (int kt = 0; kt < nk; ++kt) {
;     const int kn = (kt + 2 < nk) ? (kt + 2) : (nk - 1);
;     const LAS char* cur = lds + s0;
;     bf16x8 af[2][2], bfr[2][4];
; #pragma unroll
;     for (int kk = 0; kk < 2; ++kk) {
;       const int xo = kk ? x1 : x0;
;       af[kk][0] = *(const LAS bf16x8*)(cur + a_rd + xo);
;       bfr[kk][0] = *(const LAS bf16x8*)(cur + b_rd + xo);
;       bfr[kk][1] = *(const LAS bf16x8*)(cur + b_rd + 2048 + xo);
;       af[kk][1] = *(const LAS bf16x8*)(cur + a_rd + 2048 + xo);
;       bfr[kk][2] = *(const LAS bf16x8*)(cur + b_rd + 4096 + xo);
;       bfr[kk][3] = *(const LAS bf16x8*)(cur + b_rd + 6144 + xo);
;     }
;     DMA_STEP_(kn, s2);
; #pragma unroll
;     for (int kk = 0; kk < 2; ++kk) {
;       acc[0][0] = mfma32(bfr[kk][0], af[kk][0], acc[0][0]); acc[0][1] = mfma32(bfr[kk][1], af[kk][0], acc[0][1]);
;       acc[1][0] = mfma32(bfr[kk][0], af[kk][1], acc[1][0]); acc[1][1] = mfma32(bfr[kk][1], af[kk][1], acc[1][1]);
;       acc[0][2] = mfma32(bfr[kk][2], af[kk][0], acc[0][2]); acc[0][3] = mfma32(bfr[kk][3], af[kk][0], acc[0][3]);
;       acc[1][2] = mfma32(bfr[kk][2], af[kk][1], acc[1][2]); acc[1][3] = mfma32(bfr[kk][3], af[kk][1], acc[1][3]);
;     }
;     __builtin_amdgcn_sched_group_barrier(0x100, 12, 0);
;     __builtin_amdgcn_sched_group_barrier(0x010, 6, 0);
;     __builtin_amdgcn_sched_group_barrier(0x008, 16, 0);
;     asm volatile("s_waitcnt vmcnt(6) lgkmcnt(0)" ::: "memory");
;     __builtin_amdgcn_s_barrier();
;     asm volatile("" ::: "memory");
;     s0 = (s0 == 2 * STG) ? 0 : s0 + STG;
;     s2 = (s2 == 2 * STG) ? 0 : s2 + STG;
;   }
.LBB0_21:
	s_add_i32 s11, s42, 16
	s_mov_b32 s10, s40
	v_add_u32_e32 v142, s11, v228
	v_add_u32_e32 v150, s11, v229
	s_min_u32 s10, s10, 29
	s_lshl_b32 s70, s10, 6
	ds_read_b128 v[138:141], v142
	ds_read_b128 v[162:165], v150 offset:8192
	ds_read_b128 v[166:169], v150 offset:10240
	ds_read_b128 v[142:145], v142 offset:2048
	ds_read_b128 v[146:149], v150 offset:12288
	ds_read_b128 v[150:153], v150 offset:14336
	v_lshl_add_u64 v[222:223], v[192:193], 0, s[70:71]
	s_add_i32 s10, s13, s41
	v_lshl_add_u64 v[224:225], v[222:223], 0, s[24:25]
	s_mov_b32 m0, s10
	v_lshl_add_u64 v[222:223], v[222:223], 0, s[38:39]
	s_mul_i32 s100, s70, 0x400
	s_waitcnt lgkmcnt(6)
	v_mfma_f32_32x32x16_bf16 v[114:129], v[182:185], v[154:157], v[114:129]
	global_load_lds_dwordx4 v[224:225], off
	s_add_i32 m0, s10, 0x400
	v_mfma_f32_32x32x16_bf16 v[98:113], v[178:181], v[154:157], v[98:113]
	global_load_lds_dwordx4 v[222:223], off
	v_lshl_add_u64 v[224:225], v[194:195], 0, s[100:101]
	s_add_i32 s10, s29, s41
	s_add_i32 m0, s10, 0x2000
	v_mfma_f32_32x32x16_bf16 v[66:81], v[182:185], v[158:161], v[66:81]
	global_load_lds_dwordx4 v[224:225], off
	v_mfma_f32_32x32x16_bf16 v[34:49], v[178:181], v[158:161], v[34:49]
	global_load_lds_dwordx4 v[224:225], off offset:1024
	v_mfma_f32_32x32x16_bf16 v[82:97], v[174:177], v[154:157], v[82:97]
	global_load_lds_dwordx4 v[224:225], off offset:2048
	v_mfma_f32_32x32x16_bf16 v[50:65], v[170:173], v[154:157], v[50:65]
	global_load_lds_dwordx4 v[224:225], off offset:3072
	v_mfma_f32_32x32x16_bf16 v[18:33], v[174:177], v[158:161], v[18:33]
	s_add_i32 s10, s42, 0x6000
	s_cmpk_lg_u32 s42, 0xc000
	s_cselect_b32 s42, s10, 0
	s_add_i32 s10, s41, 0x6000
	s_cmpk_lg_u32 s41, 0xc000
	s_cselect_b32 s41, s10, 0
	v_mfma_f32_32x32x16_bf16 v[2:17], v[170:173], v[158:161], v[2:17]
	s_add_i32 s11, s42, 16
	s_waitcnt vmcnt(6) lgkmcnt(0)
	s_barrier
	v_add_u32_e32 v158, s11, v226
	v_add_u32_e32 v170, s11, v227
	ds_read_b128 v[154:157], v158
	ds_read_b128 v[182:185], v170 offset:8192
	ds_read_b128 v[178:181], v170 offset:10240
	ds_read_b128 v[158:161], v158 offset:2048
	ds_read_b128 v[174:177], v170 offset:12288
	ds_read_b128 v[170:173], v170 offset:14336
	v_mfma_f32_32x32x16_bf16 v[114:129], v[162:165], v[138:141], v[114:129]
	v_mfma_f32_32x32x16_bf16 v[98:113], v[166:169], v[138:141], v[98:113]
	v_mfma_f32_32x32x16_bf16 v[66:81], v[162:165], v[142:145], v[66:81]
	v_mfma_f32_32x32x16_bf16 v[34:49], v[166:169], v[142:145], v[34:49]
	v_mfma_f32_32x32x16_bf16 v[82:97], v[146:149], v[138:141], v[82:97]
	v_mfma_f32_32x32x16_bf16 v[50:65], v[150:153], v[138:141], v[50:65]
	v_mfma_f32_32x32x16_bf16 v[18:33], v[146:149], v[142:145], v[18:33]
	v_mfma_f32_32x32x16_bf16 v[2:17], v[150:153], v[142:145], v[2:17]
	s_add_i32 s11, s42, 16
	s_add_i32 s10, s40, 1
	v_add_u32_e32 v142, s11, v228
	v_add_u32_e32 v150, s11, v229
	s_min_u32 s10, s10, 29
	s_lshl_b32 s70, s10, 6
	ds_read_b128 v[138:141], v142
	ds_read_b128 v[162:165], v150 offset:8192
	ds_read_b128 v[166:169], v150 offset:10240
	ds_read_b128 v[142:145], v142 offset:2048
	ds_read_b128 v[146:149], v150 offset:12288
	ds_read_b128 v[150:153], v150 offset:14336
	v_lshl_add_u64 v[222:223], v[192:193], 0, s[70:71]
	s_add_i32 s10, s13, s41
	v_lshl_add_u64 v[224:225], v[222:223], 0, s[24:25]
	s_mov_b32 m0, s10
	v_lshl_add_u64 v[222:223], v[222:223], 0, s[38:39]
	s_mul_i32 s100, s70, 0x400
	s_waitcnt lgkmcnt(6)
	v_mfma_f32_32x32x16_bf16 v[114:129], v[182:185], v[154:157], v[114:129]
	global_load_lds_dwordx4 v[224:225], off
	s_add_i32 m0, s10, 0x400
	v_mfma_f32_32x32x16_bf16 v[98:113], v[178:181], v[154:157], v[98:113]
	global_load_lds_dwordx4 v[222:223], off
	v_lshl_add_u64 v[224:225], v[194:195], 0, s[100:101]
	s_add_i32 s10, s29, s41
	s_add_i32 m0, s10, 0x2000
	v_mfma_f32_32x32x16_bf16 v[66:81], v[182:185], v[158:161], v[66:81]
	global_load_lds_dwordx4 v[224:225], off
	v_mfma_f32_32x32x16_bf16 v[34:49], v[178:181], v[158:161], v[34:49]
	global_load_lds_dwordx4 v[224:225], off offset:1024
	v_mfma_f32_32x32x16_bf16 v[82:97], v[174:177], v[154:157], v[82:97]
	global_load_lds_dwordx4 v[224:225], off offset:2048
	v_mfma_f32_32x32x16_bf16 v[50:65], v[170:173], v[154:157], v[50:65]
	global_load_lds_dwordx4 v[224:225], off offset:3072
	v_mfma_f32_32x32x16_bf16 v[18:33], v[174:177], v[158:161], v[18:33]
	s_add_i32 s10, s42, 0x6000
	s_cmpk_lg_u32 s42, 0xc000
	s_cselect_b32 s42, s10, 0
	s_add_i32 s10, s41, 0x6000
	s_cmpk_lg_u32 s41, 0xc000
	s_cselect_b32 s41, s10, 0
	v_mfma_f32_32x32x16_bf16 v[2:17], v[170:173], v[158:161], v[2:17]
	s_add_i32 s11, s42, 16
	s_waitcnt vmcnt(6) lgkmcnt(0)
	s_barrier
	v_add_u32_e32 v158, s11, v226
	v_add_u32_e32 v170, s11, v227
	ds_read_b128 v[154:157], v158
	ds_read_b128 v[182:185], v170 offset:8192
	ds_read_b128 v[178:181], v170 offset:10240
	ds_read_b128 v[158:161], v158 offset:2048
	ds_read_b128 v[174:177], v170 offset:12288
	ds_read_b128 v[170:173], v170 offset:14336
	v_mfma_f32_32x32x16_bf16 v[114:129], v[162:165], v[138:141], v[114:129]
	v_mfma_f32_32x32x16_bf16 v[98:113], v[166:169], v[138:141], v[98:113]
	v_mfma_f32_32x32x16_bf16 v[66:81], v[162:165], v[142:145], v[66:81]
	v_mfma_f32_32x32x16_bf16 v[34:49], v[166:169], v[142:145], v[34:49]
	v_mfma_f32_32x32x16_bf16 v[82:97], v[146:149], v[138:141], v[82:97]
	v_mfma_f32_32x32x16_bf16 v[50:65], v[150:153], v[138:141], v[50:65]
	v_mfma_f32_32x32x16_bf16 v[18:33], v[146:149], v[142:145], v[18:33]
	v_mfma_f32_32x32x16_bf16 v[2:17], v[150:153], v[142:145], v[2:17]
	s_add_i32 s40, s40, 2
	s_cmp_lg_u32 s40, 30
	s_cbranch_scc1 .LBB0_21
; #define LAS __attribute__((address_space(3)))
; DI unsigned pk2(float a, float b) { f32x2 v = {a, b}; bf2_t r = __builtin_convertvector(v, bf2_t); return __builtin_bit_cast(unsigned, r); }
;     ...
;   for (int kt = 0; kt < nk; ++kt) {
;     const int kn = (kt + 2 < nk) ? (kt + 2) : (nk - 1);
;     const LAS char* cur = lds + s0;
;     bf16x8 af[2][2], bfr[2][4];
; #pragma unroll
;     for (int kk = 0; kk < 2; ++kk) {
;       const int xo = kk ? x1 : x0;
;       af[kk][0] = *(const LAS bf16x8*)(cur + a_rd + xo);
;       bfr[kk][0] = *(const LAS bf16x8*)(cur + b_rd + xo);
;       bfr[kk][1] = *(const LAS bf16x8*)(cur + b_rd + 2048 + xo);
;       af[kk][1] = *(const LAS bf16x8*)(cur + a_rd + 2048 + xo);
;       bfr[kk][2] = *(const LAS bf16x8*)(cur + b_rd + 4096 + xo);
;       bfr[kk][3] = *(const LAS bf16x8*)(cur + b_rd + 6144 + xo);
;     }
;     DMA_STEP_(kn, s2);
; #pragma unroll
;     for (int kk = 0; kk < 2; ++kk) {
;       acc[0][0] = mfma32(bfr[kk][0], af[kk][0], acc[0][0]); acc[0][1] = mfma32(bfr[kk][1], af[kk][0], acc[0][1]);
;       acc[1][0] = mfma32(bfr[kk][0], af[kk][1], acc[1][0]); acc[1][1] = mfma32(bfr[kk][1], af[kk][1], acc[1][1]);
;       acc[0][2] = mfma32(bfr[kk][2], af[kk][0], acc[0][2]); acc[0][3] = mfma32(bfr[kk][3], af[kk][0], acc[0][3]);
;       acc[1][2] = mfma32(bfr[kk][2], af[kk][1], acc[1][2]); acc[1][3] = mfma32(bfr[kk][3], af[kk][1], acc[1][3]);
;     }
;     __builtin_amdgcn_sched_group_barrier(0x100, 12, 0);
;     __builtin_amdgcn_sched_group_barrier(0x010, 6, 0);
;     __builtin_amdgcn_sched_group_barrier(0x008, 16, 0);
;     asm volatile("s_waitcnt vmcnt(6) lgkmcnt(0)" ::: "memory");
;     __builtin_amdgcn_s_barrier();
;     asm volatile("" ::: "memory");
;     s0 = (s0 == 2 * STG) ? 0 : s0 + STG;
;     s2 = (s2 == 2 * STG) ? 0 : s2 + STG;
;   }
;   asm volatile("s_waitcnt vmcnt(0)" ::: "memory");
;   __builtin_amdgcn_s_barrier();
;   asm volatile("" ::: "memory");
;     ...
;   {
;     const int h = lane >> 5, cl = lane & 31;
; #pragma unroll
;     for (int i = 0; i < 2; ++i)
; #pragma unroll
;       for (int j = 0; j < 4; ++j)
; #pragma unroll
;         for (int g = 0; g < 4; ++g) {
;           u32x2 w; w.x = pk2(acc[i][j][4 * g], acc[i][j][4 * g + 1]); w.y = pk2(acc[i][j][4 * g + 2], acc[i][j][4 * g + 3]);
;           *(u32x2*)(smem + (wr * 64 + i * 32 + cl) * 528 + (wc * 128 + j * 32 + 8 * g + 4 * h) * 2) = w;
;         }
	s_add_i32 s11, s42, 16
	v_add_u32_e32 v142, s11, v228
	v_add_u32_e32 v150, s11, v229
	ds_read_b128 v[138:141], v142
	ds_read_b128 v[162:165], v150 offset:8192
	ds_read_b128 v[166:169], v150 offset:10240
	ds_read_b128 v[142:145], v142 offset:2048
	ds_read_b128 v[146:149], v150 offset:12288
	ds_read_b128 v[150:153], v150 offset:14336
	s_waitcnt lgkmcnt(6)
	v_mfma_f32_32x32x16_bf16 v[114:129], v[182:185], v[154:157], v[114:129]
	v_mfma_f32_32x32x16_bf16 v[98:113], v[178:181], v[154:157], v[98:113]
	v_mfma_f32_32x32x16_bf16 v[66:81], v[182:185], v[158:161], v[66:81]
	v_mfma_f32_32x32x16_bf16 v[34:49], v[178:181], v[158:161], v[34:49]
	v_mfma_f32_32x32x16_bf16 v[82:97], v[174:177], v[154:157], v[82:97]
	v_mfma_f32_32x32x16_bf16 v[50:65], v[170:173], v[154:157], v[50:65]
	v_mfma_f32_32x32x16_bf16 v[18:33], v[174:177], v[158:161], v[18:33]
	s_add_i32 s10, s42, 0x6000
	s_cmpk_lg_u32 s42, 0xc000
	s_cselect_b32 s42, s10, 0
	v_mfma_f32_32x32x16_bf16 v[2:17], v[170:173], v[158:161], v[2:17]
	s_add_i32 s11, s42, 16
	s_waitcnt vmcnt(0) lgkmcnt(0)
	s_barrier
	v_add_u32_e32 v158, s11, v226
	v_add_u32_e32 v170, s11, v227
	ds_read_b128 v[154:157], v158
	ds_read_b128 v[182:185], v170 offset:8192
	ds_read_b128 v[178:181], v170 offset:10240
	ds_read_b128 v[158:161], v158 offset:2048
	ds_read_b128 v[174:177], v170 offset:12288
	ds_read_b128 v[170:173], v170 offset:14336
	v_mfma_f32_32x32x16_bf16 v[114:129], v[162:165], v[138:141], v[114:129]
	v_mfma_f32_32x32x16_bf16 v[98:113], v[166:169], v[138:141], v[98:113]
	v_mfma_f32_32x32x16_bf16 v[66:81], v[162:165], v[142:145], v[66:81]
	v_mfma_f32_32x32x16_bf16 v[34:49], v[166:169], v[142:145], v[34:49]
	v_mfma_f32_32x32x16_bf16 v[82:97], v[146:149], v[138:141], v[82:97]
	v_mfma_f32_32x32x16_bf16 v[50:65], v[150:153], v[138:141], v[50:65]
	v_mfma_f32_32x32x16_bf16 v[18:33], v[146:149], v[142:145], v[18:33]
	v_mfma_f32_32x32x16_bf16 v[2:17], v[150:153], v[142:145], v[2:17]
	s_add_i32 s11, s42, 16
	v_add_u32_e32 v142, s11, v228
	v_add_u32_e32 v150, s11, v229
	ds_read_b128 v[138:141], v142
	ds_read_b128 v[162:165], v150 offset:8192
	ds_read_b128 v[166:169], v150 offset:10240
	ds_read_b128 v[142:145], v142 offset:2048
	ds_read_b128 v[146:149], v150 offset:12288
	ds_read_b128 v[150:153], v150 offset:14336
	s_waitcnt lgkmcnt(6)
	v_mfma_f32_32x32x16_bf16 v[114:129], v[182:185], v[154:157], v[114:129]
	v_mfma_f32_32x32x16_bf16 v[98:113], v[178:181], v[154:157], v[98:113]
	v_mfma_f32_32x32x16_bf16 v[66:81], v[182:185], v[158:161], v[66:81]
	v_mfma_f32_32x32x16_bf16 v[34:49], v[178:181], v[158:161], v[34:49]
	v_mfma_f32_32x32x16_bf16 v[82:97], v[174:177], v[154:157], v[82:97]
	v_mfma_f32_32x32x16_bf16 v[50:65], v[170:173], v[154:157], v[50:65]
	v_mfma_f32_32x32x16_bf16 v[18:33], v[174:177], v[158:161], v[18:33]
	v_mfma_f32_32x32x16_bf16 v[2:17], v[170:173], v[158:161], v[2:17]
	s_waitcnt lgkmcnt(0)
	v_mfma_f32_32x32x16_bf16 v[114:129], v[162:165], v[138:141], v[114:129]
	v_mfma_f32_32x32x16_bf16 v[98:113], v[166:169], v[138:141], v[98:113]
	v_mfma_f32_32x32x16_bf16 v[66:81], v[162:165], v[142:145], v[66:81]
	v_mfma_f32_32x32x16_bf16 v[34:49], v[166:169], v[142:145], v[34:49]
	v_mfma_f32_32x32x16_bf16 v[82:97], v[146:149], v[138:141], v[82:97]
	v_mfma_f32_32x32x16_bf16 v[50:65], v[150:153], v[138:141], v[50:65]
	v_mfma_f32_32x32x16_bf16 v[18:33], v[146:149], v[142:145], v[18:33]
	v_mfma_f32_32x32x16_bf16 v[2:17], v[150:153], v[142:145], v[2:17]
	s_waitcnt lgkmcnt(0)
	s_setprio 0
	v_mul_lo_u32 v0, v197, s55
	v_add_u32_e32 v0, 16, v0
	s_nop 1
	v_cvt_pk_bf16_f32 v114, v114, v115
	v_cvt_pk_bf16_f32 v115, v116, v117
	v_lshlrev_b32_e32 v116, 3, v196
	s_lshl_b32 s10, s28, 1
	v_add3_u32 v0, v0, v116, s10
	v_cvt_pk_bf16_f32 v116, v118, v119
	v_cvt_pk_bf16_f32 v117, v120, v121
	v_cvt_pk_bf16_f32 v98, v98, v99
	v_cvt_pk_bf16_f32 v99, v100, v101
	v_cvt_pk_bf16_f32 v100, v102, v103
	v_cvt_pk_bf16_f32 v101, v104, v105
	v_cvt_pk_bf16_f32 v82, v82, v83
	v_cvt_pk_bf16_f32 v83, v84, v85
	v_cvt_pk_bf16_f32 v84, v86, v87
	v_cvt_pk_bf16_f32 v85, v88, v89
	v_cvt_pk_bf16_f32 v50, v50, v51
	v_cvt_pk_bf16_f32 v51, v52, v53
	v_cvt_pk_bf16_f32 v52, v54, v55
	v_cvt_pk_bf16_f32 v53, v56, v57
	s_waitcnt vmcnt(0)
	s_barrier
	ds_write2_b64 v0, v[114:115], v[116:117] offset1:2
	v_cvt_pk_bf16_f32 v114, v122, v123
	v_cvt_pk_bf16_f32 v115, v124, v125
	v_cvt_pk_bf16_f32 v116, v126, v127
	v_cvt_pk_bf16_f32 v117, v128, v129
	ds_write2_b64 v0, v[98:99], v[100:101] offset0:8 offset1:10
	v_cvt_pk_bf16_f32 v98, v106, v107
	v_cvt_pk_bf16_f32 v99, v108, v109
	v_cvt_pk_bf16_f32 v100, v110, v111
	v_cvt_pk_bf16_f32 v101, v112, v113
	ds_write2_b64 v0, v[82:83], v[84:85] offset0:16 offset1:18
	v_cvt_pk_bf16_f32 v82, v90, v91
	v_cvt_pk_bf16_f32 v83, v92, v93
	v_cvt_pk_bf16_f32 v84, v94, v95
	v_cvt_pk_bf16_f32 v85, v96, v97
	ds_write2_b64 v0, v[50:51], v[52:53] offset0:24 offset1:26
	v_cvt_pk_bf16_f32 v50, v58, v59
	v_cvt_pk_bf16_f32 v51, v60, v61
	v_cvt_pk_bf16_f32 v52, v62, v63
	v_cvt_pk_bf16_f32 v53, v64, v65
	ds_write2_b64 v0, v[114:115], v[116:117] offset0:4 offset1:6
	ds_write2_b64 v0, v[98:99], v[100:101] offset0:12 offset1:14
	ds_write2_b64 v0, v[82:83], v[84:85] offset0:20 offset1:22
	ds_write2_b64 v0, v[50:51], v[52:53] offset0:28 offset1:30
	v_cvt_pk_bf16_f32 v50, v66, v67
	v_cvt_pk_bf16_f32 v51, v68, v69
	v_cvt_pk_bf16_f32 v52, v70, v71
	v_cvt_pk_bf16_f32 v53, v72, v73
	v_add_u32_e32 v0, 0x4000, v0
	v_cvt_pk_bf16_f32 v34, v34, v35
	v_cvt_pk_bf16_f32 v35, v36, v37
	v_cvt_pk_bf16_f32 v36, v38, v39
	v_cvt_pk_bf16_f32 v37, v40, v41
	v_cvt_pk_bf16_f32 v18, v18, v19
	v_cvt_pk_bf16_f32 v19, v20, v21
	v_cvt_pk_bf16_f32 v20, v22, v23
	v_cvt_pk_bf16_f32 v21, v24, v25
	v_cvt_pk_bf16_f32 v2, v2, v3
	v_cvt_pk_bf16_f32 v3, v4, v5
	v_cvt_pk_bf16_f32 v4, v6, v7
	v_cvt_pk_bf16_f32 v5, v8, v9
	ds_write2_b64 v0, v[50:51], v[52:53] offset0:64 offset1:66
	v_cvt_pk_bf16_f32 v50, v74, v75
	v_cvt_pk_bf16_f32 v51, v76, v77
	v_cvt_pk_bf16_f32 v52, v78, v79
	v_cvt_pk_bf16_f32 v53, v80, v81
	ds_write2_b64 v0, v[34:35], v[36:37] offset0:72 offset1:74
	v_cvt_pk_bf16_f32 v34, v42, v43
	v_cvt_pk_bf16_f32 v35, v44, v45
	v_cvt_pk_bf16_f32 v36, v46, v47
	v_cvt_pk_bf16_f32 v37, v48, v49
	ds_write2_b64 v0, v[18:19], v[20:21] offset0:80 offset1:82
	v_cvt_pk_bf16_f32 v18, v26, v27
	v_cvt_pk_bf16_f32 v19, v28, v29
	v_cvt_pk_bf16_f32 v20, v30, v31
	v_cvt_pk_bf16_f32 v21, v32, v33
	ds_write2_b64 v0, v[2:3], v[4:5] offset0:88 offset1:90
	v_cvt_pk_bf16_f32 v2, v10, v11
	v_cvt_pk_bf16_f32 v3, v12, v13
	v_cvt_pk_bf16_f32 v4, v14, v15
	v_cvt_pk_bf16_f32 v5, v16, v17
	s_lshl_b64 s[14:15], s[14:15], 1
	ds_write2_b64 v0, v[50:51], v[52:53] offset0:68 offset1:70
	ds_write2_b64 v0, v[34:35], v[36:37] offset0:76 offset1:78
	ds_write2_b64 v0, v[18:19], v[20:21] offset0:84 offset1:86
	ds_write2_b64 v0, v[2:3], v[4:5] offset0:92 offset1:94
	s_waitcnt vmcnt(0) lgkmcnt(0)
	s_barrier
; #define GAS __attribute__((address_space(1)))
;     ...
;   __syncthreads();
;   int tid2 = tid; asm volatile("" : "+v"(tid2));
;   if (EPI == 0) {
; #pragma unroll
;     for (int i = 0; i < 16; ++i) {
;       const int id = tid2 + 256 * i, r = id >> 5, c8 = (id & 31) * 8;
;       const u32x4 v = *(const u32x4*)(smem + r * 528 + c8 * 2);
;       *(GAS u32x4*)(ea.out + (size_t)(m0 + r) * ea.ldo + n0 + c8) = v;
;     }
	s_add_u32 s14, s19, s14
	v_lshlrev_b32_e32 v0, 4, v189
	v_and_b32_e32 v0, 0x1f0, v0
	s_addc_u32 s15, s20, s15
	v_add_u32_e32 v10, 16, v0
	v_lshl_add_u64 v[12:13], s[14:15], 0, v[0:1]
	v_ashrrev_i32_e32 v0, 5, v189
	v_mad_u64_u32 v[2:3], s[14:15], v0, s55, v[10:11]
	ds_read_b128 v[2:5], v2
	v_add_u32_e32 v6, s12, v0
	v_ashrrev_i32_e32 v7, 31, v6
	v_add_u32_e32 v0, 0x100, v189
	v_lshlrev_b64 v[6:7], 11, v[6:7]
	v_ashrrev_i32_e32 v0, 5, v0
	v_lshl_add_u64 v[14:15], v[12:13], 0, v[6:7]
	v_mad_u64_u32 v[6:7], s[14:15], v0, s55, v[10:11]
	ds_read_b128 v[6:9], v6
	s_waitcnt lgkmcnt(1)
	global_store_dwordx4 v[14:15], v[2:5], off nt
	v_readlane_b32 s10, v252, 12
	s_add_i32 s23, s23, s10
	v_add_u32_e32 v2, s12, v0
	v_ashrrev_i32_e32 v3, 31, v2
	v_lshlrev_b64 v[2:3], 11, v[2:3]
	v_add_u32_e32 v0, 0x200, v189
	v_lshl_add_u64 v[2:3], v[12:13], 0, v[2:3]
	v_ashrrev_i32_e32 v0, 5, v0
	s_waitcnt lgkmcnt(0)
	global_store_dwordx4 v[2:3], v[6:9], off nt
	v_mad_u64_u32 v[2:3], s[14:15], v0, s55, v[10:11]
	ds_read_b128 v[2:5], v2
	v_add_u32_e32 v6, s12, v0
	v_ashrrev_i32_e32 v7, 31, v6
	v_add_u32_e32 v0, 0x300, v189
	v_lshlrev_b64 v[6:7], 11, v[6:7]
	v_ashrrev_i32_e32 v0, 5, v0
	v_lshl_add_u64 v[14:15], v[12:13], 0, v[6:7]
	v_mad_u64_u32 v[6:7], s[14:15], v0, s55, v[10:11]
	ds_read_b128 v[6:9], v6
	s_waitcnt lgkmcnt(1)
	global_store_dwordx4 v[14:15], v[2:5], off nt
	s_cmp_ge_i32 s23, s16
	s_nop 0
	v_add_u32_e32 v2, s12, v0
	v_ashrrev_i32_e32 v3, 31, v2
	v_lshlrev_b64 v[2:3], 11, v[2:3]
	v_add_u32_e32 v0, 0x400, v189
	v_lshl_add_u64 v[2:3], v[12:13], 0, v[2:3]
	v_ashrrev_i32_e32 v0, 5, v0
	s_waitcnt lgkmcnt(0)
	global_store_dwordx4 v[2:3], v[6:9], off nt
	v_mad_u64_u32 v[2:3], s[14:15], v0, s55, v[10:11]
	ds_read_b128 v[2:5], v2
	v_add_u32_e32 v6, s12, v0
	v_ashrrev_i32_e32 v7, 31, v6
	v_add_u32_e32 v0, 0x500, v189
	v_lshlrev_b64 v[6:7], 11, v[6:7]
	v_ashrrev_i32_e32 v0, 5, v0
	v_lshl_add_u64 v[14:15], v[12:13], 0, v[6:7]
	v_mad_u64_u32 v[6:7], s[14:15], v0, s55, v[10:11]
	ds_read_b128 v[6:9], v6
	s_waitcnt lgkmcnt(1)
	global_store_dwordx4 v[14:15], v[2:5], off nt
	s_nop 1
	v_add_u32_e32 v2, s12, v0
	v_ashrrev_i32_e32 v3, 31, v2
	v_lshlrev_b64 v[2:3], 11, v[2:3]
	v_add_u32_e32 v0, 0x600, v189
	v_lshl_add_u64 v[2:3], v[12:13], 0, v[2:3]
	v_ashrrev_i32_e32 v0, 5, v0
	s_waitcnt lgkmcnt(0)
	global_store_dwordx4 v[2:3], v[6:9], off nt
	v_mad_u64_u32 v[2:3], s[14:15], v0, s55, v[10:11]
	ds_read_b128 v[2:5], v2
	v_add_u32_e32 v6, s12, v0
	v_ashrrev_i32_e32 v7, 31, v6
	v_add_u32_e32 v0, 0x700, v189
	v_lshlrev_b64 v[6:7], 11, v[6:7]
	v_ashrrev_i32_e32 v0, 5, v0
	v_lshl_add_u64 v[14:15], v[12:13], 0, v[6:7]
	v_mad_u64_u32 v[6:7], s[14:15], v0, s55, v[10:11]
	ds_read_b128 v[6:9], v6
	s_waitcnt lgkmcnt(1)
	global_store_dwordx4 v[14:15], v[2:5], off nt
	s_nop 1
	v_add_u32_e32 v2, s12, v0
	v_ashrrev_i32_e32 v3, 31, v2
	v_lshlrev_b64 v[2:3], 11, v[2:3]
	v_add_u32_e32 v0, 0x800, v189
	v_lshl_add_u64 v[2:3], v[12:13], 0, v[2:3]
	v_ashrrev_i32_e32 v0, 5, v0
	s_waitcnt lgkmcnt(0)
	global_store_dwordx4 v[2:3], v[6:9], off nt
	v_mad_u64_u32 v[2:3], s[14:15], v0, s55, v[10:11]
	ds_read_b128 v[2:5], v2
	v_add_u32_e32 v6, s12, v0
	v_ashrrev_i32_e32 v7, 31, v6
	v_add_u32_e32 v0, 0x900, v189
	v_lshlrev_b64 v[6:7], 11, v[6:7]
	v_ashrrev_i32_e32 v0, 5, v0
	v_lshl_add_u64 v[14:15], v[12:13], 0, v[6:7]
	v_mad_u64_u32 v[6:7], s[14:15], v0, s55, v[10:11]
	ds_read_b128 v[6:9], v6
	s_waitcnt lgkmcnt(1)
	global_store_dwordx4 v[14:15], v[2:5], off nt
	s_nop 1
	v_add_u32_e32 v2, s12, v0
	v_ashrrev_i32_e32 v3, 31, v2
	v_lshlrev_b64 v[2:3], 11, v[2:3]
	v_add_u32_e32 v0, 0xa00, v189
	v_lshl_add_u64 v[2:3], v[12:13], 0, v[2:3]
	v_ashrrev_i32_e32 v0, 5, v0
	s_waitcnt lgkmcnt(0)
	global_store_dwordx4 v[2:3], v[6:9], off nt
	v_mad_u64_u32 v[2:3], s[14:15], v0, s55, v[10:11]
	ds_read_b128 v[2:5], v2
	v_add_u32_e32 v6, s12, v0
	v_ashrrev_i32_e32 v7, 31, v6
	v_add_u32_e32 v0, 0xb00, v189
	v_lshlrev_b64 v[6:7], 11, v[6:7]
	v_ashrrev_i32_e32 v0, 5, v0
	v_lshl_add_u64 v[14:15], v[12:13], 0, v[6:7]
	v_mad_u64_u32 v[6:7], s[14:15], v0, s55, v[10:11]
	ds_read_b128 v[6:9], v6
	s_waitcnt lgkmcnt(1)
	global_store_dwordx4 v[14:15], v[2:5], off nt
	s_nop 1
	v_add_u32_e32 v2, s12, v0
	v_ashrrev_i32_e32 v3, 31, v2
	v_lshlrev_b64 v[2:3], 11, v[2:3]
	v_add_u32_e32 v0, 0xc00, v189
	v_lshl_add_u64 v[2:3], v[12:13], 0, v[2:3]
	v_ashrrev_i32_e32 v0, 5, v0
	s_waitcnt lgkmcnt(0)
	global_store_dwordx4 v[2:3], v[6:9], off nt
	v_mad_u64_u32 v[2:3], s[14:15], v0, s55, v[10:11]
	ds_read_b128 v[2:5], v2
	v_add_u32_e32 v6, s12, v0
	v_ashrrev_i32_e32 v7, 31, v6
	v_add_u32_e32 v0, 0xd00, v189
	v_lshlrev_b64 v[6:7], 11, v[6:7]
	v_ashrrev_i32_e32 v0, 5, v0
	v_lshl_add_u64 v[14:15], v[12:13], 0, v[6:7]
	v_mad_u64_u32 v[6:7], s[14:15], v0, s55, v[10:11]
	ds_read_b128 v[6:9], v6
	s_waitcnt lgkmcnt(1)
	global_store_dwordx4 v[14:15], v[2:5], off nt
	s_nop 1
	v_add_u32_e32 v2, s12, v0
	v_ashrrev_i32_e32 v3, 31, v2
	v_lshlrev_b64 v[2:3], 11, v[2:3]
	v_add_u32_e32 v0, 0xe00, v189
	v_lshl_add_u64 v[2:3], v[12:13], 0, v[2:3]
	v_ashrrev_i32_e32 v0, 5, v0
	s_waitcnt lgkmcnt(0)
	global_store_dwordx4 v[2:3], v[6:9], off nt
	v_mad_u64_u32 v[2:3], s[14:15], v0, s55, v[10:11]
	ds_read_b128 v[2:5], v2
	v_add_u32_e32 v6, s12, v0
	v_ashrrev_i32_e32 v7, 31, v6
	v_add_u32_e32 v0, 0xf00, v189
	v_lshlrev_b64 v[6:7], 11, v[6:7]
	v_ashrrev_i32_e32 v0, 5, v0
	v_lshl_add_u64 v[14:15], v[12:13], 0, v[6:7]
	v_mad_u64_u32 v[6:7], s[14:15], v0, s55, v[10:11]
	ds_read_b128 v[6:9], v6
	s_waitcnt lgkmcnt(1)
	global_store_dwordx4 v[14:15], v[2:5], off nt
	s_nop 1
	v_add_u32_e32 v2, s12, v0
	v_ashrrev_i32_e32 v3, 31, v2
	v_lshlrev_b64 v[2:3], 11, v[2:3]
	v_lshl_add_u64 v[2:3], v[12:13], 0, v[2:3]
	s_waitcnt lgkmcnt(0)
	global_store_dwordx4 v[2:3], v[6:9], off nt
	s_barrier
	s_cbranch_scc0 .LBB0_20

; #define LAS __attribute__((address_space(3)))
;     ...
;   const int lane = tid & 63, wid = __builtin_amdgcn_readfirstlane(tid >> 6), wr = wid >> 1, wc = wid & 1;
;   const int m0 = mt * 128, n0 = nt * 256;
;   const int r = lane & 31, h = lane >> 5, key = (r >> 2) & 3;
;   constexpr int STG = 24576;
;   const int rowl = lane >> 2, cch = (lane & 3) ^ ((lane >> 4) & 3);
;   const unsigned voffA = (unsigned)(rowl * lda * 2 + cch * 16), voffB = (unsigned)(rowl * K * 2 + cch * 16);
;   const char* Abase = (const char*)(A + (size_t)m0 * lda) + (size_t)(wid * 2) * 32 * lda;
;   const char* Bbase = (const char*)(Bt + (size_t)n0 * K) + (size_t)(wid * 4) * 32 * K;
;   const size_t ablk = (size_t)32 * lda, bblk = (size_t)32 * K;
;   LAS char* lds = (LAS char*)smem;
;   LAS char* ldsA = lds + (wid * 2) * 1024;
;   LAS char* ldsB = lds + 8192 + (wid * 4) * 1024;
;     ...
;   const int x0 = ((0 + h) ^ key) * 16, x1 = ((2 + h) ^ key) * 16;
;   const int a_rd = (wr * 64 + r) * 64, b_rd = 8192 + (wc * 128 + r) * 64;
;   f32x16 acc[2][4];
; #pragma unroll
;   for (int i = 0; i < 2; ++i)
; #pragma unroll
;     for (int j = 0; j < 4; ++j)
; #pragma unroll
;       for (int e = 0; e < 16; ++e) acc[i][j][e] = 0.f;
;   const int nk = K >> 5;
;   DMA_STEP_(0, 0);
;   DMA_STEP_(1, STG);
;   asm volatile("s_waitcnt vmcnt(6)" ::: "memory");
;   __builtin_amdgcn_s_barrier();
;   asm volatile("" ::: "memory");
;   int s0 = 0, s2 = 2 * STG;
;   for (int kt = 0; kt < nk; ++kt) {
;     const int kn = (kt + 2 < nk) ? (kt + 2) : (nk - 1);
;     const LAS char* cur = lds + s0;
;     bf16x8 af[2][2], bfr[2][4];
; #pragma unroll
;     for (int kk = 0; kk < 2; ++kk) {
;       const int xo = kk ? x1 : x0;
;       af[kk][0] = *(const LAS bf16x8*)(cur + a_rd + xo);
;       bfr[kk][0] = *(const LAS bf16x8*)(cur + b_rd + xo);
.LBB0_183:
	s_mul_hi_i32 s10, s20, 0x38e38e39
	s_lshr_b32 s11, s10, 31
	s_ashr_i32 s10, s10, 4
	v_mov_b32_e32 v189, v188
	s_add_i32 s10, s10, s11
	v_readlane_b32 s12, v252, 18
	s_mul_i32 s11, s10, 0xffffffb8
	v_readfirstlane_b32 s21, v189
	s_lshl_b32 s10, s10, s12
	v_readlane_b32 s12, v252, 41
	s_ashr_i32 s44, s21, 6
	s_add_i32 s10, s10, s12
	s_lshl_b32 s12, s20, 7
	s_lshl_b32 s22, s44, 1
	s_add_i32 s11, s11, s20
	s_lshl_b32 s10, s10, 10
	s_and_b32 s12, s12, 0x380
	s_ashr_i32 s23, s22, 31
	s_or_b32 s12, s10, s12
	s_lshl_b32 s10, s11, 5
	s_lshl_b64 s[28:29], s[22:23], 10
	s_lshl_b32 s22, s44, 2
	s_ashr_i32 s11, s21, 1
	s_and_b32 s14, s10, 0xffffff00
	v_and_b32_e32 v0, 31, v189
	s_ashr_i32 s23, s22, 31
	s_lshl_b32 s10, s44, 12
	s_andn2_b32 s11, s11, 63
	v_lshlrev_b32_e32 v2, 4, v189
	s_ashr_i32 s13, s12, 31
	s_lshl_b64 s[40:41], s[22:23], 10
	s_add_i32 s22, s10, 16
	v_or_b32_e32 v197, s11, v0
	s_lshl_b32 s11, s44, 7
	v_bitop3_b32 v2, v2, 48, v189 bitop3:0x48
	v_lshlrev_b32_e32 v3, 9, v189
	s_ashr_i32 s15, s14, 31
	s_add_i32 s10, s22, 0x2000
	s_and_b32 s21, s11, 0x80
	s_movk_i32 s11, 0x7800
	s_lshl_b64 s[42:43], s[12:13], 6
	v_or_b32_e32 v4, s21, v0
	v_and_or_b32 v0, v3, s11, v2
	v_lshlrev_b32_e32 v10, 4, v189
	v_and_b32_e32 v10, 0x3c0, v10
	v_or_b32_e32 v10, v10, v2
	v_mov_b32_e32 v11, 0
	s_add_u32 s11, s18, s42
	s_addc_u32 s13, s19, s43
	s_add_u32 s28, s11, s28
	s_addc_u32 s29, s13, s29
	s_lshl_b64 s[42:43], s[14:15], 6
	v_readlane_b32 s46, v250, 18
	v_readlane_b32 s47, v250, 19
	s_add_u32 s11, s46, s42
	s_addc_u32 s13, s47, s43
	s_add_u32 s40, s11, s40
	s_addc_u32 s41, s13, s41
	s_lshl_b32 s11, s44, 11
	s_sub_i32 s13, s22, s11
	v_lshl_add_u64 v[192:193], s[28:29], 0, v[10:11]
	s_mov_b32 m0, s13
	s_nop 0
	global_load_lds_dwordx4 v[192:193], off
	global_load_lds_dwordx4 v[192:193], off offset:1024
	v_lshl_add_u64 v[194:195], s[40:41], 0, v[10:11]
	s_mov_b32 m0, s10
	s_nop 0
	global_load_lds_dwordx4 v[194:195], off
	global_load_lds_dwordx4 v[194:195], off offset:1024
	global_load_lds_dwordx4 v[194:195], off offset:2048
	global_load_lds_dwordx4 v[194:195], off offset:3072
	s_mov_b64 s[10:11], 0x10000
	s_mov_b64 s[10:11], 0x18000
	s_mov_b64 s[10:11], 0x8040
	s_add_i32 m0, s13, 0x6000
	s_mov_b32 vcc_lo, 0x480000
	s_mov_b32 vcc_hi, 0
	v_lshl_add_u64 v[2:3], v[192:193], 0, vcc
	global_load_lds_dwordx4 v[2:3], off
	global_load_lds_dwordx4 v[2:3], off offset:1024
	v_bfe_u32 v196, v189, 5, 1
	s_add_i32 m0, s22, 0x8000
	s_mov_b32 s100, 0x24000
	v_lshl_add_u64 v[2:3], v[194:195], 0, s[100:101]
	global_load_lds_dwordx4 v[2:3], off
	global_load_lds_dwordx4 v[2:3], off offset:1024
	global_load_lds_dwordx4 v[2:3], off offset:2048
	global_load_lds_dwordx4 v[2:3], off offset:3072
	s_mov_b64 s[10:11], 0x10040
	s_mov_b64 s[10:11], 0x18040
	v_lshlrev_b32_e32 v218, 6, v4
	v_bfe_u32 v4, v189, 2, 2
	v_lshrrev_b32_e32 v5, 5, v189
	s_lshl_b32 s100, s100, 1
	v_lshl_add_u64 v[194:195], v[194:195], 0, s[100:101]
	s_lshl_b32 vcc_lo, vcc_lo, 1
	v_lshl_add_u64 v[192:193], v[192:193], 0, vcc
	s_waitcnt vmcnt(6)
	s_barrier
	v_bitop3_b32 v2, v196, v4, 2 bitop3:0x36
	v_bitop3_b32 v0, v5, v4, 1 bitop3:0x6c
	v_lshlrev_b32_e32 v220, 4, v2
	v_mov_b32_e32 v2, 0
	v_lshlrev_b32_e32 v219, 6, v197
	v_lshlrev_b32_e32 v0, 4, v0
	s_mov_b32 s28, 0xc000
	s_mov_b32 s23, 0
	s_mov_b32 s29, 0
	v_mov_b32_e32 v3, v2
	v_mov_b32_e32 v4, v2
	v_mov_b32_e32 v5, v2
	v_mov_b32_e32 v6, v2
	v_mov_b32_e32 v7, v2
	v_mov_b32_e32 v8, v2
	v_mov_b32_e32 v9, v2
	v_mov_b32_e32 v10, v2
	v_mov_b32_e32 v11, v2
	v_mov_b32_e32 v12, v2
	v_mov_b32_e32 v13, v2
	v_mov_b32_e32 v14, v2
	v_mov_b32_e32 v15, v2
	v_mov_b32_e32 v16, v2
	v_mov_b32_e32 v17, v2
	v_mov_b32_e32 v18, v2
	v_mov_b32_e32 v19, v2
	v_mov_b32_e32 v20, v2
	v_mov_b32_e32 v21, v2
	v_mov_b32_e32 v22, v2
	v_mov_b32_e32 v23, v2
	v_mov_b32_e32 v24, v2
	v_mov_b32_e32 v25, v2
	v_mov_b32_e32 v26, v2
	v_mov_b32_e32 v27, v2
	v_mov_b32_e32 v28, v2
	v_mov_b32_e32 v29, v2
	v_mov_b32_e32 v30, v2
	v_mov_b32_e32 v31, v2
	v_mov_b32_e32 v32, v2
	v_mov_b32_e32 v33, v2
	v_mov_b32_e32 v50, v2
	v_mov_b32_e32 v51, v2
	v_mov_b32_e32 v52, v2
	v_mov_b32_e32 v53, v2
	v_mov_b32_e32 v54, v2
	v_mov_b32_e32 v55, v2
	v_mov_b32_e32 v56, v2
	v_mov_b32_e32 v57, v2
	v_mov_b32_e32 v58, v2
	v_mov_b32_e32 v59, v2
	v_mov_b32_e32 v60, v2
	v_mov_b32_e32 v61, v2
	v_mov_b32_e32 v62, v2
	v_mov_b32_e32 v63, v2
	v_mov_b32_e32 v64, v2
	v_mov_b32_e32 v65, v2
	v_mov_b32_e32 v82, v2
	v_mov_b32_e32 v83, v2
	v_mov_b32_e32 v84, v2
	v_mov_b32_e32 v85, v2
	v_mov_b32_e32 v86, v2
	v_mov_b32_e32 v87, v2
	v_mov_b32_e32 v88, v2
	v_mov_b32_e32 v89, v2
	v_mov_b32_e32 v90, v2
	v_mov_b32_e32 v91, v2
	v_mov_b32_e32 v92, v2
	v_mov_b32_e32 v93, v2
	v_mov_b32_e32 v94, v2
	v_mov_b32_e32 v95, v2
	v_mov_b32_e32 v96, v2
	v_mov_b32_e32 v97, v2
	v_mov_b32_e32 v34, v2
	v_mov_b32_e32 v35, v2
	v_mov_b32_e32 v36, v2
	v_mov_b32_e32 v37, v2
	v_mov_b32_e32 v38, v2
	v_mov_b32_e32 v39, v2
	v_mov_b32_e32 v40, v2
	v_mov_b32_e32 v41, v2
	v_mov_b32_e32 v42, v2
	v_mov_b32_e32 v43, v2
	v_mov_b32_e32 v44, v2
	v_mov_b32_e32 v45, v2
	v_mov_b32_e32 v46, v2
	v_mov_b32_e32 v47, v2
	v_mov_b32_e32 v48, v2
	v_mov_b32_e32 v49, v2
	v_mov_b32_e32 v66, v2
	v_mov_b32_e32 v67, v2
	v_mov_b32_e32 v68, v2
	v_mov_b32_e32 v69, v2
	v_mov_b32_e32 v70, v2
	v_mov_b32_e32 v71, v2
	v_mov_b32_e32 v72, v2
	v_mov_b32_e32 v73, v2
	v_mov_b32_e32 v74, v2
	v_mov_b32_e32 v75, v2
	v_mov_b32_e32 v76, v2
	v_mov_b32_e32 v77, v2
	v_mov_b32_e32 v78, v2
	v_mov_b32_e32 v79, v2
	v_mov_b32_e32 v80, v2
	v_mov_b32_e32 v81, v2
	v_mov_b32_e32 v98, v2
	v_mov_b32_e32 v99, v2
	v_mov_b32_e32 v100, v2
	v_mov_b32_e32 v101, v2
	v_mov_b32_e32 v102, v2
	v_mov_b32_e32 v103, v2
	v_mov_b32_e32 v104, v2
	v_mov_b32_e32 v105, v2
	v_mov_b32_e32 v106, v2
	v_mov_b32_e32 v107, v2
	v_mov_b32_e32 v108, v2
	v_mov_b32_e32 v109, v2
	v_mov_b32_e32 v110, v2
	v_mov_b32_e32 v111, v2
	v_mov_b32_e32 v112, v2
	v_mov_b32_e32 v113, v2
	v_mov_b32_e32 v114, v2
	v_mov_b32_e32 v115, v2
	v_mov_b32_e32 v116, v2
	v_mov_b32_e32 v117, v2
	v_mov_b32_e32 v118, v2
	v_mov_b32_e32 v119, v2
	v_mov_b32_e32 v120, v2
	v_mov_b32_e32 v121, v2
	v_mov_b32_e32 v122, v2
	v_mov_b32_e32 v123, v2
	v_mov_b32_e32 v124, v2
	v_mov_b32_e32 v125, v2
	v_mov_b32_e32 v126, v2
	v_mov_b32_e32 v127, v2
	v_mov_b32_e32 v128, v2
	v_mov_b32_e32 v129, v2
	s_mov_b32 vcc_hi, 0
	v_add_u32_e32 v226, v219, v0
	v_add_u32_e32 v227, v218, v0
	v_add_u32_e32 v228, v219, v220
	v_add_u32_e32 v229, v218, v220
	v_add_u32_e32 v158, 16, v226
	v_add_u32_e32 v170, 16, v227
	ds_read_b128 v[154:157], v158
	ds_read_b128 v[182:185], v170 offset:8192
	ds_read_b128 v[178:181], v170 offset:10240
	ds_read_b128 v[158:161], v158 offset:2048
	ds_read_b128 v[174:177], v170 offset:12288
	ds_read_b128 v[170:173], v170 offset:14336
	s_setprio 1
; #define LAS __attribute__((address_space(3)))
; DI f32x16 mfma32(bf16x8 a, bf16x8 b, f32x16 c) { return __builtin_amdgcn_mfma_f32_32x32x16_bf16(a, b, c, 0, 0, 0); }
;     ...
;   for (int kt = 0; kt < nk; ++kt) {
;     const int kn = (kt + 2 < nk) ? (kt + 2) : (nk - 1);
;     const LAS char* cur = lds + s0;
;     bf16x8 af[2][2], bfr[2][4];
; #pragma unroll
;     for (int kk = 0; kk < 2; ++kk) {
;       const int xo = kk ? x1 : x0;
;       af[kk][0] = *(const LAS bf16x8*)(cur + a_rd + xo);
;       bfr[kk][0] = *(const LAS bf16x8*)(cur + b_rd + xo);
;       bfr[kk][1] = *(const LAS bf16x8*)(cur + b_rd + 2048 + xo);
;       af[kk][1] = *(const LAS bf16x8*)(cur + a_rd + 2048 + xo);
;       bfr[kk][2] = *(const LAS bf16x8*)(cur + b_rd + 4096 + xo);
;       bfr[kk][3] = *(const LAS bf16x8*)(cur + b_rd + 6144 + xo);
;     }
;     DMA_STEP_(kn, s2);
; #pragma unroll
;     for (int kk = 0; kk < 2; ++kk) {
;       acc[0][0] = mfma32(bfr[kk][0], af[kk][0], acc[0][0]); acc[0][1] = mfma32(bfr[kk][1], af[kk][0], acc[0][1]);
;       acc[1][0] = mfma32(bfr[kk][0], af[kk][1], acc[1][0]); acc[1][1] = mfma32(bfr[kk][1], af[kk][1], acc[1][1]);
;       acc[0][2] = mfma32(bfr[kk][2], af[kk][0], acc[0][2]); acc[0][3] = mfma32(bfr[kk][3], af[kk][0], acc[0][3]);
;       acc[1][2] = mfma32(bfr[kk][2], af[kk][1], acc[1][2]); acc[1][3] = mfma32(bfr[kk][3], af[kk][1], acc[1][3]);
;     }
;     __builtin_amdgcn_sched_group_barrier(0x100, 12, 0);
;     __builtin_amdgcn_sched_group_barrier(0x010, 6, 0);
;     __builtin_amdgcn_sched_group_barrier(0x008, 16, 0);
;     asm volatile("s_waitcnt vmcnt(6) lgkmcnt(0)" ::: "memory");
;     __builtin_amdgcn_s_barrier();
;     asm volatile("" ::: "memory");
;     s0 = (s0 == 2 * STG) ? 0 : s0 + STG;
;     s2 = (s2 == 2 * STG) ? 0 : s2 + STG;
;   }
.LBB0_184:
	s_add_i32 s11, s29, 16
	s_mov_b32 s10, s23
	v_add_u32_e32 v142, s11, v228
	v_add_u32_e32 v150, s11, v229
	s_min_u32 s10, s10, 29
	s_lshl_b32 s70, s10, 6
	ds_read_b128 v[138:141], v142
	ds_read_b128 v[162:165], v150 offset:8192
	ds_read_b128 v[166:169], v150 offset:10240
	ds_read_b128 v[142:145], v142 offset:2048
	ds_read_b128 v[146:149], v150 offset:12288
	ds_read_b128 v[150:153], v150 offset:14336
	s_mul_i32 vcc_lo, s70, 0x12000
	s_add_i32 s10, s13, s28
	v_lshl_add_u64 v[222:223], v[192:193], 0, vcc
	s_mov_b32 m0, s10
	s_mul_i32 s100, s70, 0x900
	v_lshl_add_u64 v[224:225], v[194:195], 0, s[100:101]
	s_add_i32 s10, s22, s28
	s_waitcnt lgkmcnt(6)
	v_mfma_f32_32x32x16_bf16 v[114:129], v[182:185], v[154:157], v[114:129]
	global_load_lds_dwordx4 v[222:223], off
	v_mfma_f32_32x32x16_bf16 v[98:113], v[178:181], v[154:157], v[98:113]
	global_load_lds_dwordx4 v[222:223], off offset:1024
	s_add_i32 m0, s10, 0x2000
	v_mfma_f32_32x32x16_bf16 v[66:81], v[182:185], v[158:161], v[66:81]
	global_load_lds_dwordx4 v[224:225], off
	v_mfma_f32_32x32x16_bf16 v[34:49], v[178:181], v[158:161], v[34:49]
	global_load_lds_dwordx4 v[224:225], off offset:1024
	v_mfma_f32_32x32x16_bf16 v[82:97], v[174:177], v[154:157], v[82:97]
	global_load_lds_dwordx4 v[224:225], off offset:2048
	v_mfma_f32_32x32x16_bf16 v[50:65], v[170:173], v[154:157], v[50:65]
	global_load_lds_dwordx4 v[224:225], off offset:3072
	v_mfma_f32_32x32x16_bf16 v[18:33], v[174:177], v[158:161], v[18:33]
	s_add_i32 s10, s29, 0x6000
	s_cmpk_lg_u32 s29, 0xc000
	s_cselect_b32 s29, s10, 0
	s_add_i32 s10, s28, 0x6000
	s_cmpk_lg_u32 s28, 0xc000
	s_cselect_b32 s28, s10, 0
	v_mfma_f32_32x32x16_bf16 v[2:17], v[170:173], v[158:161], v[2:17]
	s_add_i32 s11, s29, 16
	s_waitcnt vmcnt(6) lgkmcnt(0)
	s_barrier
	v_add_u32_e32 v158, s11, v226
	v_add_u32_e32 v170, s11, v227
	ds_read_b128 v[154:157], v158
	ds_read_b128 v[182:185], v170 offset:8192
	ds_read_b128 v[178:181], v170 offset:10240
	ds_read_b128 v[158:161], v158 offset:2048
	ds_read_b128 v[174:177], v170 offset:12288
	ds_read_b128 v[170:173], v170 offset:14336
	v_mfma_f32_32x32x16_bf16 v[114:129], v[162:165], v[138:141], v[114:129]
	v_mfma_f32_32x32x16_bf16 v[98:113], v[166:169], v[138:141], v[98:113]
	v_mfma_f32_32x32x16_bf16 v[66:81], v[162:165], v[142:145], v[66:81]
	v_mfma_f32_32x32x16_bf16 v[34:49], v[166:169], v[142:145], v[34:49]
	v_mfma_f32_32x32x16_bf16 v[82:97], v[146:149], v[138:141], v[82:97]
	v_mfma_f32_32x32x16_bf16 v[50:65], v[150:153], v[138:141], v[50:65]
	v_mfma_f32_32x32x16_bf16 v[18:33], v[146:149], v[142:145], v[18:33]
	v_mfma_f32_32x32x16_bf16 v[2:17], v[150:153], v[142:145], v[2:17]
	s_add_i32 s11, s29, 16
	s_add_i32 s10, s23, 1
	v_add_u32_e32 v142, s11, v228
	v_add_u32_e32 v150, s11, v229
	s_min_u32 s10, s10, 29
	s_lshl_b32 s70, s10, 6
	ds_read_b128 v[138:141], v142
	ds_read_b128 v[162:165], v150 offset:8192
	ds_read_b128 v[166:169], v150 offset:10240
	ds_read_b128 v[142:145], v142 offset:2048
	ds_read_b128 v[146:149], v150 offset:12288
	ds_read_b128 v[150:153], v150 offset:14336
	s_mul_i32 vcc_lo, s70, 0x12000
	s_add_i32 s10, s13, s28
	v_lshl_add_u64 v[222:223], v[192:193], 0, vcc
	s_mov_b32 m0, s10
	s_mul_i32 s100, s70, 0x900
	v_lshl_add_u64 v[224:225], v[194:195], 0, s[100:101]
	s_add_i32 s10, s22, s28
	s_waitcnt lgkmcnt(6)
	v_mfma_f32_32x32x16_bf16 v[114:129], v[182:185], v[154:157], v[114:129]
	global_load_lds_dwordx4 v[222:223], off
	v_mfma_f32_32x32x16_bf16 v[98:113], v[178:181], v[154:157], v[98:113]
	global_load_lds_dwordx4 v[222:223], off offset:1024
	s_add_i32 m0, s10, 0x2000
	v_mfma_f32_32x32x16_bf16 v[66:81], v[182:185], v[158:161], v[66:81]
	global_load_lds_dwordx4 v[224:225], off
	v_mfma_f32_32x32x16_bf16 v[34:49], v[178:181], v[158:161], v[34:49]
	global_load_lds_dwordx4 v[224:225], off offset:1024
	v_mfma_f32_32x32x16_bf16 v[82:97], v[174:177], v[154:157], v[82:97]
	global_load_lds_dwordx4 v[224:225], off offset:2048
	v_mfma_f32_32x32x16_bf16 v[50:65], v[170:173], v[154:157], v[50:65]
	global_load_lds_dwordx4 v[224:225], off offset:3072
	v_mfma_f32_32x32x16_bf16 v[18:33], v[174:177], v[158:161], v[18:33]
	s_add_i32 s10, s29, 0x6000
	s_cmpk_lg_u32 s29, 0xc000
	s_cselect_b32 s29, s10, 0
	s_add_i32 s10, s28, 0x6000
	s_cmpk_lg_u32 s28, 0xc000
	s_cselect_b32 s28, s10, 0
	v_mfma_f32_32x32x16_bf16 v[2:17], v[170:173], v[158:161], v[2:17]
	s_add_i32 s11, s29, 16
	s_waitcnt vmcnt(6) lgkmcnt(0)
	s_barrier
	v_add_u32_e32 v158, s11, v226
	v_add_u32_e32 v170, s11, v227
	ds_read_b128 v[154:157], v158
	ds_read_b128 v[182:185], v170 offset:8192
	ds_read_b128 v[178:181], v170 offset:10240
	ds_read_b128 v[158:161], v158 offset:2048
	ds_read_b128 v[174:177], v170 offset:12288
	ds_read_b128 v[170:173], v170 offset:14336
	v_mfma_f32_32x32x16_bf16 v[114:129], v[162:165], v[138:141], v[114:129]
	v_mfma_f32_32x32x16_bf16 v[98:113], v[166:169], v[138:141], v[98:113]
	v_mfma_f32_32x32x16_bf16 v[66:81], v[162:165], v[142:145], v[66:81]
	v_mfma_f32_32x32x16_bf16 v[34:49], v[166:169], v[142:145], v[34:49]
	v_mfma_f32_32x32x16_bf16 v[82:97], v[146:149], v[138:141], v[82:97]
	v_mfma_f32_32x32x16_bf16 v[50:65], v[150:153], v[138:141], v[50:65]
	v_mfma_f32_32x32x16_bf16 v[18:33], v[146:149], v[142:145], v[18:33]
	v_mfma_f32_32x32x16_bf16 v[2:17], v[150:153], v[142:145], v[2:17]
	s_add_i32 s23, s23, 2
	s_cmp_lg_u32 s23, 30
	s_cbranch_scc1 .LBB0_184
; #define LAS __attribute__((address_space(3)))
; DI unsigned pk2(float a, float b) { f32x2 v = {a, b}; bf2_t r = __builtin_convertvector(v, bf2_t); return __builtin_bit_cast(unsigned, r); }
;     ...
;   for (int kt = 0; kt < nk; ++kt) {
;     const int kn = (kt + 2 < nk) ? (kt + 2) : (nk - 1);
;     const LAS char* cur = lds + s0;
;     bf16x8 af[2][2], bfr[2][4];
; #pragma unroll
;     for (int kk = 0; kk < 2; ++kk) {
;       const int xo = kk ? x1 : x0;
;       af[kk][0] = *(const LAS bf16x8*)(cur + a_rd + xo);
;       bfr[kk][0] = *(const LAS bf16x8*)(cur + b_rd + xo);
;       bfr[kk][1] = *(const LAS bf16x8*)(cur + b_rd + 2048 + xo);
;       af[kk][1] = *(const LAS bf16x8*)(cur + a_rd + 2048 + xo);
;       bfr[kk][2] = *(const LAS bf16x8*)(cur + b_rd + 4096 + xo);
;       bfr[kk][3] = *(const LAS bf16x8*)(cur + b_rd + 6144 + xo);
;     }
;     DMA_STEP_(kn, s2);
; #pragma unroll
;     for (int kk = 0; kk < 2; ++kk) {
;       acc[0][0] = mfma32(bfr[kk][0], af[kk][0], acc[0][0]); acc[0][1] = mfma32(bfr[kk][1], af[kk][0], acc[0][1]);
;       acc[1][0] = mfma32(bfr[kk][0], af[kk][1], acc[1][0]); acc[1][1] = mfma32(bfr[kk][1], af[kk][1], acc[1][1]);
;       acc[0][2] = mfma32(bfr[kk][2], af[kk][0], acc[0][2]); acc[0][3] = mfma32(bfr[kk][3], af[kk][0], acc[0][3]);
;       acc[1][2] = mfma32(bfr[kk][2], af[kk][1], acc[1][2]); acc[1][3] = mfma32(bfr[kk][3], af[kk][1], acc[1][3]);
;     }
;     __builtin_amdgcn_sched_group_barrier(0x100, 12, 0);
;     __builtin_amdgcn_sched_group_barrier(0x010, 6, 0);
;     __builtin_amdgcn_sched_group_barrier(0x008, 16, 0);
;     asm volatile("s_waitcnt vmcnt(6) lgkmcnt(0)" ::: "memory");
;     __builtin_amdgcn_s_barrier();
;     asm volatile("" ::: "memory");
;     s0 = (s0 == 2 * STG) ? 0 : s0 + STG;
;     s2 = (s2 == 2 * STG) ? 0 : s2 + STG;
;   }
;   asm volatile("s_waitcnt vmcnt(0)" ::: "memory");
;   __builtin_amdgcn_s_barrier();
;   asm volatile("" ::: "memory");
;     ...
;   {
;     const int h = lane >> 5, cl = lane & 31;
; #pragma unroll
;     for (int i = 0; i < 2; ++i)
; #pragma unroll
;       for (int j = 0; j < 4; ++j)
; #pragma unroll
;         for (int g = 0; g < 4; ++g) {
;           u32x2 w; w.x = pk2(acc[i][j][4 * g], acc[i][j][4 * g + 1]); w.y = pk2(acc[i][j][4 * g + 2], acc[i][j][4 * g + 3]);
;           *(u32x2*)(smem + (wr * 64 + i * 32 + cl) * 528 + (wc * 128 + j * 32 + 8 * g + 4 * h) * 2) = w;
;         }
	s_add_i32 s11, s29, 16
	v_add_u32_e32 v142, s11, v228
	v_add_u32_e32 v150, s11, v229
	ds_read_b128 v[138:141], v142
	ds_read_b128 v[162:165], v150 offset:8192
	ds_read_b128 v[166:169], v150 offset:10240
	ds_read_b128 v[142:145], v142 offset:2048
	ds_read_b128 v[146:149], v150 offset:12288
	ds_read_b128 v[150:153], v150 offset:14336
	s_waitcnt lgkmcnt(6)
	v_mfma_f32_32x32x16_bf16 v[114:129], v[182:185], v[154:157], v[114:129]
	v_mfma_f32_32x32x16_bf16 v[98:113], v[178:181], v[154:157], v[98:113]
	v_mfma_f32_32x32x16_bf16 v[66:81], v[182:185], v[158:161], v[66:81]
	v_mfma_f32_32x32x16_bf16 v[34:49], v[178:181], v[158:161], v[34:49]
	v_mfma_f32_32x32x16_bf16 v[82:97], v[174:177], v[154:157], v[82:97]
	v_mfma_f32_32x32x16_bf16 v[50:65], v[170:173], v[154:157], v[50:65]
	v_mfma_f32_32x32x16_bf16 v[18:33], v[174:177], v[158:161], v[18:33]
	s_add_i32 s10, s29, 0x6000
	s_cmpk_lg_u32 s29, 0xc000
	s_cselect_b32 s29, s10, 0
	v_mfma_f32_32x32x16_bf16 v[2:17], v[170:173], v[158:161], v[2:17]
	s_add_i32 s11, s29, 16
	s_waitcnt vmcnt(0) lgkmcnt(0)
	s_barrier
	v_add_u32_e32 v158, s11, v226
	v_add_u32_e32 v170, s11, v227
	ds_read_b128 v[154:157], v158
	ds_read_b128 v[182:185], v170 offset:8192
	ds_read_b128 v[178:181], v170 offset:10240
	ds_read_b128 v[158:161], v158 offset:2048
	ds_read_b128 v[174:177], v170 offset:12288
	ds_read_b128 v[170:173], v170 offset:14336
	v_mfma_f32_32x32x16_bf16 v[114:129], v[162:165], v[138:141], v[114:129]
	v_mfma_f32_32x32x16_bf16 v[98:113], v[166:169], v[138:141], v[98:113]
	v_mfma_f32_32x32x16_bf16 v[66:81], v[162:165], v[142:145], v[66:81]
	v_mfma_f32_32x32x16_bf16 v[34:49], v[166:169], v[142:145], v[34:49]
	v_mfma_f32_32x32x16_bf16 v[82:97], v[146:149], v[138:141], v[82:97]
	v_mfma_f32_32x32x16_bf16 v[50:65], v[150:153], v[138:141], v[50:65]
	v_mfma_f32_32x32x16_bf16 v[18:33], v[146:149], v[142:145], v[18:33]
	v_mfma_f32_32x32x16_bf16 v[2:17], v[150:153], v[142:145], v[2:17]
	s_add_i32 s11, s29, 16
	v_add_u32_e32 v142, s11, v228
	v_add_u32_e32 v150, s11, v229
	ds_read_b128 v[138:141], v142
	ds_read_b128 v[162:165], v150 offset:8192
	ds_read_b128 v[166:169], v150 offset:10240
	ds_read_b128 v[142:145], v142 offset:2048
	ds_read_b128 v[146:149], v150 offset:12288
	ds_read_b128 v[150:153], v150 offset:14336
	s_waitcnt lgkmcnt(6)
	v_mfma_f32_32x32x16_bf16 v[114:129], v[182:185], v[154:157], v[114:129]
	v_mfma_f32_32x32x16_bf16 v[98:113], v[178:181], v[154:157], v[98:113]
	v_mfma_f32_32x32x16_bf16 v[66:81], v[182:185], v[158:161], v[66:81]
	v_mfma_f32_32x32x16_bf16 v[34:49], v[178:181], v[158:161], v[34:49]
	v_mfma_f32_32x32x16_bf16 v[82:97], v[174:177], v[154:157], v[82:97]
	v_mfma_f32_32x32x16_bf16 v[50:65], v[170:173], v[154:157], v[50:65]
	v_mfma_f32_32x32x16_bf16 v[18:33], v[174:177], v[158:161], v[18:33]
	v_mfma_f32_32x32x16_bf16 v[2:17], v[170:173], v[158:161], v[2:17]
	s_waitcnt lgkmcnt(0)
	v_mfma_f32_32x32x16_bf16 v[114:129], v[162:165], v[138:141], v[114:129]
	v_mfma_f32_32x32x16_bf16 v[98:113], v[166:169], v[138:141], v[98:113]
	v_mfma_f32_32x32x16_bf16 v[66:81], v[162:165], v[142:145], v[66:81]
	v_mfma_f32_32x32x16_bf16 v[34:49], v[166:169], v[142:145], v[34:49]
	v_mfma_f32_32x32x16_bf16 v[82:97], v[146:149], v[138:141], v[82:97]
	v_mfma_f32_32x32x16_bf16 v[50:65], v[150:153], v[138:141], v[50:65]
	v_mfma_f32_32x32x16_bf16 v[18:33], v[146:149], v[142:145], v[18:33]
	v_mfma_f32_32x32x16_bf16 v[2:17], v[150:153], v[142:145], v[2:17]
	s_waitcnt lgkmcnt(0)
	s_setprio 0
	v_mul_lo_u32 v0, v197, s55
	v_add_u32_e32 v0, 16, v0
	s_nop 1
	v_cvt_pk_bf16_f32 v114, v114, v115
	v_cvt_pk_bf16_f32 v115, v116, v117
	v_lshlrev_b32_e32 v116, 3, v196
	s_lshl_b32 s10, s21, 1
	v_add3_u32 v0, v0, v116, s10
	v_cvt_pk_bf16_f32 v116, v118, v119
	v_cvt_pk_bf16_f32 v117, v120, v121
	v_cvt_pk_bf16_f32 v98, v98, v99
	v_cvt_pk_bf16_f32 v99, v100, v101
	v_cvt_pk_bf16_f32 v100, v102, v103
	v_cvt_pk_bf16_f32 v101, v104, v105
	v_cvt_pk_bf16_f32 v82, v82, v83
	v_cvt_pk_bf16_f32 v83, v84, v85
	v_cvt_pk_bf16_f32 v84, v86, v87
	v_cvt_pk_bf16_f32 v85, v88, v89
	v_cvt_pk_bf16_f32 v50, v50, v51
	v_cvt_pk_bf16_f32 v51, v52, v53
	v_cvt_pk_bf16_f32 v52, v54, v55
	v_cvt_pk_bf16_f32 v53, v56, v57
	s_waitcnt vmcnt(0)
	s_barrier
	ds_write2_b64 v0, v[114:115], v[116:117] offset1:2
	v_cvt_pk_bf16_f32 v114, v122, v123
	v_cvt_pk_bf16_f32 v115, v124, v125
	v_cvt_pk_bf16_f32 v116, v126, v127
	v_cvt_pk_bf16_f32 v117, v128, v129
	ds_write2_b64 v0, v[98:99], v[100:101] offset0:8 offset1:10
	v_cvt_pk_bf16_f32 v98, v106, v107
	v_cvt_pk_bf16_f32 v99, v108, v109
	v_cvt_pk_bf16_f32 v100, v110, v111
	v_cvt_pk_bf16_f32 v101, v112, v113
	ds_write2_b64 v0, v[82:83], v[84:85] offset0:16 offset1:18
	v_cvt_pk_bf16_f32 v82, v90, v91
	v_cvt_pk_bf16_f32 v83, v92, v93
	v_cvt_pk_bf16_f32 v84, v94, v95
	v_cvt_pk_bf16_f32 v85, v96, v97
	ds_write2_b64 v0, v[50:51], v[52:53] offset0:24 offset1:26
	v_cvt_pk_bf16_f32 v50, v58, v59
	v_cvt_pk_bf16_f32 v51, v60, v61
	v_cvt_pk_bf16_f32 v52, v62, v63
	v_cvt_pk_bf16_f32 v53, v64, v65
	ds_write2_b64 v0, v[114:115], v[116:117] offset0:4 offset1:6
	ds_write2_b64 v0, v[98:99], v[100:101] offset0:12 offset1:14
	ds_write2_b64 v0, v[82:83], v[84:85] offset0:20 offset1:22
	ds_write2_b64 v0, v[50:51], v[52:53] offset0:28 offset1:30
	v_cvt_pk_bf16_f32 v50, v66, v67
	v_cvt_pk_bf16_f32 v51, v68, v69
	v_cvt_pk_bf16_f32 v52, v70, v71
	v_cvt_pk_bf16_f32 v53, v72, v73
	v_add_u32_e32 v0, 0x4000, v0
	v_cvt_pk_bf16_f32 v34, v34, v35
	v_cvt_pk_bf16_f32 v35, v36, v37
	v_cvt_pk_bf16_f32 v36, v38, v39
	v_cvt_pk_bf16_f32 v37, v40, v41
	v_cvt_pk_bf16_f32 v18, v18, v19
	v_cvt_pk_bf16_f32 v19, v20, v21
	v_cvt_pk_bf16_f32 v20, v22, v23
	v_cvt_pk_bf16_f32 v21, v24, v25
	v_cvt_pk_bf16_f32 v2, v2, v3
	v_cvt_pk_bf16_f32 v3, v4, v5
	v_cvt_pk_bf16_f32 v4, v6, v7
	v_cvt_pk_bf16_f32 v5, v8, v9
	ds_write2_b64 v0, v[50:51], v[52:53] offset0:64 offset1:66
	v_cvt_pk_bf16_f32 v50, v74, v75
	v_cvt_pk_bf16_f32 v51, v76, v77
	v_cvt_pk_bf16_f32 v52, v78, v79
	v_cvt_pk_bf16_f32 v53, v80, v81
	ds_write2_b64 v0, v[34:35], v[36:37] offset0:72 offset1:74
	v_cvt_pk_bf16_f32 v34, v42, v43
	v_cvt_pk_bf16_f32 v35, v44, v45
	v_cvt_pk_bf16_f32 v36, v46, v47
	v_cvt_pk_bf16_f32 v37, v48, v49
	ds_write2_b64 v0, v[18:19], v[20:21] offset0:80 offset1:82
	v_cvt_pk_bf16_f32 v18, v26, v27
	v_cvt_pk_bf16_f32 v19, v28, v29
	v_cvt_pk_bf16_f32 v20, v30, v31
	v_cvt_pk_bf16_f32 v21, v32, v33
	ds_write2_b64 v0, v[2:3], v[4:5] offset0:88 offset1:90
	v_cvt_pk_bf16_f32 v2, v10, v11
	v_cvt_pk_bf16_f32 v3, v12, v13
	v_cvt_pk_bf16_f32 v4, v14, v15
	v_cvt_pk_bf16_f32 v5, v16, v17
	s_lshl_b64 s[14:15], s[14:15], 1
	ds_write2_b64 v0, v[50:51], v[52:53] offset0:68 offset1:70
	ds_write2_b64 v0, v[34:35], v[36:37] offset0:76 offset1:78
	ds_write2_b64 v0, v[18:19], v[20:21] offset0:84 offset1:86
	ds_write2_b64 v0, v[2:3], v[4:5] offset0:92 offset1:94
	s_waitcnt vmcnt(0) lgkmcnt(0)
	s_barrier
; #define GAS __attribute__((address_space(1)))
;     ...
;   __syncthreads();
;   int tid2 = tid; asm volatile("" : "+v"(tid2));
;   if (EPI == 0) {
; #pragma unroll
;     for (int i = 0; i < 16; ++i) {
;       const int id = tid2 + 256 * i, r = id >> 5, c8 = (id & 31) * 8;
;       const u32x4 v = *(const u32x4*)(smem + r * 528 + c8 * 2);
;       *(GAS u32x4*)(ea.out + (size_t)(m0 + r) * ea.ldo + n0 + c8) = v;
;     }
;   } else {
	s_add_u32 s14, s16, s14
	v_lshlrev_b32_e32 v0, 4, v189
	v_and_b32_e32 v0, 0x1f0, v0
	s_addc_u32 s15, s17, s15
	v_add_u32_e32 v10, 16, v0
	v_lshl_add_u64 v[12:13], s[14:15], 0, v[0:1]
	v_ashrrev_i32_e32 v0, 5, v189
	v_mad_u64_u32 v[2:3], s[14:15], v0, s55, v[10:11]
	v_add_u32_e32 v0, s12, v0
	v_mad_i64_i32 v[14:15], s[14:15], v0, s35, v[12:13]
	v_add_u32_e32 v0, 0x100, v189
	ds_read_b128 v[2:5], v2
	v_ashrrev_i32_e32 v0, 5, v0
	v_mad_u64_u32 v[6:7], s[14:15], v0, s55, v[10:11]
	ds_read_b128 v[6:9], v6
	v_add_u32_e32 v0, s12, v0
	s_waitcnt lgkmcnt(1)
	global_store_dwordx4 v[14:15], v[2:5], off nt
	v_readlane_b32 s10, v252, 12
	s_add_i32 s20, s20, s10
	v_mad_i64_i32 v[2:3], s[14:15], v0, s35, v[12:13]
	v_add_u32_e32 v0, 0x200, v189
	v_ashrrev_i32_e32 v0, 5, v0
	s_waitcnt lgkmcnt(0)
	global_store_dwordx4 v[2:3], v[6:9], off nt
	v_mad_u64_u32 v[2:3], s[14:15], v0, s55, v[10:11]
	v_add_u32_e32 v0, s12, v0
	v_mad_i64_i32 v[14:15], s[14:15], v0, s35, v[12:13]
	v_add_u32_e32 v0, 0x300, v189
	ds_read_b128 v[2:5], v2
	v_ashrrev_i32_e32 v0, 5, v0
	v_mad_u64_u32 v[6:7], s[14:15], v0, s55, v[10:11]
	ds_read_b128 v[6:9], v6
	v_add_u32_e32 v0, s12, v0
	s_waitcnt lgkmcnt(1)
	global_store_dwordx4 v[14:15], v[2:5], off nt
	s_cmp_ge_i32 s20, s45
	s_nop 0
	v_mad_i64_i32 v[2:3], s[14:15], v0, s35, v[12:13]
	v_add_u32_e32 v0, 0x400, v189
	v_ashrrev_i32_e32 v0, 5, v0
	s_waitcnt lgkmcnt(0)
	global_store_dwordx4 v[2:3], v[6:9], off nt
	v_mad_u64_u32 v[2:3], s[14:15], v0, s55, v[10:11]
	v_add_u32_e32 v0, s12, v0
	v_mad_i64_i32 v[14:15], s[14:15], v0, s35, v[12:13]
	v_add_u32_e32 v0, 0x500, v189
	ds_read_b128 v[2:5], v2
	v_ashrrev_i32_e32 v0, 5, v0
	v_mad_u64_u32 v[6:7], s[14:15], v0, s55, v[10:11]
	ds_read_b128 v[6:9], v6
	v_add_u32_e32 v0, s12, v0
	s_waitcnt lgkmcnt(1)
	global_store_dwordx4 v[14:15], v[2:5], off nt
	s_nop 1
	v_mad_i64_i32 v[2:3], s[14:15], v0, s35, v[12:13]
	v_add_u32_e32 v0, 0x600, v189
	v_ashrrev_i32_e32 v0, 5, v0
	s_waitcnt lgkmcnt(0)
	global_store_dwordx4 v[2:3], v[6:9], off nt
	v_mad_u64_u32 v[2:3], s[14:15], v0, s55, v[10:11]
	v_add_u32_e32 v0, s12, v0
	v_mad_i64_i32 v[14:15], s[14:15], v0, s35, v[12:13]
	v_add_u32_e32 v0, 0x700, v189
	ds_read_b128 v[2:5], v2
	v_ashrrev_i32_e32 v0, 5, v0
	v_mad_u64_u32 v[6:7], s[14:15], v0, s55, v[10:11]
	ds_read_b128 v[6:9], v6
	v_add_u32_e32 v0, s12, v0
	s_waitcnt lgkmcnt(1)
	global_store_dwordx4 v[14:15], v[2:5], off nt
	s_nop 1
	v_mad_i64_i32 v[2:3], s[14:15], v0, s35, v[12:13]
	v_add_u32_e32 v0, 0x800, v189
	v_ashrrev_i32_e32 v0, 5, v0
	s_waitcnt lgkmcnt(0)
	global_store_dwordx4 v[2:3], v[6:9], off nt
	v_mad_u64_u32 v[2:3], s[14:15], v0, s55, v[10:11]
	v_add_u32_e32 v0, s12, v0
	v_mad_i64_i32 v[14:15], s[14:15], v0, s35, v[12:13]
	v_add_u32_e32 v0, 0x900, v189
	ds_read_b128 v[2:5], v2
	v_ashrrev_i32_e32 v0, 5, v0
	v_mad_u64_u32 v[6:7], s[14:15], v0, s55, v[10:11]
	ds_read_b128 v[6:9], v6
	v_add_u32_e32 v0, s12, v0
	s_waitcnt lgkmcnt(1)
	global_store_dwordx4 v[14:15], v[2:5], off nt
	s_nop 1
	v_mad_i64_i32 v[2:3], s[14:15], v0, s35, v[12:13]
	v_add_u32_e32 v0, 0xa00, v189
	v_ashrrev_i32_e32 v0, 5, v0
	s_waitcnt lgkmcnt(0)
	global_store_dwordx4 v[2:3], v[6:9], off nt
	v_mad_u64_u32 v[2:3], s[14:15], v0, s55, v[10:11]
	v_add_u32_e32 v0, s12, v0
	v_mad_i64_i32 v[14:15], s[14:15], v0, s35, v[12:13]
	v_add_u32_e32 v0, 0xb00, v189
	ds_read_b128 v[2:5], v2
	v_ashrrev_i32_e32 v0, 5, v0
	v_mad_u64_u32 v[6:7], s[14:15], v0, s55, v[10:11]
	ds_read_b128 v[6:9], v6
	v_add_u32_e32 v0, s12, v0
	s_waitcnt lgkmcnt(1)
	global_store_dwordx4 v[14:15], v[2:5], off nt
	s_nop 1
	v_mad_i64_i32 v[2:3], s[14:15], v0, s35, v[12:13]
	v_add_u32_e32 v0, 0xc00, v189
	v_ashrrev_i32_e32 v0, 5, v0
	s_waitcnt lgkmcnt(0)
	global_store_dwordx4 v[2:3], v[6:9], off nt
	v_mad_u64_u32 v[2:3], s[14:15], v0, s55, v[10:11]
	v_add_u32_e32 v0, s12, v0
	v_mad_i64_i32 v[14:15], s[14:15], v0, s35, v[12:13]
	v_add_u32_e32 v0, 0xd00, v189
	ds_read_b128 v[2:5], v2
	v_ashrrev_i32_e32 v0, 5, v0
	v_mad_u64_u32 v[6:7], s[14:15], v0, s55, v[10:11]
	ds_read_b128 v[6:9], v6
	v_add_u32_e32 v0, s12, v0
	s_waitcnt lgkmcnt(1)
	global_store_dwordx4 v[14:15], v[2:5], off nt
	s_nop 1
	v_mad_i64_i32 v[2:3], s[14:15], v0, s35, v[12:13]
	v_add_u32_e32 v0, 0xe00, v189
	v_ashrrev_i32_e32 v0, 5, v0
	s_waitcnt lgkmcnt(0)
	global_store_dwordx4 v[2:3], v[6:9], off nt
	v_mad_u64_u32 v[2:3], s[14:15], v0, s55, v[10:11]
	v_add_u32_e32 v0, s12, v0
	v_mad_i64_i32 v[14:15], s[14:15], v0, s35, v[12:13]
	v_add_u32_e32 v0, 0xf00, v189
	v_ashrrev_i32_e32 v0, 5, v0
	ds_read_b128 v[2:5], v2
	v_mad_u64_u32 v[6:7], s[14:15], v0, s55, v[10:11]
	ds_read_b128 v[6:9], v6
	v_add_u32_e32 v0, s12, v0
	s_waitcnt lgkmcnt(1)
	global_store_dwordx4 v[14:15], v[2:5], off nt
	s_nop 1
	v_mad_i64_i32 v[2:3], s[12:13], v0, s35, v[12:13]
	s_waitcnt lgkmcnt(0)
	global_store_dwordx4 v[2:3], v[6:9], off nt
	s_barrier
	s_cbranch_scc0 .LBB0_183
	v_mov_b64_e32 v[6:7], v[130:131]
	v_mov_b64_e32 v[2:3], v[134:135]
	v_mov_b32_e32 v31, v214
	v_mov_b32_e32 v30, v215
	v_mov_b32_e32 v29, v216
	v_mov_b32_e32 v28, v217
	v_mov_b64_e32 v[8:9], v[132:133]
	v_mov_b64_e32 v[4:5], v[136:137]
	v_readlane_b32 s44, v250, 17

; #define LAS __attribute__((address_space(3)))
;     ...
;   const int lane = tid & 63, wid = __builtin_amdgcn_readfirstlane(tid >> 6), wr = wid >> 1, wc = wid & 1;
;   const int m0 = mt * 128, n0 = nt * 256;
;   const int r = lane & 31, h = lane >> 5, key = (r >> 2) & 3;
;   constexpr int STG = 24576;
;   const int rowl = lane >> 2, cch = (lane & 3) ^ ((lane >> 4) & 3);
;   const unsigned voffA = (unsigned)(rowl * lda * 2 + cch * 16), voffB = (unsigned)(rowl * K * 2 + cch * 16);
;   const char* Abase = (const char*)(A + (size_t)m0 * lda) + (size_t)(wid * 2) * 32 * lda;
;   const char* Bbase = (const char*)(Bt + (size_t)n0 * K) + (size_t)(wid * 4) * 32 * K;
;   const size_t ablk = (size_t)32 * lda, bblk = (size_t)32 * K;
;   LAS char* lds = (LAS char*)smem;
;   LAS char* ldsA = lds + (wid * 2) * 1024;
;   LAS char* ldsB = lds + 8192 + (wid * 4) * 1024;
;     ...
;   const int x0 = ((0 + h) ^ key) * 16, x1 = ((2 + h) ^ key) * 16;
;   const int a_rd = (wr * 64 + r) * 64, b_rd = 8192 + (wc * 128 + r) * 64;
;   f32x16 acc[2][4];
; #pragma unroll
;   for (int i = 0; i < 2; ++i)
; #pragma unroll
;     for (int j = 0; j < 4; ++j)
; #pragma unroll
;       for (int e = 0; e < 16; ++e) acc[i][j][e] = 0.f;
;   const int nk = K >> 5;
;   DMA_STEP_(0, 0);
;   DMA_STEP_(1, STG);
;   asm volatile("s_waitcnt vmcnt(6)" ::: "memory");
;   __builtin_amdgcn_s_barrier();
;   asm volatile("" ::: "memory");
;   int s0 = 0, s2 = 2 * STG;
;   for (int kt = 0; kt < nk; ++kt) {
;     const int kn = (kt + 2 < nk) ? (kt + 2) : (nk - 1);
;     const LAS char* cur = lds + s0;
;     bf16x8 af[2][2], bfr[2][4];
; #pragma unroll
;     for (int kk = 0; kk < 2; ++kk) {
;       const int xo = kk ? x1 : x0;
;       af[kk][0] = *(const LAS bf16x8*)(cur + a_rd + xo);
;       bfr[kk][0] = *(const LAS bf16x8*)(cur + b_rd + xo);
.LBB0_234:
	v_mov_b32_e32 v189, v188
	s_lshl_b32 s12, s23, 7
	v_readfirstlane_b32 s42, v189
	s_ashr_i32 s44, s42, 6
	s_lshl_b32 s28, s44, 2
	s_ashr_i32 s29, s28, 31
	s_lshl_b32 s23, s44, 12
	s_lshl_b64 s[40:41], s[28:29], 10
	s_add_i32 s28, s23, 16
	s_ashr_i32 s23, s42, 1
	v_and_b32_e32 v0, 31, v189
	s_andn2_b32 s23, s23, 63
	v_lshlrev_b32_e32 v2, 4, v189
	s_lshl_b32 s10, s44, 1
	v_or_b32_e32 v197, s23, v0
	s_lshl_b32 s23, s44, 7
	v_bitop3_b32 v2, v2, 48, v189 bitop3:0x48
	v_lshlrev_b32_e32 v3, 9, v189
	s_ashr_i32 s13, s12, 31
	s_ashr_i32 s11, s10, 31
	s_and_b32 s23, s23, 0x80
	s_movk_i32 s42, 0x7800
	s_lshl_b64 s[10:11], s[10:11], 10
	s_add_i32 s29, s28, 0x2000
	v_or_b32_e32 v4, s23, v0
	v_and_or_b32 v0, v3, s42, v2
	v_lshlrev_b32_e32 v10, 4, v189
	v_and_b32_e32 v10, 0x3c0, v10
	v_or_b32_e32 v10, v10, v2
	v_mov_b32_e32 v11, 0
	s_lshl_b64 s[42:43], s[12:13], 6
	s_add_u32 s13, s18, s42
	s_addc_u32 s42, s19, s43
	s_add_u32 s10, s13, s10
	s_addc_u32 s11, s42, s11
	s_lshl_b64 s[42:43], s[14:15], 6
	s_add_u32 s13, s20, s42
	s_addc_u32 s42, s21, s43
	s_add_u32 s40, s13, s40
	s_addc_u32 s41, s42, s41
	s_lshl_b32 s13, s44, 11
	s_sub_i32 s13, s28, s13
	v_lshl_add_u64 v[192:193], s[10:11], 0, v[10:11]
	s_mov_b32 m0, s13
	s_nop 0
	global_load_lds_dwordx4 v[192:193], off
	global_load_lds_dwordx4 v[192:193], off offset:1024
	v_lshl_add_u64 v[194:195], s[40:41], 0, v[10:11]
	s_mov_b32 m0, s29
	s_nop 0
	global_load_lds_dwordx4 v[194:195], off
	global_load_lds_dwordx4 v[194:195], off offset:1024
	global_load_lds_dwordx4 v[194:195], off offset:2048
	global_load_lds_dwordx4 v[194:195], off offset:3072
	s_mov_b64 s[10:11], 0x10000
	s_mov_b64 s[10:11], 0x18000
	s_mov_b64 s[10:11], 0x8040
	s_add_i32 m0, s13, 0x6000
	s_mov_b32 vcc_lo, 0x480000
	s_mov_b32 vcc_hi, 0
	v_lshl_add_u64 v[2:3], v[192:193], 0, vcc
	global_load_lds_dwordx4 v[2:3], off
	global_load_lds_dwordx4 v[2:3], off offset:1024
	v_bfe_u32 v196, v189, 5, 1
	s_add_i32 m0, s28, 0x8000
	s_mov_b32 s100, 0x24000
	v_lshl_add_u64 v[2:3], v[194:195], 0, s[100:101]
	global_load_lds_dwordx4 v[2:3], off
	global_load_lds_dwordx4 v[2:3], off offset:1024
	global_load_lds_dwordx4 v[2:3], off offset:2048
	global_load_lds_dwordx4 v[2:3], off offset:3072
	s_mov_b64 s[10:11], 0x10040
	s_mov_b64 s[10:11], 0x18040
	v_lshlrev_b32_e32 v218, 6, v4
	v_bfe_u32 v4, v189, 2, 2
	v_lshrrev_b32_e32 v5, 5, v189
	s_lshl_b32 s100, s100, 1
	v_lshl_add_u64 v[194:195], v[194:195], 0, s[100:101]
	s_lshl_b32 vcc_lo, vcc_lo, 1
	v_lshl_add_u64 v[192:193], v[192:193], 0, vcc
	s_waitcnt vmcnt(6)
	s_barrier
	v_bitop3_b32 v2, v196, v4, 2 bitop3:0x36
	v_bitop3_b32 v0, v5, v4, 1 bitop3:0x6c
	v_lshlrev_b32_e32 v220, 4, v2
	v_mov_b32_e32 v2, 0
	v_lshlrev_b32_e32 v219, 6, v197
	v_lshlrev_b32_e32 v0, 4, v0
	s_mov_b32 s40, 0xc000
	s_mov_b32 s29, 0
	s_mov_b32 s41, 0
	v_mov_b32_e32 v3, v2
	v_mov_b32_e32 v4, v2
	v_mov_b32_e32 v5, v2
	v_mov_b32_e32 v6, v2
	v_mov_b32_e32 v7, v2
	v_mov_b32_e32 v8, v2
	v_mov_b32_e32 v9, v2
	v_mov_b32_e32 v10, v2
	v_mov_b32_e32 v11, v2
	v_mov_b32_e32 v12, v2
	v_mov_b32_e32 v13, v2
	v_mov_b32_e32 v14, v2
	v_mov_b32_e32 v15, v2
	v_mov_b32_e32 v16, v2
	v_mov_b32_e32 v17, v2
	v_mov_b32_e32 v18, v2
	v_mov_b32_e32 v19, v2
	v_mov_b32_e32 v20, v2
	v_mov_b32_e32 v21, v2
	v_mov_b32_e32 v22, v2
	v_mov_b32_e32 v23, v2
	v_mov_b32_e32 v24, v2
	v_mov_b32_e32 v25, v2
	v_mov_b32_e32 v26, v2
	v_mov_b32_e32 v27, v2
	v_mov_b32_e32 v28, v2
	v_mov_b32_e32 v29, v2
	v_mov_b32_e32 v30, v2
	v_mov_b32_e32 v31, v2
	v_mov_b32_e32 v32, v2
	v_mov_b32_e32 v33, v2
	v_mov_b32_e32 v50, v2
	v_mov_b32_e32 v51, v2
	v_mov_b32_e32 v52, v2
	v_mov_b32_e32 v53, v2
	v_mov_b32_e32 v54, v2
	v_mov_b32_e32 v55, v2
	v_mov_b32_e32 v56, v2
	v_mov_b32_e32 v57, v2
	v_mov_b32_e32 v58, v2
	v_mov_b32_e32 v59, v2
	v_mov_b32_e32 v60, v2
	v_mov_b32_e32 v61, v2
	v_mov_b32_e32 v62, v2
	v_mov_b32_e32 v63, v2
	v_mov_b32_e32 v64, v2
	v_mov_b32_e32 v65, v2
	v_mov_b32_e32 v82, v2
	v_mov_b32_e32 v83, v2
	v_mov_b32_e32 v84, v2
	v_mov_b32_e32 v85, v2
	v_mov_b32_e32 v86, v2
	v_mov_b32_e32 v87, v2
	v_mov_b32_e32 v88, v2
	v_mov_b32_e32 v89, v2
	v_mov_b32_e32 v90, v2
	v_mov_b32_e32 v91, v2
	v_mov_b32_e32 v92, v2
	v_mov_b32_e32 v93, v2
	v_mov_b32_e32 v94, v2
	v_mov_b32_e32 v95, v2
	v_mov_b32_e32 v96, v2
	v_mov_b32_e32 v97, v2
	v_mov_b32_e32 v34, v2
	v_mov_b32_e32 v35, v2
	v_mov_b32_e32 v36, v2
	v_mov_b32_e32 v37, v2
	v_mov_b32_e32 v38, v2
	v_mov_b32_e32 v39, v2
	v_mov_b32_e32 v40, v2
	v_mov_b32_e32 v41, v2
	v_mov_b32_e32 v42, v2
	v_mov_b32_e32 v43, v2
	v_mov_b32_e32 v44, v2
	v_mov_b32_e32 v45, v2
	v_mov_b32_e32 v46, v2
	v_mov_b32_e32 v47, v2
	v_mov_b32_e32 v48, v2
	v_mov_b32_e32 v49, v2
	v_mov_b32_e32 v66, v2
	v_mov_b32_e32 v67, v2
	v_mov_b32_e32 v68, v2
	v_mov_b32_e32 v69, v2
	v_mov_b32_e32 v70, v2
	v_mov_b32_e32 v71, v2
	v_mov_b32_e32 v72, v2
	v_mov_b32_e32 v73, v2
	v_mov_b32_e32 v74, v2
	v_mov_b32_e32 v75, v2
	v_mov_b32_e32 v76, v2
	v_mov_b32_e32 v77, v2
	v_mov_b32_e32 v78, v2
	v_mov_b32_e32 v79, v2
	v_mov_b32_e32 v80, v2
	v_mov_b32_e32 v81, v2
	v_mov_b32_e32 v98, v2
	v_mov_b32_e32 v99, v2
	v_mov_b32_e32 v100, v2
	v_mov_b32_e32 v101, v2
	v_mov_b32_e32 v102, v2
	v_mov_b32_e32 v103, v2
	v_mov_b32_e32 v104, v2
	v_mov_b32_e32 v105, v2
	v_mov_b32_e32 v106, v2
	v_mov_b32_e32 v107, v2
	v_mov_b32_e32 v108, v2
	v_mov_b32_e32 v109, v2
	v_mov_b32_e32 v110, v2
	v_mov_b32_e32 v111, v2
	v_mov_b32_e32 v112, v2
	v_mov_b32_e32 v113, v2
	v_mov_b32_e32 v114, v2
	v_mov_b32_e32 v115, v2
	v_mov_b32_e32 v116, v2
	v_mov_b32_e32 v117, v2
	v_mov_b32_e32 v118, v2
	v_mov_b32_e32 v119, v2
	v_mov_b32_e32 v120, v2
	v_mov_b32_e32 v121, v2
	v_mov_b32_e32 v122, v2
	v_mov_b32_e32 v123, v2
	v_mov_b32_e32 v124, v2
	v_mov_b32_e32 v125, v2
	v_mov_b32_e32 v126, v2
	v_mov_b32_e32 v127, v2
	v_mov_b32_e32 v128, v2
	v_mov_b32_e32 v129, v2
	s_mov_b32 vcc_hi, 0
	v_add_u32_e32 v226, v219, v0
	v_add_u32_e32 v227, v218, v0
	v_add_u32_e32 v228, v219, v220
	v_add_u32_e32 v229, v218, v220
	v_add_u32_e32 v158, 16, v226
	v_add_u32_e32 v170, 16, v227
	ds_read_b128 v[154:157], v158
	ds_read_b128 v[182:185], v170 offset:8192
	ds_read_b128 v[178:181], v170 offset:10240
	ds_read_b128 v[158:161], v158 offset:2048
	ds_read_b128 v[174:177], v170 offset:12288
	ds_read_b128 v[170:173], v170 offset:14336
	s_setprio 1
; #define LAS __attribute__((address_space(3)))
; DI f32x16 mfma32(bf16x8 a, bf16x8 b, f32x16 c) { return __builtin_amdgcn_mfma_f32_32x32x16_bf16(a, b, c, 0, 0, 0); }
;     ...
;   for (int kt = 0; kt < nk; ++kt) {
;     const int kn = (kt + 2 < nk) ? (kt + 2) : (nk - 1);
;     const LAS char* cur = lds + s0;
;     bf16x8 af[2][2], bfr[2][4];
; #pragma unroll
;     for (int kk = 0; kk < 2; ++kk) {
;       const int xo = kk ? x1 : x0;
;       af[kk][0] = *(const LAS bf16x8*)(cur + a_rd + xo);
;       bfr[kk][0] = *(const LAS bf16x8*)(cur + b_rd + xo);
;       bfr[kk][1] = *(const LAS bf16x8*)(cur + b_rd + 2048 + xo);
;       af[kk][1] = *(const LAS bf16x8*)(cur + a_rd + 2048 + xo);
;       bfr[kk][2] = *(const LAS bf16x8*)(cur + b_rd + 4096 + xo);
;       bfr[kk][3] = *(const LAS bf16x8*)(cur + b_rd + 6144 + xo);
;     }
;     DMA_STEP_(kn, s2);
; #pragma unroll
;     for (int kk = 0; kk < 2; ++kk) {
;       acc[0][0] = mfma32(bfr[kk][0], af[kk][0], acc[0][0]); acc[0][1] = mfma32(bfr[kk][1], af[kk][0], acc[0][1]);
;       acc[1][0] = mfma32(bfr[kk][0], af[kk][1], acc[1][0]); acc[1][1] = mfma32(bfr[kk][1], af[kk][1], acc[1][1]);
;       acc[0][2] = mfma32(bfr[kk][2], af[kk][0], acc[0][2]); acc[0][3] = mfma32(bfr[kk][3], af[kk][0], acc[0][3]);
;       acc[1][2] = mfma32(bfr[kk][2], af[kk][1], acc[1][2]); acc[1][3] = mfma32(bfr[kk][3], af[kk][1], acc[1][3]);
;     }
;     __builtin_amdgcn_sched_group_barrier(0x100, 12, 0);
;     __builtin_amdgcn_sched_group_barrier(0x010, 6, 0);
;     __builtin_amdgcn_sched_group_barrier(0x008, 16, 0);
;     asm volatile("s_waitcnt vmcnt(6) lgkmcnt(0)" ::: "memory");
;     __builtin_amdgcn_s_barrier();
;     asm volatile("" ::: "memory");
;     s0 = (s0 == 2 * STG) ? 0 : s0 + STG;
;     s2 = (s2 == 2 * STG) ? 0 : s2 + STG;
;   }
.LBB0_235:
	s_add_i32 s11, s41, 16
	s_mov_b32 s10, s29
	v_add_u32_e32 v142, s11, v228
	v_add_u32_e32 v150, s11, v229
	s_min_u32 s10, s10, 29
	s_lshl_b32 s70, s10, 6
	ds_read_b128 v[138:141], v142
	ds_read_b128 v[162:165], v150 offset:8192
	ds_read_b128 v[166:169], v150 offset:10240
	ds_read_b128 v[142:145], v142 offset:2048
	ds_read_b128 v[146:149], v150 offset:12288
	ds_read_b128 v[150:153], v150 offset:14336
	s_mul_i32 vcc_lo, s70, 0x12000
	s_add_i32 s10, s13, s40
	v_lshl_add_u64 v[222:223], v[192:193], 0, vcc
	s_mov_b32 m0, s10
	s_mul_i32 s100, s70, 0x900
	v_lshl_add_u64 v[224:225], v[194:195], 0, s[100:101]
	s_add_i32 s10, s28, s40
	s_waitcnt lgkmcnt(6)
	v_mfma_f32_32x32x16_bf16 v[114:129], v[182:185], v[154:157], v[114:129]
	global_load_lds_dwordx4 v[222:223], off
	v_mfma_f32_32x32x16_bf16 v[98:113], v[178:181], v[154:157], v[98:113]
	global_load_lds_dwordx4 v[222:223], off offset:1024
	s_add_i32 m0, s10, 0x2000
	v_mfma_f32_32x32x16_bf16 v[66:81], v[182:185], v[158:161], v[66:81]
	global_load_lds_dwordx4 v[224:225], off
	v_mfma_f32_32x32x16_bf16 v[34:49], v[178:181], v[158:161], v[34:49]
	global_load_lds_dwordx4 v[224:225], off offset:1024
	v_mfma_f32_32x32x16_bf16 v[82:97], v[174:177], v[154:157], v[82:97]
	global_load_lds_dwordx4 v[224:225], off offset:2048
	v_mfma_f32_32x32x16_bf16 v[50:65], v[170:173], v[154:157], v[50:65]
	global_load_lds_dwordx4 v[224:225], off offset:3072
	v_mfma_f32_32x32x16_bf16 v[18:33], v[174:177], v[158:161], v[18:33]
	s_add_i32 s10, s41, 0x6000
	s_cmpk_lg_u32 s41, 0xc000
	s_cselect_b32 s41, s10, 0
	s_add_i32 s10, s40, 0x6000
	s_cmpk_lg_u32 s40, 0xc000
	s_cselect_b32 s40, s10, 0
	v_mfma_f32_32x32x16_bf16 v[2:17], v[170:173], v[158:161], v[2:17]
	s_add_i32 s11, s41, 16
	s_waitcnt vmcnt(6) lgkmcnt(0)
	s_barrier
	v_add_u32_e32 v158, s11, v226
	v_add_u32_e32 v170, s11, v227
	ds_read_b128 v[154:157], v158
	ds_read_b128 v[182:185], v170 offset:8192
	ds_read_b128 v[178:181], v170 offset:10240
	ds_read_b128 v[158:161], v158 offset:2048
	ds_read_b128 v[174:177], v170 offset:12288
	ds_read_b128 v[170:173], v170 offset:14336
	v_mfma_f32_32x32x16_bf16 v[114:129], v[162:165], v[138:141], v[114:129]
	v_mfma_f32_32x32x16_bf16 v[98:113], v[166:169], v[138:141], v[98:113]
	v_mfma_f32_32x32x16_bf16 v[66:81], v[162:165], v[142:145], v[66:81]
	v_mfma_f32_32x32x16_bf16 v[34:49], v[166:169], v[142:145], v[34:49]
	v_mfma_f32_32x32x16_bf16 v[82:97], v[146:149], v[138:141], v[82:97]
	v_mfma_f32_32x32x16_bf16 v[50:65], v[150:153], v[138:141], v[50:65]
	v_mfma_f32_32x32x16_bf16 v[18:33], v[146:149], v[142:145], v[18:33]
	v_mfma_f32_32x32x16_bf16 v[2:17], v[150:153], v[142:145], v[2:17]
	s_add_i32 s11, s41, 16
	s_add_i32 s10, s29, 1
	v_add_u32_e32 v142, s11, v228
	v_add_u32_e32 v150, s11, v229
	s_min_u32 s10, s10, 29
	s_lshl_b32 s70, s10, 6
	ds_read_b128 v[138:141], v142
	ds_read_b128 v[162:165], v150 offset:8192
	ds_read_b128 v[166:169], v150 offset:10240
	ds_read_b128 v[142:145], v142 offset:2048
	ds_read_b128 v[146:149], v150 offset:12288
	ds_read_b128 v[150:153], v150 offset:14336
	s_mul_i32 vcc_lo, s70, 0x12000
	s_add_i32 s10, s13, s40
	v_lshl_add_u64 v[222:223], v[192:193], 0, vcc
	s_mov_b32 m0, s10
	s_mul_i32 s100, s70, 0x900
	v_lshl_add_u64 v[224:225], v[194:195], 0, s[100:101]
	s_add_i32 s10, s28, s40
	s_waitcnt lgkmcnt(6)
	v_mfma_f32_32x32x16_bf16 v[114:129], v[182:185], v[154:157], v[114:129]
	global_load_lds_dwordx4 v[222:223], off
	v_mfma_f32_32x32x16_bf16 v[98:113], v[178:181], v[154:157], v[98:113]
	global_load_lds_dwordx4 v[222:223], off offset:1024
	s_add_i32 m0, s10, 0x2000
	v_mfma_f32_32x32x16_bf16 v[66:81], v[182:185], v[158:161], v[66:81]
	global_load_lds_dwordx4 v[224:225], off
	v_mfma_f32_32x32x16_bf16 v[34:49], v[178:181], v[158:161], v[34:49]
	global_load_lds_dwordx4 v[224:225], off offset:1024
	v_mfma_f32_32x32x16_bf16 v[82:97], v[174:177], v[154:157], v[82:97]
	global_load_lds_dwordx4 v[224:225], off offset:2048
	v_mfma_f32_32x32x16_bf16 v[50:65], v[170:173], v[154:157], v[50:65]
	global_load_lds_dwordx4 v[224:225], off offset:3072
	v_mfma_f32_32x32x16_bf16 v[18:33], v[174:177], v[158:161], v[18:33]
	s_add_i32 s10, s41, 0x6000
	s_cmpk_lg_u32 s41, 0xc000
	s_cselect_b32 s41, s10, 0
	s_add_i32 s10, s40, 0x6000
	s_cmpk_lg_u32 s40, 0xc000
	s_cselect_b32 s40, s10, 0
	v_mfma_f32_32x32x16_bf16 v[2:17], v[170:173], v[158:161], v[2:17]
	s_add_i32 s11, s41, 16
	s_waitcnt vmcnt(6) lgkmcnt(0)
	s_barrier
	v_add_u32_e32 v158, s11, v226
	v_add_u32_e32 v170, s11, v227
	ds_read_b128 v[154:157], v158
	ds_read_b128 v[182:185], v170 offset:8192
	ds_read_b128 v[178:181], v170 offset:10240
	ds_read_b128 v[158:161], v158 offset:2048
	ds_read_b128 v[174:177], v170 offset:12288
	ds_read_b128 v[170:173], v170 offset:14336
	v_mfma_f32_32x32x16_bf16 v[114:129], v[162:165], v[138:141], v[114:129]
	v_mfma_f32_32x32x16_bf16 v[98:113], v[166:169], v[138:141], v[98:113]
	v_mfma_f32_32x32x16_bf16 v[66:81], v[162:165], v[142:145], v[66:81]
	v_mfma_f32_32x32x16_bf16 v[34:49], v[166:169], v[142:145], v[34:49]
	v_mfma_f32_32x32x16_bf16 v[82:97], v[146:149], v[138:141], v[82:97]
	v_mfma_f32_32x32x16_bf16 v[50:65], v[150:153], v[138:141], v[50:65]
	v_mfma_f32_32x32x16_bf16 v[18:33], v[146:149], v[142:145], v[18:33]
	v_mfma_f32_32x32x16_bf16 v[2:17], v[150:153], v[142:145], v[2:17]
	s_add_i32 s29, s29, 2
	s_cmp_lg_u32 s29, 30
	s_cbranch_scc1 .LBB0_235
; #define LAS __attribute__((address_space(3)))
; DI unsigned pk2(float a, float b) { f32x2 v = {a, b}; bf2_t r = __builtin_convertvector(v, bf2_t); return __builtin_bit_cast(unsigned, r); }
;     ...
;   for (int kt = 0; kt < nk; ++kt) {
;     const int kn = (kt + 2 < nk) ? (kt + 2) : (nk - 1);
;     const LAS char* cur = lds + s0;
;     bf16x8 af[2][2], bfr[2][4];
; #pragma unroll
;     for (int kk = 0; kk < 2; ++kk) {
;       const int xo = kk ? x1 : x0;
;       af[kk][0] = *(const LAS bf16x8*)(cur + a_rd + xo);
;       bfr[kk][0] = *(const LAS bf16x8*)(cur + b_rd + xo);
;       bfr[kk][1] = *(const LAS bf16x8*)(cur + b_rd + 2048 + xo);
;       af[kk][1] = *(const LAS bf16x8*)(cur + a_rd + 2048 + xo);
;       bfr[kk][2] = *(const LAS bf16x8*)(cur + b_rd + 4096 + xo);
;       bfr[kk][3] = *(const LAS bf16x8*)(cur + b_rd + 6144 + xo);
;     }
;     DMA_STEP_(kn, s2);
; #pragma unroll
;     for (int kk = 0; kk < 2; ++kk) {
;       acc[0][0] = mfma32(bfr[kk][0], af[kk][0], acc[0][0]); acc[0][1] = mfma32(bfr[kk][1], af[kk][0], acc[0][1]);
;       acc[1][0] = mfma32(bfr[kk][0], af[kk][1], acc[1][0]); acc[1][1] = mfma32(bfr[kk][1], af[kk][1], acc[1][1]);
;       acc[0][2] = mfma32(bfr[kk][2], af[kk][0], acc[0][2]); acc[0][3] = mfma32(bfr[kk][3], af[kk][0], acc[0][3]);
;       acc[1][2] = mfma32(bfr[kk][2], af[kk][1], acc[1][2]); acc[1][3] = mfma32(bfr[kk][3], af[kk][1], acc[1][3]);
;     }
;     __builtin_amdgcn_sched_group_barrier(0x100, 12, 0);
;     __builtin_amdgcn_sched_group_barrier(0x010, 6, 0);
;     __builtin_amdgcn_sched_group_barrier(0x008, 16, 0);
;     asm volatile("s_waitcnt vmcnt(6) lgkmcnt(0)" ::: "memory");
;     __builtin_amdgcn_s_barrier();
;     asm volatile("" ::: "memory");
;     s0 = (s0 == 2 * STG) ? 0 : s0 + STG;
;     s2 = (s2 == 2 * STG) ? 0 : s2 + STG;
;   }
;   asm volatile("s_waitcnt vmcnt(0)" ::: "memory");
;   __builtin_amdgcn_s_barrier();
;   asm volatile("" ::: "memory");
;     ...
;   {
;     const int h = lane >> 5, cl = lane & 31;
; #pragma unroll
;     for (int i = 0; i < 2; ++i)
; #pragma unroll
;       for (int j = 0; j < 4; ++j)
; #pragma unroll
;         for (int g = 0; g < 4; ++g) {
;           u32x2 w; w.x = pk2(acc[i][j][4 * g], acc[i][j][4 * g + 1]); w.y = pk2(acc[i][j][4 * g + 2], acc[i][j][4 * g + 3]);
;           *(u32x2*)(smem + (wr * 64 + i * 32 + cl) * 528 + (wc * 128 + j * 32 + 8 * g + 4 * h) * 2) = w;
;         }
	s_add_i32 s11, s41, 16
	v_add_u32_e32 v142, s11, v228
	v_add_u32_e32 v150, s11, v229
	ds_read_b128 v[138:141], v142
	ds_read_b128 v[162:165], v150 offset:8192
	ds_read_b128 v[166:169], v150 offset:10240
	ds_read_b128 v[142:145], v142 offset:2048
	ds_read_b128 v[146:149], v150 offset:12288
	ds_read_b128 v[150:153], v150 offset:14336
	s_waitcnt lgkmcnt(6)
	v_mfma_f32_32x32x16_bf16 v[114:129], v[182:185], v[154:157], v[114:129]
	v_mfma_f32_32x32x16_bf16 v[98:113], v[178:181], v[154:157], v[98:113]
	v_mfma_f32_32x32x16_bf16 v[66:81], v[182:185], v[158:161], v[66:81]
	v_mfma_f32_32x32x16_bf16 v[34:49], v[178:181], v[158:161], v[34:49]
	v_mfma_f32_32x32x16_bf16 v[82:97], v[174:177], v[154:157], v[82:97]
	v_mfma_f32_32x32x16_bf16 v[50:65], v[170:173], v[154:157], v[50:65]
	v_mfma_f32_32x32x16_bf16 v[18:33], v[174:177], v[158:161], v[18:33]
	s_add_i32 s10, s41, 0x6000
	s_cmpk_lg_u32 s41, 0xc000
	s_cselect_b32 s41, s10, 0
	v_mfma_f32_32x32x16_bf16 v[2:17], v[170:173], v[158:161], v[2:17]
	s_add_i32 s11, s41, 16
	s_waitcnt vmcnt(0) lgkmcnt(0)
	s_barrier
	v_add_u32_e32 v158, s11, v226
	v_add_u32_e32 v170, s11, v227
	ds_read_b128 v[154:157], v158
	ds_read_b128 v[182:185], v170 offset:8192
	ds_read_b128 v[178:181], v170 offset:10240
	ds_read_b128 v[158:161], v158 offset:2048
	ds_read_b128 v[174:177], v170 offset:12288
	ds_read_b128 v[170:173], v170 offset:14336
	v_mfma_f32_32x32x16_bf16 v[114:129], v[162:165], v[138:141], v[114:129]
	v_mfma_f32_32x32x16_bf16 v[98:113], v[166:169], v[138:141], v[98:113]
	v_mfma_f32_32x32x16_bf16 v[66:81], v[162:165], v[142:145], v[66:81]
	v_mfma_f32_32x32x16_bf16 v[34:49], v[166:169], v[142:145], v[34:49]
	v_mfma_f32_32x32x16_bf16 v[82:97], v[146:149], v[138:141], v[82:97]
	v_mfma_f32_32x32x16_bf16 v[50:65], v[150:153], v[138:141], v[50:65]
	v_mfma_f32_32x32x16_bf16 v[18:33], v[146:149], v[142:145], v[18:33]
	v_mfma_f32_32x32x16_bf16 v[2:17], v[150:153], v[142:145], v[2:17]
	s_add_i32 s11, s41, 16
	v_add_u32_e32 v142, s11, v228
	v_add_u32_e32 v150, s11, v229
	ds_read_b128 v[138:141], v142
	ds_read_b128 v[162:165], v150 offset:8192
	ds_read_b128 v[166:169], v150 offset:10240
	ds_read_b128 v[142:145], v142 offset:2048
	ds_read_b128 v[146:149], v150 offset:12288
	ds_read_b128 v[150:153], v150 offset:14336
	s_waitcnt lgkmcnt(6)
	v_mfma_f32_32x32x16_bf16 v[114:129], v[182:185], v[154:157], v[114:129]
	v_mfma_f32_32x32x16_bf16 v[98:113], v[178:181], v[154:157], v[98:113]
	v_mfma_f32_32x32x16_bf16 v[66:81], v[182:185], v[158:161], v[66:81]
	v_mfma_f32_32x32x16_bf16 v[34:49], v[178:181], v[158:161], v[34:49]
	v_mfma_f32_32x32x16_bf16 v[82:97], v[174:177], v[154:157], v[82:97]
	v_mfma_f32_32x32x16_bf16 v[50:65], v[170:173], v[154:157], v[50:65]
	v_mfma_f32_32x32x16_bf16 v[18:33], v[174:177], v[158:161], v[18:33]
	v_mfma_f32_32x32x16_bf16 v[2:17], v[170:173], v[158:161], v[2:17]
	s_waitcnt lgkmcnt(0)
	v_mfma_f32_32x32x16_bf16 v[114:129], v[162:165], v[138:141], v[114:129]
	v_mfma_f32_32x32x16_bf16 v[98:113], v[166:169], v[138:141], v[98:113]
	v_mfma_f32_32x32x16_bf16 v[66:81], v[162:165], v[142:145], v[66:81]
	v_mfma_f32_32x32x16_bf16 v[34:49], v[166:169], v[142:145], v[34:49]
	v_mfma_f32_32x32x16_bf16 v[82:97], v[146:149], v[138:141], v[82:97]
	v_mfma_f32_32x32x16_bf16 v[50:65], v[150:153], v[138:141], v[50:65]
	v_mfma_f32_32x32x16_bf16 v[18:33], v[146:149], v[142:145], v[18:33]
	v_mfma_f32_32x32x16_bf16 v[2:17], v[150:153], v[142:145], v[2:17]
	s_waitcnt lgkmcnt(0)
	s_setprio 0
	v_mul_lo_u32 v0, v197, s55
	v_add_u32_e32 v0, 16, v0
	s_nop 1
	v_cvt_pk_bf16_f32 v114, v114, v115
	v_cvt_pk_bf16_f32 v115, v116, v117
	v_lshlrev_b32_e32 v116, 3, v196
	s_lshl_b32 s10, s23, 1
	v_add3_u32 v0, v0, v116, s10
	v_cvt_pk_bf16_f32 v116, v118, v119
	v_cvt_pk_bf16_f32 v117, v120, v121
	v_cvt_pk_bf16_f32 v98, v98, v99
	v_cvt_pk_bf16_f32 v99, v100, v101
	v_cvt_pk_bf16_f32 v100, v102, v103
	v_cvt_pk_bf16_f32 v101, v104, v105
	v_cvt_pk_bf16_f32 v82, v82, v83
	v_cvt_pk_bf16_f32 v83, v84, v85
	v_cvt_pk_bf16_f32 v84, v86, v87
	v_cvt_pk_bf16_f32 v85, v88, v89
	v_cvt_pk_bf16_f32 v50, v50, v51
	v_cvt_pk_bf16_f32 v51, v52, v53
	v_cvt_pk_bf16_f32 v52, v54, v55
	v_cvt_pk_bf16_f32 v53, v56, v57
	s_waitcnt vmcnt(0)
	s_barrier
	ds_write2_b64 v0, v[114:115], v[116:117] offset1:2
	v_cvt_pk_bf16_f32 v114, v122, v123
	v_cvt_pk_bf16_f32 v115, v124, v125
	v_cvt_pk_bf16_f32 v116, v126, v127
	v_cvt_pk_bf16_f32 v117, v128, v129
	ds_write2_b64 v0, v[98:99], v[100:101] offset0:8 offset1:10
	v_cvt_pk_bf16_f32 v98, v106, v107
	v_cvt_pk_bf16_f32 v99, v108, v109
	v_cvt_pk_bf16_f32 v100, v110, v111
	v_cvt_pk_bf16_f32 v101, v112, v113
	ds_write2_b64 v0, v[82:83], v[84:85] offset0:16 offset1:18
	v_cvt_pk_bf16_f32 v82, v90, v91
	v_cvt_pk_bf16_f32 v83, v92, v93
	v_cvt_pk_bf16_f32 v84, v94, v95
	v_cvt_pk_bf16_f32 v85, v96, v97
	ds_write2_b64 v0, v[50:51], v[52:53] offset0:24 offset1:26
	v_cvt_pk_bf16_f32 v50, v58, v59
	v_cvt_pk_bf16_f32 v51, v60, v61
	v_cvt_pk_bf16_f32 v52, v62, v63
	v_cvt_pk_bf16_f32 v53, v64, v65
	ds_write2_b64 v0, v[114:115], v[116:117] offset0:4 offset1:6
	ds_write2_b64 v0, v[98:99], v[100:101] offset0:12 offset1:14
	ds_write2_b64 v0, v[82:83], v[84:85] offset0:20 offset1:22
	ds_write2_b64 v0, v[50:51], v[52:53] offset0:28 offset1:30
	v_cvt_pk_bf16_f32 v50, v66, v67
	v_cvt_pk_bf16_f32 v51, v68, v69
	v_cvt_pk_bf16_f32 v52, v70, v71
	v_cvt_pk_bf16_f32 v53, v72, v73
	v_add_u32_e32 v0, 0x4000, v0
	v_cvt_pk_bf16_f32 v34, v34, v35
	v_cvt_pk_bf16_f32 v35, v36, v37
	v_cvt_pk_bf16_f32 v36, v38, v39
	v_cvt_pk_bf16_f32 v37, v40, v41
	v_cvt_pk_bf16_f32 v18, v18, v19
	v_cvt_pk_bf16_f32 v19, v20, v21
	v_cvt_pk_bf16_f32 v20, v22, v23
	v_cvt_pk_bf16_f32 v21, v24, v25
	v_cvt_pk_bf16_f32 v2, v2, v3
	v_cvt_pk_bf16_f32 v3, v4, v5
	v_cvt_pk_bf16_f32 v4, v6, v7
	v_cvt_pk_bf16_f32 v5, v8, v9
	ds_write2_b64 v0, v[50:51], v[52:53] offset0:64 offset1:66
	v_cvt_pk_bf16_f32 v50, v74, v75
	v_cvt_pk_bf16_f32 v51, v76, v77
	v_cvt_pk_bf16_f32 v52, v78, v79
	v_cvt_pk_bf16_f32 v53, v80, v81
	ds_write2_b64 v0, v[34:35], v[36:37] offset0:72 offset1:74
	v_cvt_pk_bf16_f32 v34, v42, v43
	v_cvt_pk_bf16_f32 v35, v44, v45
	v_cvt_pk_bf16_f32 v36, v46, v47
	v_cvt_pk_bf16_f32 v37, v48, v49
	ds_write2_b64 v0, v[18:19], v[20:21] offset0:80 offset1:82
	v_cvt_pk_bf16_f32 v18, v26, v27
	v_cvt_pk_bf16_f32 v19, v28, v29
	v_cvt_pk_bf16_f32 v20, v30, v31
	v_cvt_pk_bf16_f32 v21, v32, v33
	ds_write2_b64 v0, v[2:3], v[4:5] offset0:88 offset1:90
	v_cvt_pk_bf16_f32 v2, v10, v11
	v_cvt_pk_bf16_f32 v3, v12, v13
	v_cvt_pk_bf16_f32 v4, v14, v15
	v_cvt_pk_bf16_f32 v5, v16, v17
	s_lshl_b64 s[10:11], s[14:15], 1
	ds_write2_b64 v0, v[50:51], v[52:53] offset0:68 offset1:70
	ds_write2_b64 v0, v[34:35], v[36:37] offset0:76 offset1:78
	ds_write2_b64 v0, v[18:19], v[20:21] offset0:84 offset1:86
	ds_write2_b64 v0, v[2:3], v[4:5] offset0:92 offset1:94
	s_waitcnt vmcnt(0) lgkmcnt(0)
	s_barrier
; #define GAS __attribute__((address_space(1)))
;     ...
;   __syncthreads();
;   int tid2 = tid; asm volatile("" : "+v"(tid2));
;   if (EPI == 0) {
; #pragma unroll
;     for (int i = 0; i < 16; ++i) {
;       const int id = tid2 + 256 * i, r = id >> 5, c8 = (id & 31) * 8;
;       const u32x4 v = *(const u32x4*)(smem + r * 528 + c8 * 2);
;       *(GAS u32x4*)(ea.out + (size_t)(m0 + r) * ea.ldo + n0 + c8) = v;
;     }
;   } else {
	s_add_u32 s10, s16, s10
	v_lshlrev_b32_e32 v0, 4, v189
	v_and_b32_e32 v0, 0x1f0, v0
	s_addc_u32 s11, s17, s11
	v_add_u32_e32 v10, 16, v0
	v_lshl_add_u64 v[12:13], s[10:11], 0, v[0:1]
	v_ashrrev_i32_e32 v0, 5, v189
	v_mad_u64_u32 v[2:3], s[10:11], v0, s55, v[10:11]
	v_add_u32_e32 v0, s12, v0
	v_mad_i64_i32 v[14:15], s[10:11], v0, s35, v[12:13]
	v_add_u32_e32 v0, 0x100, v189
	ds_read_b128 v[2:5], v2
	v_ashrrev_i32_e32 v0, 5, v0
	v_mad_u64_u32 v[6:7], s[10:11], v0, s55, v[10:11]
	ds_read_b128 v[6:9], v6
	v_add_u32_e32 v0, s12, v0
	s_waitcnt lgkmcnt(1)
	global_store_dwordx4 v[14:15], v[2:5], off nt
	s_nop 1
	v_mad_i64_i32 v[2:3], s[10:11], v0, s35, v[12:13]
	v_add_u32_e32 v0, 0x200, v189
	v_ashrrev_i32_e32 v0, 5, v0
	s_waitcnt lgkmcnt(0)
	global_store_dwordx4 v[2:3], v[6:9], off nt
	v_mad_u64_u32 v[2:3], s[10:11], v0, s55, v[10:11]
	v_add_u32_e32 v0, s12, v0
	v_mad_i64_i32 v[14:15], s[10:11], v0, s35, v[12:13]
	v_add_u32_e32 v0, 0x300, v189
	ds_read_b128 v[2:5], v2
	v_ashrrev_i32_e32 v0, 5, v0
	v_mad_u64_u32 v[6:7], s[10:11], v0, s55, v[10:11]
	ds_read_b128 v[6:9], v6
	v_add_u32_e32 v0, s12, v0
	s_waitcnt lgkmcnt(1)
	global_store_dwordx4 v[14:15], v[2:5], off nt
	s_nop 1
	v_mad_i64_i32 v[2:3], s[10:11], v0, s35, v[12:13]
	v_add_u32_e32 v0, 0x400, v189
	v_ashrrev_i32_e32 v0, 5, v0
	s_waitcnt lgkmcnt(0)
	global_store_dwordx4 v[2:3], v[6:9], off nt
	v_mad_u64_u32 v[2:3], s[10:11], v0, s55, v[10:11]
	v_add_u32_e32 v0, s12, v0
	v_mad_i64_i32 v[14:15], s[10:11], v0, s35, v[12:13]
	v_add_u32_e32 v0, 0x500, v189
	ds_read_b128 v[2:5], v2
	v_ashrrev_i32_e32 v0, 5, v0
	v_mad_u64_u32 v[6:7], s[10:11], v0, s55, v[10:11]
	ds_read_b128 v[6:9], v6
	v_add_u32_e32 v0, s12, v0
	s_waitcnt lgkmcnt(1)
	global_store_dwordx4 v[14:15], v[2:5], off nt
	s_nop 1
	v_mad_i64_i32 v[2:3], s[10:11], v0, s35, v[12:13]
	v_add_u32_e32 v0, 0x600, v189
	v_ashrrev_i32_e32 v0, 5, v0
	s_waitcnt lgkmcnt(0)
	global_store_dwordx4 v[2:3], v[6:9], off nt
	v_mad_u64_u32 v[2:3], s[10:11], v0, s55, v[10:11]
	v_add_u32_e32 v0, s12, v0
	v_mad_i64_i32 v[14:15], s[10:11], v0, s35, v[12:13]
	v_add_u32_e32 v0, 0x700, v189
	ds_read_b128 v[2:5], v2
	v_ashrrev_i32_e32 v0, 5, v0
	v_mad_u64_u32 v[6:7], s[10:11], v0, s55, v[10:11]
	ds_read_b128 v[6:9], v6
	v_add_u32_e32 v0, s12, v0
	s_waitcnt lgkmcnt(1)
	global_store_dwordx4 v[14:15], v[2:5], off nt
	s_nop 1
	v_mad_i64_i32 v[2:3], s[10:11], v0, s35, v[12:13]
	v_add_u32_e32 v0, 0x800, v189
	v_ashrrev_i32_e32 v0, 5, v0
	s_waitcnt lgkmcnt(0)
	global_store_dwordx4 v[2:3], v[6:9], off nt
	v_mad_u64_u32 v[2:3], s[10:11], v0, s55, v[10:11]
	v_add_u32_e32 v0, s12, v0
	v_mad_i64_i32 v[14:15], s[10:11], v0, s35, v[12:13]
	v_add_u32_e32 v0, 0x900, v189
	ds_read_b128 v[2:5], v2
	v_ashrrev_i32_e32 v0, 5, v0
	v_mad_u64_u32 v[6:7], s[10:11], v0, s55, v[10:11]
	ds_read_b128 v[6:9], v6
	v_add_u32_e32 v0, s12, v0
	s_waitcnt lgkmcnt(1)
	global_store_dwordx4 v[14:15], v[2:5], off nt
	s_nop 1
	v_mad_i64_i32 v[2:3], s[10:11], v0, s35, v[12:13]
	v_add_u32_e32 v0, 0xa00, v189
	v_ashrrev_i32_e32 v0, 5, v0
	s_waitcnt lgkmcnt(0)
	global_store_dwordx4 v[2:3], v[6:9], off nt
	v_mad_u64_u32 v[2:3], s[10:11], v0, s55, v[10:11]
	v_add_u32_e32 v0, s12, v0
	v_mad_i64_i32 v[14:15], s[10:11], v0, s35, v[12:13]
	v_add_u32_e32 v0, 0xb00, v189
	ds_read_b128 v[2:5], v2
	v_ashrrev_i32_e32 v0, 5, v0
	v_mad_u64_u32 v[6:7], s[10:11], v0, s55, v[10:11]
	ds_read_b128 v[6:9], v6
	v_add_u32_e32 v0, s12, v0
	s_waitcnt lgkmcnt(1)
	global_store_dwordx4 v[14:15], v[2:5], off nt
	s_nop 1
	v_mad_i64_i32 v[2:3], s[10:11], v0, s35, v[12:13]
	v_add_u32_e32 v0, 0xc00, v189
	v_ashrrev_i32_e32 v0, 5, v0
	s_waitcnt lgkmcnt(0)
	global_store_dwordx4 v[2:3], v[6:9], off nt
	v_mad_u64_u32 v[2:3], s[10:11], v0, s55, v[10:11]
	v_add_u32_e32 v0, s12, v0
	v_mad_i64_i32 v[14:15], s[10:11], v0, s35, v[12:13]
	v_add_u32_e32 v0, 0xd00, v189
	ds_read_b128 v[2:5], v2
	v_ashrrev_i32_e32 v0, 5, v0
	v_mad_u64_u32 v[6:7], s[10:11], v0, s55, v[10:11]
	ds_read_b128 v[6:9], v6
	v_add_u32_e32 v0, s12, v0
	s_waitcnt lgkmcnt(1)
	global_store_dwordx4 v[14:15], v[2:5], off nt
	s_nop 1
	v_mad_i64_i32 v[2:3], s[10:11], v0, s35, v[12:13]
	v_add_u32_e32 v0, 0xe00, v189
	v_ashrrev_i32_e32 v0, 5, v0
	s_waitcnt lgkmcnt(0)
	global_store_dwordx4 v[2:3], v[6:9], off nt
	v_mad_u64_u32 v[2:3], s[10:11], v0, s55, v[10:11]
	ds_read_b128 v[2:5], v2
	v_add_u32_e32 v0, s12, v0
	v_mad_i64_i32 v[14:15], s[10:11], v0, s35, v[12:13]
	v_add_u32_e32 v0, 0xf00, v189
	v_ashrrev_i32_e32 v0, 5, v0
	v_mad_u64_u32 v[6:7], s[10:11], v0, s55, v[10:11]
	ds_read_b128 v[6:9], v6
	v_add_u32_e32 v0, s12, v0
	s_waitcnt lgkmcnt(1)
	global_store_dwordx4 v[14:15], v[2:5], off nt
	s_nop 1
	v_mad_i64_i32 v[2:3], s[10:11], v0, s35, v[12:13]
	v_readlane_b32 s10, v252, 12
	s_add_i32 s22, s22, s10
	v_readlane_b32 s10, v252, 38
	s_cmp_ge_i32 s22, s10
	s_waitcnt lgkmcnt(0)
	global_store_dwordx4 v[2:3], v[6:9], off nt
	s_barrier
	s_cbranch_scc0 .LBB0_230

; #define LAS __attribute__((address_space(3)))
;     ...
;   const int lane = tid & 63, wid = __builtin_amdgcn_readfirstlane(tid >> 6), wr = wid >> 1, wc = wid & 1;
;   const int m0 = mt * 128, n0 = nt * 256;
;   const int r = lane & 31, h = lane >> 5, key = (r >> 2) & 3;
;   constexpr int STG = 24576;
;   const int rowl = lane >> 2, cch = (lane & 3) ^ ((lane >> 4) & 3);
;   const unsigned voffA = (unsigned)(rowl * lda * 2 + cch * 16), voffB = (unsigned)(rowl * K * 2 + cch * 16);
;   const char* Abase = (const char*)(A + (size_t)m0 * lda) + (size_t)(wid * 2) * 32 * lda;
;   const char* Bbase = (const char*)(Bt + (size_t)n0 * K) + (size_t)(wid * 4) * 32 * K;
;   const size_t ablk = (size_t)32 * lda, bblk = (size_t)32 * K;
;   LAS char* lds = (LAS char*)smem;
;   LAS char* ldsA = lds + (wid * 2) * 1024;
;   LAS char* ldsB = lds + 8192 + (wid * 4) * 1024;
;     ...
;   const int x0 = ((0 + h) ^ key) * 16, x1 = ((2 + h) ^ key) * 16;
;   const int a_rd = (wr * 64 + r) * 64, b_rd = 8192 + (wc * 128 + r) * 64;
;   f32x16 acc[2][4];
; #pragma unroll
;   for (int i = 0; i < 2; ++i)
; #pragma unroll
;     for (int j = 0; j < 4; ++j)
; #pragma unroll
;       for (int e = 0; e < 16; ++e) acc[i][j][e] = 0.f;
;   const int nk = K >> 5;
;   DMA_STEP_(0, 0);
;   DMA_STEP_(1, STG);
;   asm volatile("s_waitcnt vmcnt(6)" ::: "memory");
;   __builtin_amdgcn_s_barrier();
;   asm volatile("" ::: "memory");
;   int s0 = 0, s2 = 2 * STG;
;   for (int kt = 0; kt < nk; ++kt) {
;     const int kn = (kt + 2 < nk) ? (kt + 2) : (nk - 1);
;     const LAS char* cur = lds + s0;
;     bf16x8 af[2][2], bfr[2][4];
; #pragma unroll
;     for (int kk = 0; kk < 2; ++kk) {
;       const int xo = kk ? x1 : x0;
;       af[kk][0] = *(const LAS bf16x8*)(cur + a_rd + xo);
;       bfr[kk][0] = *(const LAS bf16x8*)(cur + b_rd + xo);
.LBB0_243:
	s_ashr_i32 s10, s29, 31
	s_lshr_b32 s10, s10, 27
	s_add_i32 s10, s29, s10
	s_ashr_i32 s10, s10, 5
	v_readlane_b32 s11, v252, 18
	s_lshl_b32 s11, s10, s11
	v_readlane_b32 s16, v252, 41
	s_add_i32 s11, s11, s16
	s_lshl_b32 s16, s29, 7
	v_mov_b32_e32 v189, v188
	s_lshl_b32 s11, s11, 10
	s_and_b32 s16, s16, 0x380
	s_or_b32 s40, s11, s16
	v_readfirstlane_b32 s42, v189
	s_lshl_b32 s10, s10, 10
	s_lshl_b32 s11, s29, 5
	s_ashr_i32 s44, s42, 6
	s_sub_i32 s10, s11, s10
	s_and_b32 s16, s10, 0xffffff00
	s_lshl_b32 s10, s44, 1
	s_mul_hi_i32 s45, s10, 0x16000
	s_lshl_b32 s10, s44, 2
	s_mov_b32 s47, 0
	s_lshl_b32 s10, s44, 12
	s_add_i32 s43, s10, 16
	s_ashr_i32 s10, s42, 1
	v_and_b32_e32 v0, 31, v189
	s_andn2_b32 s10, s10, 63
	v_or_b32_e32 v197, s10, v0
	s_lshl_b32 s10, s44, 7
	s_ashr_i32 s17, s16, 31
	s_add_i32 s56, s43, 0x2000
	s_and_b32 s42, s10, 0x80
	s_mul_i32 s57, s40, 0x1600
	s_mul_hi_i32 s10, s40, 0x1600
	s_add_u32 s57, s23, s57
	s_mul_i32 s11, s44, 0x2c000
	s_addc_u32 s58, s28, s10
	s_add_u32 s10, s57, s11
	s_addc_u32 s11, s58, s45
	s_mul_i32 s57, s16, 64
	s_mov_b32 s45, 0
	s_add_u32 s57, s19, s57
	s_mul_i32 s46, s44, 0x1000
	s_addc_u32 s45, s20, s45
	s_add_u32 s46, s57, s46
	v_bfe_u32 v2, v189, 2, 4
	v_lshlrev_b32_e32 v3, 4, v189
	s_addc_u32 s47, s45, s47
	s_lshl_b32 s44, s44, 11
	v_xor_b32_e32 v3, v3, v189
	v_mul_u32_u24_e32 v2, 0x1600, v2
	s_sub_i32 s44, s43, s44
	v_or_b32_e32 v5, s42, v0
	v_and_or_b32 v0, v3, 48, v2
	v_bfe_u32 v10, v189, 2, 4
	v_lshlrev_b32_e32 v10, 6, v10
	v_and_or_b32 v10, v3, 48, v10
	v_mov_b32_e32 v11, 0
	s_mov_b32 m0, s44
	v_lshl_add_u64 v[192:193], s[10:11], 0, v[0:1]
	global_load_lds_dwordx4 v0, s[10:11]
	s_mov_b64 s[10:11], 0x16000
	v_lshl_add_u64 v[2:3], v[192:193], 0, s[10:11]
	s_add_i32 m0, s44, 0x400
	v_lshl_add_u64 v[194:195], s[46:47], 0, v[10:11]
	global_load_lds_dwordx4 v[2:3], off
	s_mov_b32 m0, s56
	s_nop 0
	global_load_lds_dwordx4 v[194:195], off
	global_load_lds_dwordx4 v[194:195], off offset:1024
	global_load_lds_dwordx4 v[194:195], off offset:2048
	global_load_lds_dwordx4 v[194:195], off offset:3072
	s_mov_b64 s[10:11], 0x2c000
	s_mov_b64 s[10:11], 0x42000
	s_mov_b64 s[10:11], 0x16040
	s_add_i32 m0, s44, 0x6000
	v_lshl_add_u64 v[2:3], v[192:193], 0, 64
	global_load_lds_dwordx4 v[2:3], off
	v_lshl_add_u64 v[2:3], v[192:193], 0, s[10:11]
	s_add_i32 m0, s44, 0x6400
	v_bfe_u32 v196, v189, 5, 1
	global_load_lds_dwordx4 v[2:3], off
	s_add_i32 m0, s43, 0x8000
	s_mov_b32 s100, 0x10000
	v_lshl_add_u64 v[2:3], v[194:195], 0, s[100:101]
	global_load_lds_dwordx4 v[2:3], off
	global_load_lds_dwordx4 v[2:3], off offset:1024
	global_load_lds_dwordx4 v[2:3], off offset:2048
	global_load_lds_dwordx4 v[2:3], off offset:3072
	s_mov_b64 s[10:11], 0x2c040
	s_mov_b64 s[10:11], 0x42040
	v_lshlrev_b32_e32 v218, 6, v5
	v_bfe_u32 v5, v189, 2, 2
	v_lshrrev_b32_e32 v4, 2, v189
	s_lshl_b32 s100, s100, 1
	v_lshl_add_u64 v[194:195], v[194:195], 0, s[100:101]
	s_waitcnt vmcnt(6)
	s_barrier
	v_bitop3_b32 v2, v196, v5, 2 bitop3:0x36
	v_bitop3_b32 v0, v196, v4, 3 bitop3:0x78
	v_lshlrev_b32_e32 v220, 4, v2
	v_mov_b32_e32 v2, 0
	s_mov_b32 s41, 1
	v_lshlrev_b32_e32 v219, 6, v197
	v_lshlrev_b32_e32 v0, 4, v0
	s_mov_b32 s46, 0
	s_mov_b32 s45, 0xc000
	v_mov_b32_e32 v3, v2
	v_mov_b32_e32 v4, v2
	v_mov_b32_e32 v5, v2
	v_mov_b32_e32 v6, v2
	v_mov_b32_e32 v7, v2
	v_mov_b32_e32 v8, v2
	v_mov_b32_e32 v9, v2
	v_mov_b32_e32 v10, v2
	v_mov_b32_e32 v11, v2
	v_mov_b32_e32 v12, v2
	v_mov_b32_e32 v13, v2
	v_mov_b32_e32 v14, v2
	v_mov_b32_e32 v15, v2
	v_mov_b32_e32 v16, v2
	v_mov_b32_e32 v17, v2
	v_mov_b32_e32 v18, v2
	v_mov_b32_e32 v19, v2
	v_mov_b32_e32 v20, v2
	v_mov_b32_e32 v21, v2
	v_mov_b32_e32 v22, v2
	v_mov_b32_e32 v23, v2
	v_mov_b32_e32 v24, v2
	v_mov_b32_e32 v25, v2
	v_mov_b32_e32 v26, v2
	v_mov_b32_e32 v27, v2
	v_mov_b32_e32 v28, v2
	v_mov_b32_e32 v29, v2
	v_mov_b32_e32 v30, v2
	v_mov_b32_e32 v31, v2
	v_mov_b32_e32 v32, v2
	v_mov_b32_e32 v33, v2
	v_mov_b32_e32 v50, v2
	v_mov_b32_e32 v51, v2
	v_mov_b32_e32 v52, v2
	v_mov_b32_e32 v53, v2
	v_mov_b32_e32 v54, v2
	v_mov_b32_e32 v55, v2
	v_mov_b32_e32 v56, v2
	v_mov_b32_e32 v57, v2
	v_mov_b32_e32 v58, v2
	v_mov_b32_e32 v59, v2
	v_mov_b32_e32 v60, v2
	v_mov_b32_e32 v61, v2
	v_mov_b32_e32 v62, v2
	v_mov_b32_e32 v63, v2
	v_mov_b32_e32 v64, v2
	v_mov_b32_e32 v65, v2
	v_mov_b32_e32 v82, v2
	v_mov_b32_e32 v83, v2
	v_mov_b32_e32 v84, v2
	v_mov_b32_e32 v85, v2
	v_mov_b32_e32 v86, v2
	v_mov_b32_e32 v87, v2
	v_mov_b32_e32 v88, v2
	v_mov_b32_e32 v89, v2
	v_mov_b32_e32 v90, v2
	v_mov_b32_e32 v91, v2
	v_mov_b32_e32 v92, v2
	v_mov_b32_e32 v93, v2
	v_mov_b32_e32 v94, v2
	v_mov_b32_e32 v95, v2
	v_mov_b32_e32 v96, v2
	v_mov_b32_e32 v97, v2
	v_mov_b32_e32 v34, v2
	v_mov_b32_e32 v35, v2
	v_mov_b32_e32 v36, v2
	v_mov_b32_e32 v37, v2
	v_mov_b32_e32 v38, v2
	v_mov_b32_e32 v39, v2
	v_mov_b32_e32 v40, v2
	v_mov_b32_e32 v41, v2
	v_mov_b32_e32 v42, v2
	v_mov_b32_e32 v43, v2
	v_mov_b32_e32 v44, v2
	v_mov_b32_e32 v45, v2
	v_mov_b32_e32 v46, v2
	v_mov_b32_e32 v47, v2
	v_mov_b32_e32 v48, v2
	v_mov_b32_e32 v49, v2
	v_mov_b32_e32 v66, v2
	v_mov_b32_e32 v67, v2
	v_mov_b32_e32 v68, v2
	v_mov_b32_e32 v69, v2
	v_mov_b32_e32 v70, v2
	v_mov_b32_e32 v71, v2
	v_mov_b32_e32 v72, v2
	v_mov_b32_e32 v73, v2
	v_mov_b32_e32 v74, v2
	v_mov_b32_e32 v75, v2
	v_mov_b32_e32 v76, v2
	v_mov_b32_e32 v77, v2
	v_mov_b32_e32 v78, v2
	v_mov_b32_e32 v79, v2
	v_mov_b32_e32 v80, v2
	v_mov_b32_e32 v81, v2
	v_mov_b32_e32 v98, v2
	v_mov_b32_e32 v99, v2
	v_mov_b32_e32 v100, v2
	v_mov_b32_e32 v101, v2
	v_mov_b32_e32 v102, v2
	v_mov_b32_e32 v103, v2
	v_mov_b32_e32 v104, v2
	v_mov_b32_e32 v105, v2
	v_mov_b32_e32 v106, v2
	v_mov_b32_e32 v107, v2
	v_mov_b32_e32 v108, v2
	v_mov_b32_e32 v109, v2
	v_mov_b32_e32 v110, v2
	v_mov_b32_e32 v111, v2
	v_mov_b32_e32 v112, v2
	v_mov_b32_e32 v113, v2
	v_mov_b32_e32 v114, v2
	v_mov_b32_e32 v115, v2
	v_mov_b32_e32 v116, v2
	v_mov_b32_e32 v117, v2
	v_mov_b32_e32 v118, v2
	v_mov_b32_e32 v119, v2
	v_mov_b32_e32 v120, v2
	v_mov_b32_e32 v121, v2
	v_mov_b32_e32 v122, v2
	v_mov_b32_e32 v123, v2
	v_mov_b32_e32 v124, v2
	v_mov_b32_e32 v125, v2
	v_mov_b32_e32 v126, v2
	v_mov_b32_e32 v127, v2
	v_mov_b32_e32 v128, v2
	v_mov_b32_e32 v129, v2
	v_add_u32_e32 v226, v219, v0
	v_add_u32_e32 v227, v218, v0
	v_add_u32_e32 v228, v219, v220
	v_add_u32_e32 v229, v218, v220
	v_add_u32_e32 v162, 16, v226
	v_add_u32_e32 v170, 16, v227
	ds_read_b128 v[158:161], v162
	ds_read_b128 v[182:185], v170 offset:8192
	ds_read_b128 v[178:181], v170 offset:10240
	ds_read_b128 v[162:165], v162 offset:2048
	ds_read_b128 v[174:177], v170 offset:12288
	ds_read_b128 v[170:173], v170 offset:14336
	s_setprio 1
; #define LAS __attribute__((address_space(3)))
; DI f32x16 mfma32(bf16x8 a, bf16x8 b, f32x16 c) { return __builtin_amdgcn_mfma_f32_32x32x16_bf16(a, b, c, 0, 0, 0); }
;     ...
;   for (int kt = 0; kt < nk; ++kt) {
;     const int kn = (kt + 2 < nk) ? (kt + 2) : (nk - 1);
;     const LAS char* cur = lds + s0;
;     bf16x8 af[2][2], bfr[2][4];
; #pragma unroll
;     for (int kk = 0; kk < 2; ++kk) {
;       const int xo = kk ? x1 : x0;
;       af[kk][0] = *(const LAS bf16x8*)(cur + a_rd + xo);
;       bfr[kk][0] = *(const LAS bf16x8*)(cur + b_rd + xo);
;       bfr[kk][1] = *(const LAS bf16x8*)(cur + b_rd + 2048 + xo);
;       af[kk][1] = *(const LAS bf16x8*)(cur + a_rd + 2048 + xo);
;       bfr[kk][2] = *(const LAS bf16x8*)(cur + b_rd + 4096 + xo);
;       bfr[kk][3] = *(const LAS bf16x8*)(cur + b_rd + 6144 + xo);
;     }
;     DMA_STEP_(kn, s2);
; #pragma unroll
;     for (int kk = 0; kk < 2; ++kk) {
;       acc[0][0] = mfma32(bfr[kk][0], af[kk][0], acc[0][0]); acc[0][1] = mfma32(bfr[kk][1], af[kk][0], acc[0][1]);
;       acc[1][0] = mfma32(bfr[kk][0], af[kk][1], acc[1][0]); acc[1][1] = mfma32(bfr[kk][1], af[kk][1], acc[1][1]);
;       acc[0][2] = mfma32(bfr[kk][2], af[kk][0], acc[0][2]); acc[0][3] = mfma32(bfr[kk][3], af[kk][0], acc[0][3]);
;       acc[1][2] = mfma32(bfr[kk][2], af[kk][1], acc[1][2]); acc[1][3] = mfma32(bfr[kk][3], af[kk][1], acc[1][3]);
;     }
;     __builtin_amdgcn_sched_group_barrier(0x100, 12, 0);
;     __builtin_amdgcn_sched_group_barrier(0x010, 6, 0);
;     __builtin_amdgcn_sched_group_barrier(0x008, 16, 0);
;     asm volatile("s_waitcnt vmcnt(6) lgkmcnt(0)" ::: "memory");
;     __builtin_amdgcn_s_barrier();
;     asm volatile("" ::: "memory");
;     s0 = (s0 == 2 * STG) ? 0 : s0 + STG;
;     s2 = (s2 == 2 * STG) ? 0 : s2 + STG;
;   }
.LBB0_244:
	s_add_i32 s11, s46, 16
	s_add_i32 s10, s41, -1
	v_add_u32_e32 v142, s11, v228
	v_add_u32_e32 v150, s11, v229
	s_min_u32 s10, s10, 0x55
	s_lshl_b32 s70, s10, 6
	ds_read_b128 v[138:141], v142
	ds_read_b128 v[166:169], v150 offset:8192
	ds_read_b128 v[154:157], v150 offset:10240
	ds_read_b128 v[142:145], v142 offset:2048
	ds_read_b128 v[146:149], v150 offset:12288
	ds_read_b128 v[150:153], v150 offset:14336
	v_lshl_add_u64 v[222:223], v[192:193], 0, s[70:71]
	s_add_i32 s10, s44, s45
	v_lshl_add_u64 v[224:225], v[222:223], 0, s[24:25]
	s_mov_b32 m0, s10
	v_lshl_add_u64 v[222:223], v[222:223], 0, s[98:99]
	s_mul_i32 s100, s70, 0x400
	s_waitcnt lgkmcnt(6)
	v_mfma_f32_32x32x16_bf16 v[114:129], v[182:185], v[158:161], v[114:129]
	global_load_lds_dwordx4 v[224:225], off
	s_add_i32 m0, s10, 0x400
	v_mfma_f32_32x32x16_bf16 v[98:113], v[178:181], v[158:161], v[98:113]
	global_load_lds_dwordx4 v[222:223], off
	v_lshl_add_u64 v[224:225], v[194:195], 0, s[100:101]
	s_add_i32 s10, s43, s45
	s_add_i32 m0, s10, 0x2000
	v_mfma_f32_32x32x16_bf16 v[66:81], v[182:185], v[162:165], v[66:81]
	global_load_lds_dwordx4 v[224:225], off
	v_mfma_f32_32x32x16_bf16 v[34:49], v[178:181], v[162:165], v[34:49]
	global_load_lds_dwordx4 v[224:225], off offset:1024
	v_mfma_f32_32x32x16_bf16 v[82:97], v[174:177], v[158:161], v[82:97]
	global_load_lds_dwordx4 v[224:225], off offset:2048
	v_mfma_f32_32x32x16_bf16 v[50:65], v[170:173], v[158:161], v[50:65]
	global_load_lds_dwordx4 v[224:225], off offset:3072
	v_mfma_f32_32x32x16_bf16 v[18:33], v[174:177], v[162:165], v[18:33]
	s_add_i32 s10, s46, 0x6000
	s_cmpk_lg_u32 s46, 0xc000
	s_cselect_b32 s46, s10, 0
	s_add_i32 s10, s45, 0x6000
	s_cmpk_lg_u32 s45, 0xc000
	s_cselect_b32 s45, s10, 0
	v_mfma_f32_32x32x16_bf16 v[2:17], v[170:173], v[162:165], v[2:17]
	s_add_i32 s11, s46, 16
	s_waitcnt vmcnt(6) lgkmcnt(0)
	s_barrier
	v_add_u32_e32 v162, s11, v226
	v_add_u32_e32 v170, s11, v227
	ds_read_b128 v[158:161], v162
	ds_read_b128 v[182:185], v170 offset:8192
	ds_read_b128 v[178:181], v170 offset:10240
	ds_read_b128 v[162:165], v162 offset:2048
	ds_read_b128 v[174:177], v170 offset:12288
	ds_read_b128 v[170:173], v170 offset:14336
	v_mfma_f32_32x32x16_bf16 v[114:129], v[166:169], v[138:141], v[114:129]
	v_mfma_f32_32x32x16_bf16 v[98:113], v[154:157], v[138:141], v[98:113]
	v_mfma_f32_32x32x16_bf16 v[66:81], v[166:169], v[142:145], v[66:81]
	v_mfma_f32_32x32x16_bf16 v[34:49], v[154:157], v[142:145], v[34:49]
	v_mfma_f32_32x32x16_bf16 v[82:97], v[146:149], v[138:141], v[82:97]
	v_mfma_f32_32x32x16_bf16 v[50:65], v[150:153], v[138:141], v[50:65]
	v_mfma_f32_32x32x16_bf16 v[18:33], v[146:149], v[142:145], v[18:33]
	v_mfma_f32_32x32x16_bf16 v[2:17], v[150:153], v[142:145], v[2:17]
	s_add_i32 s11, s46, 16
	s_mov_b32 s10, s41
	v_add_u32_e32 v142, s11, v228
	v_add_u32_e32 v150, s11, v229
	s_min_u32 s10, s10, 0x55
	s_lshl_b32 s70, s10, 6
	ds_read_b128 v[138:141], v142
	ds_read_b128 v[166:169], v150 offset:8192
	ds_read_b128 v[154:157], v150 offset:10240
	ds_read_b128 v[142:145], v142 offset:2048
	ds_read_b128 v[146:149], v150 offset:12288
	ds_read_b128 v[150:153], v150 offset:14336
	v_lshl_add_u64 v[222:223], v[192:193], 0, s[70:71]
	s_add_i32 s10, s44, s45
	v_lshl_add_u64 v[224:225], v[222:223], 0, s[24:25]
	s_mov_b32 m0, s10
	v_lshl_add_u64 v[222:223], v[222:223], 0, s[98:99]
	s_mul_i32 s100, s70, 0x400
	s_waitcnt lgkmcnt(6)
	v_mfma_f32_32x32x16_bf16 v[114:129], v[182:185], v[158:161], v[114:129]
	global_load_lds_dwordx4 v[224:225], off
	s_add_i32 m0, s10, 0x400
	v_mfma_f32_32x32x16_bf16 v[98:113], v[178:181], v[158:161], v[98:113]
	global_load_lds_dwordx4 v[222:223], off
	v_lshl_add_u64 v[224:225], v[194:195], 0, s[100:101]
	s_add_i32 s10, s43, s45
	s_add_i32 m0, s10, 0x2000
	v_mfma_f32_32x32x16_bf16 v[66:81], v[182:185], v[162:165], v[66:81]
	global_load_lds_dwordx4 v[224:225], off
	v_mfma_f32_32x32x16_bf16 v[34:49], v[178:181], v[162:165], v[34:49]
	global_load_lds_dwordx4 v[224:225], off offset:1024
	v_mfma_f32_32x32x16_bf16 v[82:97], v[174:177], v[158:161], v[82:97]
	global_load_lds_dwordx4 v[224:225], off offset:2048
	v_mfma_f32_32x32x16_bf16 v[50:65], v[170:173], v[158:161], v[50:65]
	global_load_lds_dwordx4 v[224:225], off offset:3072
	v_mfma_f32_32x32x16_bf16 v[18:33], v[174:177], v[162:165], v[18:33]
	s_add_i32 s10, s46, 0x6000
	s_cmpk_lg_u32 s46, 0xc000
	s_cselect_b32 s46, s10, 0
	s_add_i32 s10, s45, 0x6000
	s_cmpk_lg_u32 s45, 0xc000
	s_cselect_b32 s45, s10, 0
	v_mfma_f32_32x32x16_bf16 v[2:17], v[170:173], v[162:165], v[2:17]
	s_add_i32 s11, s46, 16
	s_waitcnt vmcnt(6) lgkmcnt(0)
	s_barrier
	v_add_u32_e32 v162, s11, v226
	v_add_u32_e32 v170, s11, v227
	ds_read_b128 v[158:161], v162
	ds_read_b128 v[182:185], v170 offset:8192
	ds_read_b128 v[178:181], v170 offset:10240
	ds_read_b128 v[162:165], v162 offset:2048
	ds_read_b128 v[174:177], v170 offset:12288
	ds_read_b128 v[170:173], v170 offset:14336
	v_mfma_f32_32x32x16_bf16 v[114:129], v[166:169], v[138:141], v[114:129]
	v_mfma_f32_32x32x16_bf16 v[98:113], v[154:157], v[138:141], v[98:113]
	v_mfma_f32_32x32x16_bf16 v[66:81], v[166:169], v[142:145], v[66:81]
	v_mfma_f32_32x32x16_bf16 v[34:49], v[154:157], v[142:145], v[34:49]
	v_mfma_f32_32x32x16_bf16 v[82:97], v[146:149], v[138:141], v[82:97]
	v_mfma_f32_32x32x16_bf16 v[50:65], v[150:153], v[138:141], v[50:65]
	v_mfma_f32_32x32x16_bf16 v[18:33], v[146:149], v[142:145], v[18:33]
	v_mfma_f32_32x32x16_bf16 v[2:17], v[150:153], v[142:145], v[2:17]
	s_add_i32 s41, s41, 2
	s_cmpk_lg_i32 s41, 87
	s_cbranch_scc1 .LBB0_244
; #define LAS __attribute__((address_space(3)))
; DI unsigned pk2(float a, float b) { f32x2 v = {a, b}; bf2_t r = __builtin_convertvector(v, bf2_t); return __builtin_bit_cast(unsigned, r); }
;     ...
;   for (int kt = 0; kt < nk; ++kt) {
;     const int kn = (kt + 2 < nk) ? (kt + 2) : (nk - 1);
;     const LAS char* cur = lds + s0;
;     bf16x8 af[2][2], bfr[2][4];
; #pragma unroll
;     for (int kk = 0; kk < 2; ++kk) {
;       const int xo = kk ? x1 : x0;
;       af[kk][0] = *(const LAS bf16x8*)(cur + a_rd + xo);
;       bfr[kk][0] = *(const LAS bf16x8*)(cur + b_rd + xo);
;       bfr[kk][1] = *(const LAS bf16x8*)(cur + b_rd + 2048 + xo);
;       af[kk][1] = *(const LAS bf16x8*)(cur + a_rd + 2048 + xo);
;       bfr[kk][2] = *(const LAS bf16x8*)(cur + b_rd + 4096 + xo);
;       bfr[kk][3] = *(const LAS bf16x8*)(cur + b_rd + 6144 + xo);
;     }
;     DMA_STEP_(kn, s2);
; #pragma unroll
;     for (int kk = 0; kk < 2; ++kk) {
;       acc[0][0] = mfma32(bfr[kk][0], af[kk][0], acc[0][0]); acc[0][1] = mfma32(bfr[kk][1], af[kk][0], acc[0][1]);
;       acc[1][0] = mfma32(bfr[kk][0], af[kk][1], acc[1][0]); acc[1][1] = mfma32(bfr[kk][1], af[kk][1], acc[1][1]);
;       acc[0][2] = mfma32(bfr[kk][2], af[kk][0], acc[0][2]); acc[0][3] = mfma32(bfr[kk][3], af[kk][0], acc[0][3]);
;       acc[1][2] = mfma32(bfr[kk][2], af[kk][1], acc[1][2]); acc[1][3] = mfma32(bfr[kk][3], af[kk][1], acc[1][3]);
;     }
;     __builtin_amdgcn_sched_group_barrier(0x100, 12, 0);
;     __builtin_amdgcn_sched_group_barrier(0x010, 6, 0);
;     __builtin_amdgcn_sched_group_barrier(0x008, 16, 0);
;     asm volatile("s_waitcnt vmcnt(6) lgkmcnt(0)" ::: "memory");
;     __builtin_amdgcn_s_barrier();
;     asm volatile("" ::: "memory");
;     s0 = (s0 == 2 * STG) ? 0 : s0 + STG;
;     s2 = (s2 == 2 * STG) ? 0 : s2 + STG;
;   }
;   asm volatile("s_waitcnt vmcnt(0)" ::: "memory");
;   __builtin_amdgcn_s_barrier();
;   asm volatile("" ::: "memory");
;     ...
;   {
;     const int h = lane >> 5, cl = lane & 31;
; #pragma unroll
;     for (int i = 0; i < 2; ++i)
; #pragma unroll
;       for (int j = 0; j < 4; ++j)
; #pragma unroll
;         for (int g = 0; g < 4; ++g) {
;           u32x2 w; w.x = pk2(acc[i][j][4 * g], acc[i][j][4 * g + 1]); w.y = pk2(acc[i][j][4 * g + 2], acc[i][j][4 * g + 3]);
;           *(u32x2*)(smem + (wr * 64 + i * 32 + cl) * 528 + (wc * 128 + j * 32 + 8 * g + 4 * h) * 2) = w;
;         }
	s_add_i32 s11, s46, 16
	v_add_u32_e32 v142, s11, v228
	v_add_u32_e32 v150, s11, v229
	ds_read_b128 v[138:141], v142
	ds_read_b128 v[166:169], v150 offset:8192
	ds_read_b128 v[154:157], v150 offset:10240
	ds_read_b128 v[142:145], v142 offset:2048
	ds_read_b128 v[146:149], v150 offset:12288
	ds_read_b128 v[150:153], v150 offset:14336
	s_waitcnt lgkmcnt(6)
	v_mfma_f32_32x32x16_bf16 v[114:129], v[182:185], v[158:161], v[114:129]
	v_mfma_f32_32x32x16_bf16 v[98:113], v[178:181], v[158:161], v[98:113]
	v_mfma_f32_32x32x16_bf16 v[66:81], v[182:185], v[162:165], v[66:81]
	v_mfma_f32_32x32x16_bf16 v[34:49], v[178:181], v[162:165], v[34:49]
	v_mfma_f32_32x32x16_bf16 v[82:97], v[174:177], v[158:161], v[82:97]
	v_mfma_f32_32x32x16_bf16 v[50:65], v[170:173], v[158:161], v[50:65]
	v_mfma_f32_32x32x16_bf16 v[18:33], v[174:177], v[162:165], v[18:33]
	s_add_i32 s10, s46, 0x6000
	s_cmpk_lg_u32 s46, 0xc000
	s_cselect_b32 s46, s10, 0
	v_mfma_f32_32x32x16_bf16 v[2:17], v[170:173], v[162:165], v[2:17]
	s_add_i32 s11, s46, 16
	s_waitcnt vmcnt(0) lgkmcnt(0)
	s_barrier
	v_add_u32_e32 v162, s11, v226
	v_add_u32_e32 v170, s11, v227
	ds_read_b128 v[158:161], v162
	ds_read_b128 v[182:185], v170 offset:8192
	ds_read_b128 v[178:181], v170 offset:10240
	ds_read_b128 v[162:165], v162 offset:2048
	ds_read_b128 v[174:177], v170 offset:12288
	ds_read_b128 v[170:173], v170 offset:14336
	v_mfma_f32_32x32x16_bf16 v[114:129], v[166:169], v[138:141], v[114:129]
	v_mfma_f32_32x32x16_bf16 v[98:113], v[154:157], v[138:141], v[98:113]
	v_mfma_f32_32x32x16_bf16 v[66:81], v[166:169], v[142:145], v[66:81]
	v_mfma_f32_32x32x16_bf16 v[34:49], v[154:157], v[142:145], v[34:49]
	v_mfma_f32_32x32x16_bf16 v[82:97], v[146:149], v[138:141], v[82:97]
	v_mfma_f32_32x32x16_bf16 v[50:65], v[150:153], v[138:141], v[50:65]
	v_mfma_f32_32x32x16_bf16 v[18:33], v[146:149], v[142:145], v[18:33]
	v_mfma_f32_32x32x16_bf16 v[2:17], v[150:153], v[142:145], v[2:17]
	s_add_i32 s11, s46, 16
	v_add_u32_e32 v142, s11, v228
	v_add_u32_e32 v150, s11, v229
	ds_read_b128 v[138:141], v142
	ds_read_b128 v[166:169], v150 offset:8192
	ds_read_b128 v[154:157], v150 offset:10240
	ds_read_b128 v[142:145], v142 offset:2048
	ds_read_b128 v[146:149], v150 offset:12288
	ds_read_b128 v[150:153], v150 offset:14336
	s_waitcnt lgkmcnt(6)
	v_mfma_f32_32x32x16_bf16 v[114:129], v[182:185], v[158:161], v[114:129]
	v_mfma_f32_32x32x16_bf16 v[98:113], v[178:181], v[158:161], v[98:113]
	v_mfma_f32_32x32x16_bf16 v[66:81], v[182:185], v[162:165], v[66:81]
	v_mfma_f32_32x32x16_bf16 v[34:49], v[178:181], v[162:165], v[34:49]
	v_mfma_f32_32x32x16_bf16 v[82:97], v[174:177], v[158:161], v[82:97]
	v_mfma_f32_32x32x16_bf16 v[50:65], v[170:173], v[158:161], v[50:65]
	v_mfma_f32_32x32x16_bf16 v[18:33], v[174:177], v[162:165], v[18:33]
	v_mfma_f32_32x32x16_bf16 v[2:17], v[170:173], v[162:165], v[2:17]
	s_waitcnt lgkmcnt(0)
	v_mfma_f32_32x32x16_bf16 v[114:129], v[166:169], v[138:141], v[114:129]
	v_mfma_f32_32x32x16_bf16 v[98:113], v[154:157], v[138:141], v[98:113]
	v_mfma_f32_32x32x16_bf16 v[66:81], v[166:169], v[142:145], v[66:81]
	v_mfma_f32_32x32x16_bf16 v[34:49], v[154:157], v[142:145], v[34:49]
	v_mfma_f32_32x32x16_bf16 v[82:97], v[146:149], v[138:141], v[82:97]
	v_mfma_f32_32x32x16_bf16 v[50:65], v[150:153], v[138:141], v[50:65]
	v_mfma_f32_32x32x16_bf16 v[18:33], v[146:149], v[142:145], v[18:33]
	v_mfma_f32_32x32x16_bf16 v[2:17], v[150:153], v[142:145], v[2:17]
	s_waitcnt lgkmcnt(0)
	s_setprio 0
	v_mul_lo_u32 v0, v197, s55
	v_add_u32_e32 v0, 16, v0
	s_nop 1
	v_cvt_pk_bf16_f32 v114, v114, v115
	v_cvt_pk_bf16_f32 v115, v116, v117
	v_lshlrev_b32_e32 v116, 3, v196
	s_lshl_b32 s10, s42, 1
	v_add3_u32 v0, v0, v116, s10
	v_cvt_pk_bf16_f32 v116, v118, v119
	v_cvt_pk_bf16_f32 v117, v120, v121
	v_cvt_pk_bf16_f32 v98, v98, v99
	v_cvt_pk_bf16_f32 v99, v100, v101
	v_cvt_pk_bf16_f32 v100, v102, v103
	v_cvt_pk_bf16_f32 v101, v104, v105
	v_cvt_pk_bf16_f32 v82, v82, v83
	v_cvt_pk_bf16_f32 v83, v84, v85
	v_cvt_pk_bf16_f32 v84, v86, v87
	v_cvt_pk_bf16_f32 v85, v88, v89
	v_cvt_pk_bf16_f32 v50, v50, v51
	v_cvt_pk_bf16_f32 v51, v52, v53
	v_cvt_pk_bf16_f32 v52, v54, v55
	v_cvt_pk_bf16_f32 v53, v56, v57
	s_waitcnt vmcnt(0)
	s_barrier
	ds_write2_b64 v0, v[114:115], v[116:117] offset1:2
	v_cvt_pk_bf16_f32 v114, v122, v123
	v_cvt_pk_bf16_f32 v115, v124, v125
	v_cvt_pk_bf16_f32 v116, v126, v127
	v_cvt_pk_bf16_f32 v117, v128, v129
	ds_write2_b64 v0, v[98:99], v[100:101] offset0:8 offset1:10
	v_cvt_pk_bf16_f32 v98, v106, v107
	v_cvt_pk_bf16_f32 v99, v108, v109
	v_cvt_pk_bf16_f32 v100, v110, v111
	v_cvt_pk_bf16_f32 v101, v112, v113
	ds_write2_b64 v0, v[82:83], v[84:85] offset0:16 offset1:18
	v_cvt_pk_bf16_f32 v82, v90, v91
	v_cvt_pk_bf16_f32 v83, v92, v93
	v_cvt_pk_bf16_f32 v84, v94, v95
	v_cvt_pk_bf16_f32 v85, v96, v97
	ds_write2_b64 v0, v[50:51], v[52:53] offset0:24 offset1:26
	v_cvt_pk_bf16_f32 v50, v58, v59
	v_cvt_pk_bf16_f32 v51, v60, v61
	v_cvt_pk_bf16_f32 v52, v62, v63
	v_cvt_pk_bf16_f32 v53, v64, v65
	ds_write2_b64 v0, v[114:115], v[116:117] offset0:4 offset1:6
	ds_write2_b64 v0, v[98:99], v[100:101] offset0:12 offset1:14
	ds_write2_b64 v0, v[82:83], v[84:85] offset0:20 offset1:22
	ds_write2_b64 v0, v[50:51], v[52:53] offset0:28 offset1:30
	v_cvt_pk_bf16_f32 v50, v66, v67
	v_cvt_pk_bf16_f32 v51, v68, v69
	v_cvt_pk_bf16_f32 v52, v70, v71
	v_cvt_pk_bf16_f32 v53, v72, v73
	v_add_u32_e32 v0, 0x4000, v0
	v_cvt_pk_bf16_f32 v34, v34, v35
	v_cvt_pk_bf16_f32 v35, v36, v37
	v_cvt_pk_bf16_f32 v36, v38, v39
	v_cvt_pk_bf16_f32 v37, v40, v41
	v_cvt_pk_bf16_f32 v18, v18, v19
	v_cvt_pk_bf16_f32 v19, v20, v21
	v_cvt_pk_bf16_f32 v20, v22, v23
	v_cvt_pk_bf16_f32 v21, v24, v25
	v_cvt_pk_bf16_f32 v2, v2, v3
	v_cvt_pk_bf16_f32 v3, v4, v5
	v_cvt_pk_bf16_f32 v4, v6, v7
	v_cvt_pk_bf16_f32 v5, v8, v9
	ds_write2_b64 v0, v[50:51], v[52:53] offset0:64 offset1:66
	v_cvt_pk_bf16_f32 v50, v74, v75
	v_cvt_pk_bf16_f32 v51, v76, v77
	v_cvt_pk_bf16_f32 v52, v78, v79
	v_cvt_pk_bf16_f32 v53, v80, v81
	ds_write2_b64 v0, v[34:35], v[36:37] offset0:72 offset1:74
	v_cvt_pk_bf16_f32 v34, v42, v43
	v_cvt_pk_bf16_f32 v35, v44, v45
	v_cvt_pk_bf16_f32 v36, v46, v47
	v_cvt_pk_bf16_f32 v37, v48, v49
	ds_write2_b64 v0, v[18:19], v[20:21] offset0:80 offset1:82
	v_cvt_pk_bf16_f32 v18, v26, v27
	v_cvt_pk_bf16_f32 v19, v28, v29
	v_cvt_pk_bf16_f32 v20, v30, v31
	v_cvt_pk_bf16_f32 v21, v32, v33
	ds_write2_b64 v0, v[2:3], v[4:5] offset0:88 offset1:90
	v_cvt_pk_bf16_f32 v2, v10, v11
	v_cvt_pk_bf16_f32 v3, v12, v13
	v_cvt_pk_bf16_f32 v4, v14, v15
	v_cvt_pk_bf16_f32 v5, v16, v17
	s_lshl_b64 s[10:11], s[16:17], 1
	ds_write2_b64 v0, v[50:51], v[52:53] offset0:68 offset1:70
	ds_write2_b64 v0, v[34:35], v[36:37] offset0:76 offset1:78
	ds_write2_b64 v0, v[18:19], v[20:21] offset0:84 offset1:86
	ds_write2_b64 v0, v[2:3], v[4:5] offset0:92 offset1:94
	s_waitcnt vmcnt(0) lgkmcnt(0)
	s_barrier
; #define GAS __attribute__((address_space(1)))
;     ...
;   __syncthreads();
;   int tid2 = tid; asm volatile("" : "+v"(tid2));
;   if (EPI == 0) {
; #pragma unroll
;     for (int i = 0; i < 16; ++i) {
;       const int id = tid2 + 256 * i, r = id >> 5, c8 = (id & 31) * 8;
;       const u32x4 v = *(const u32x4*)(smem + r * 528 + c8 * 2);
;       *(GAS u32x4*)(ea.out + (size_t)(m0 + r) * ea.ldo + n0 + c8) = v;
;     }
;   } else {
	s_add_u32 s10, s21, s10
	v_lshlrev_b32_e32 v0, 4, v189
	v_and_b32_e32 v0, 0x1f0, v0
	s_addc_u32 s11, s22, s11
	v_add_u32_e32 v10, 16, v0
	v_lshl_add_u64 v[12:13], s[10:11], 0, v[0:1]
	v_ashrrev_i32_e32 v0, 5, v189
	v_mad_u64_u32 v[2:3], s[10:11], v0, s55, v[10:11]
	ds_read_b128 v[2:5], v2
	v_add_u32_e32 v6, s40, v0
	v_ashrrev_i32_e32 v7, 31, v6
	v_add_u32_e32 v0, 0x100, v189
	v_lshlrev_b64 v[6:7], 11, v[6:7]
	v_ashrrev_i32_e32 v0, 5, v0
	v_lshl_add_u64 v[14:15], v[12:13], 0, v[6:7]
	v_mad_u64_u32 v[6:7], s[10:11], v0, s55, v[10:11]
	ds_read_b128 v[6:9], v6
	s_waitcnt lgkmcnt(1)
	global_store_dwordx4 v[14:15], v[2:5], off nt
	s_nop 1
	v_add_u32_e32 v2, s40, v0
	v_ashrrev_i32_e32 v3, 31, v2
	v_lshlrev_b64 v[2:3], 11, v[2:3]
	v_add_u32_e32 v0, 0x200, v189
	v_lshl_add_u64 v[2:3], v[12:13], 0, v[2:3]
	v_ashrrev_i32_e32 v0, 5, v0
	s_waitcnt lgkmcnt(0)
	global_store_dwordx4 v[2:3], v[6:9], off nt
	v_mad_u64_u32 v[2:3], s[10:11], v0, s55, v[10:11]
	ds_read_b128 v[2:5], v2
	v_add_u32_e32 v6, s40, v0
	v_ashrrev_i32_e32 v7, 31, v6
	v_add_u32_e32 v0, 0x300, v189
	v_lshlrev_b64 v[6:7], 11, v[6:7]
	v_ashrrev_i32_e32 v0, 5, v0
	v_lshl_add_u64 v[14:15], v[12:13], 0, v[6:7]
	v_mad_u64_u32 v[6:7], s[10:11], v0, s55, v[10:11]
	ds_read_b128 v[6:9], v6
	s_waitcnt lgkmcnt(1)
	global_store_dwordx4 v[14:15], v[2:5], off nt
	s_nop 1
	v_add_u32_e32 v2, s40, v0
	v_ashrrev_i32_e32 v3, 31, v2
	v_lshlrev_b64 v[2:3], 11, v[2:3]
	v_add_u32_e32 v0, 0x400, v189
	v_lshl_add_u64 v[2:3], v[12:13], 0, v[2:3]
	v_ashrrev_i32_e32 v0, 5, v0
	s_waitcnt lgkmcnt(0)
	global_store_dwordx4 v[2:3], v[6:9], off nt
	v_mad_u64_u32 v[2:3], s[10:11], v0, s55, v[10:11]
	ds_read_b128 v[2:5], v2
	v_add_u32_e32 v6, s40, v0
	v_ashrrev_i32_e32 v7, 31, v6
	v_add_u32_e32 v0, 0x500, v189
	v_lshlrev_b64 v[6:7], 11, v[6:7]
	v_ashrrev_i32_e32 v0, 5, v0
	v_lshl_add_u64 v[14:15], v[12:13], 0, v[6:7]
	v_mad_u64_u32 v[6:7], s[10:11], v0, s55, v[10:11]
	ds_read_b128 v[6:9], v6
	s_waitcnt lgkmcnt(1)
	global_store_dwordx4 v[14:15], v[2:5], off nt
	s_nop 1
	v_add_u32_e32 v2, s40, v0
	v_ashrrev_i32_e32 v3, 31, v2
	v_lshlrev_b64 v[2:3], 11, v[2:3]
	v_add_u32_e32 v0, 0x600, v189
	v_lshl_add_u64 v[2:3], v[12:13], 0, v[2:3]
	v_ashrrev_i32_e32 v0, 5, v0
	s_waitcnt lgkmcnt(0)
	global_store_dwordx4 v[2:3], v[6:9], off nt
	v_mad_u64_u32 v[2:3], s[10:11], v0, s55, v[10:11]
	ds_read_b128 v[2:5], v2
	v_add_u32_e32 v6, s40, v0
	v_ashrrev_i32_e32 v7, 31, v6
	v_add_u32_e32 v0, 0x700, v189
	v_lshlrev_b64 v[6:7], 11, v[6:7]
	v_ashrrev_i32_e32 v0, 5, v0
	v_lshl_add_u64 v[14:15], v[12:13], 0, v[6:7]
	v_mad_u64_u32 v[6:7], s[10:11], v0, s55, v[10:11]
	ds_read_b128 v[6:9], v6
	s_waitcnt lgkmcnt(1)
	global_store_dwordx4 v[14:15], v[2:5], off nt
	s_nop 1
	v_add_u32_e32 v2, s40, v0
	v_ashrrev_i32_e32 v3, 31, v2
	v_lshlrev_b64 v[2:3], 11, v[2:3]
	v_add_u32_e32 v0, 0x800, v189
	v_lshl_add_u64 v[2:3], v[12:13], 0, v[2:3]
	v_ashrrev_i32_e32 v0, 5, v0
	s_waitcnt lgkmcnt(0)
	global_store_dwordx4 v[2:3], v[6:9], off nt
	v_mad_u64_u32 v[2:3], s[10:11], v0, s55, v[10:11]
	ds_read_b128 v[2:5], v2
	v_add_u32_e32 v6, s40, v0
	v_ashrrev_i32_e32 v7, 31, v6
	v_add_u32_e32 v0, 0x900, v189
	v_lshlrev_b64 v[6:7], 11, v[6:7]
	v_ashrrev_i32_e32 v0, 5, v0
	v_lshl_add_u64 v[14:15], v[12:13], 0, v[6:7]
	v_mad_u64_u32 v[6:7], s[10:11], v0, s55, v[10:11]
	ds_read_b128 v[6:9], v6
	s_waitcnt lgkmcnt(1)
	global_store_dwordx4 v[14:15], v[2:5], off nt
	s_nop 1
	v_add_u32_e32 v2, s40, v0
	v_ashrrev_i32_e32 v3, 31, v2
	v_lshlrev_b64 v[2:3], 11, v[2:3]
	v_add_u32_e32 v0, 0xa00, v189
	v_lshl_add_u64 v[2:3], v[12:13], 0, v[2:3]
	v_ashrrev_i32_e32 v0, 5, v0
	s_waitcnt lgkmcnt(0)
	global_store_dwordx4 v[2:3], v[6:9], off nt
	v_mad_u64_u32 v[2:3], s[10:11], v0, s55, v[10:11]
	ds_read_b128 v[2:5], v2
	v_add_u32_e32 v6, s40, v0
	v_ashrrev_i32_e32 v7, 31, v6
	v_add_u32_e32 v0, 0xb00, v189
	v_lshlrev_b64 v[6:7], 11, v[6:7]
	v_ashrrev_i32_e32 v0, 5, v0
	v_lshl_add_u64 v[14:15], v[12:13], 0, v[6:7]
	v_mad_u64_u32 v[6:7], s[10:11], v0, s55, v[10:11]
	ds_read_b128 v[6:9], v6
	s_waitcnt lgkmcnt(1)
	global_store_dwordx4 v[14:15], v[2:5], off nt
	s_nop 1
	v_add_u32_e32 v2, s40, v0
	v_ashrrev_i32_e32 v3, 31, v2
	v_lshlrev_b64 v[2:3], 11, v[2:3]
	v_add_u32_e32 v0, 0xc00, v189
	v_lshl_add_u64 v[2:3], v[12:13], 0, v[2:3]
	v_ashrrev_i32_e32 v0, 5, v0
	s_waitcnt lgkmcnt(0)
	global_store_dwordx4 v[2:3], v[6:9], off nt
	v_mad_u64_u32 v[2:3], s[10:11], v0, s55, v[10:11]
	ds_read_b128 v[2:5], v2
	v_add_u32_e32 v6, s40, v0
	v_ashrrev_i32_e32 v7, 31, v6
	v_add_u32_e32 v0, 0xd00, v189
	v_lshlrev_b64 v[6:7], 11, v[6:7]
	v_ashrrev_i32_e32 v0, 5, v0
	v_lshl_add_u64 v[14:15], v[12:13], 0, v[6:7]
	v_mad_u64_u32 v[6:7], s[10:11], v0, s55, v[10:11]
	ds_read_b128 v[6:9], v6
	s_waitcnt lgkmcnt(1)
	global_store_dwordx4 v[14:15], v[2:5], off nt
	s_nop 1
	v_add_u32_e32 v2, s40, v0
	v_ashrrev_i32_e32 v3, 31, v2
	v_lshlrev_b64 v[2:3], 11, v[2:3]
	v_add_u32_e32 v0, 0xe00, v189
	v_lshl_add_u64 v[2:3], v[12:13], 0, v[2:3]
	v_ashrrev_i32_e32 v0, 5, v0
	s_waitcnt lgkmcnt(0)
	global_store_dwordx4 v[2:3], v[6:9], off nt
	v_mad_u64_u32 v[2:3], s[10:11], v0, s55, v[10:11]
	ds_read_b128 v[2:5], v2
	v_add_u32_e32 v6, s40, v0
	v_ashrrev_i32_e32 v7, 31, v6
	v_add_u32_e32 v0, 0xf00, v189
	v_lshlrev_b64 v[6:7], 11, v[6:7]
	v_ashrrev_i32_e32 v0, 5, v0
	v_lshl_add_u64 v[14:15], v[12:13], 0, v[6:7]
	v_mad_u64_u32 v[6:7], s[10:11], v0, s55, v[10:11]
	ds_read_b128 v[6:9], v6
	s_waitcnt lgkmcnt(1)
	global_store_dwordx4 v[14:15], v[2:5], off nt
	v_readlane_b32 s10, v252, 12
	s_add_i32 s29, s29, s10
	v_add_u32_e32 v2, s40, v0
	v_ashrrev_i32_e32 v3, 31, v2
	v_lshlrev_b64 v[2:3], 11, v[2:3]
	v_lshl_add_u64 v[2:3], v[12:13], 0, v[2:3]
	s_cmp_ge_i32 s29, s18
	s_waitcnt lgkmcnt(0)
	global_store_dwordx4 v[2:3], v[6:9], off nt
	s_barrier
	s_cbranch_scc0 .LBB0_243

; #define LAS __attribute__((address_space(3)))
;     ...
;   const int lane = tid & 63, wid = __builtin_amdgcn_readfirstlane(tid >> 6), wr = wid >> 1, wc = wid & 1;
;   const int m0 = mt * 128, n0 = nt * 256;
;   const int r = lane & 31, h = lane >> 5, key = (r >> 2) & 3;
;   constexpr int STG = 24576;
;   const int rowl = lane >> 2, cch = (lane & 3) ^ ((lane >> 4) & 3);
;   const unsigned voffA = (unsigned)(rowl * lda * 2 + cch * 16), voffB = (unsigned)(rowl * K * 2 + cch * 16);
;   const char* Abase = (const char*)(A + (size_t)m0 * lda) + (size_t)(wid * 2) * 32 * lda;
;   const char* Bbase = (const char*)(Bt + (size_t)n0 * K) + (size_t)(wid * 4) * 32 * K;
;   const size_t ablk = (size_t)32 * lda, bblk = (size_t)32 * K;
;   LAS char* lds = (LAS char*)smem;
;   LAS char* ldsA = lds + (wid * 2) * 1024;
;   LAS char* ldsB = lds + 8192 + (wid * 4) * 1024;
;     ...
;   const int x0 = ((0 + h) ^ key) * 16, x1 = ((2 + h) ^ key) * 16;
;   const int a_rd = (wr * 64 + r) * 64, b_rd = 8192 + (wc * 128 + r) * 64;
;   f32x16 acc[2][4];
; #pragma unroll
;   for (int i = 0; i < 2; ++i)
; #pragma unroll
;     for (int j = 0; j < 4; ++j)
; #pragma unroll
;       for (int e = 0; e < 16; ++e) acc[i][j][e] = 0.f;
;   const int nk = K >> 5;
;   DMA_STEP_(0, 0);
;   DMA_STEP_(1, STG);
;   asm volatile("s_waitcnt vmcnt(6)" ::: "memory");
;   __builtin_amdgcn_s_barrier();
;   asm volatile("" ::: "memory");
;   int s0 = 0, s2 = 2 * STG;
;   for (int kt = 0; kt < nk; ++kt) {
;     const int kn = (kt + 2 < nk) ? (kt + 2) : (nk - 1);
;     const LAS char* cur = lds + s0;
;     bf16x8 af[2][2], bfr[2][4];
; #pragma unroll
;     for (int kk = 0; kk < 2; ++kk) {
;       const int xo = kk ? x1 : x0;
;       af[kk][0] = *(const LAS bf16x8*)(cur + a_rd + xo);
;       bfr[kk][0] = *(const LAS bf16x8*)(cur + b_rd + xo);
.LBB0_271:
	s_mul_hi_i32 s10, s14, 0x2e8ba2e9
	s_lshr_b32 s11, s10, 31
	s_ashr_i32 s10, s10, 4
	s_add_i32 s10, s10, s11
	v_readlane_b32 s15, v252, 18
	s_mul_i32 s11, s10, 0xffffffa8
	s_lshl_b32 s10, s10, s15
	v_readlane_b32 s15, v252, 41
	s_add_i32 s10, s10, s15
	s_lshr_b32 s15, s10, 31
	s_add_i32 s15, s10, s15
	s_and_b32 s18, s15, -2
	s_add_i32 s11, s11, s14
	s_sub_i32 s10, s10, s18
	s_mul_i32 s22, s10, 11
	s_ashr_i32 s10, s11, 3
	v_mov_b32_e32 v189, v188
	s_lshl_b32 s15, s15, 2
	s_add_i32 s22, s22, s10
	s_and_b32 s15, s15, -8
	v_readfirstlane_b32 s10, v189
	s_and_b32 s18, s14, 7
	s_ashr_i32 s11, s10, 6
	s_or_b32 s15, s15, s18
	s_lshl_b32 s18, s11, 1
	s_ashr_i32 s19, s18, 31
	s_lshl_b64 s[28:29], s[18:19], 10
	s_lshl_b32 s18, s11, 2
	s_ashr_i32 s19, s18, 31
	s_ashr_i32 s10, s10, 1
	s_lshl_b32 s46, s15, 7
	s_lshl_b32 s66, s22, 8
	v_and_b32_e32 v0, 31, v189
	s_lshl_b64 s[74:75], s[18:19], 10
	s_lshl_b32 s18, s11, 12
	s_andn2_b32 s10, s10, 63
	v_lshlrev_b32_e32 v3, 4, v189
	s_ashr_i32 s47, s46, 31
	s_ashr_i32 s67, s66, 31
	s_add_i32 s19, s18, 16
	v_or_b32_e32 v197, s10, v0
	s_lshl_b32 s10, s11, 7
	v_lshlrev_b32_e32 v2, 9, v189
	v_bitop3_b32 v3, v3, 48, v189 bitop3:0x48
	s_lshl_b64 s[20:21], s[46:47], 6
	s_lshl_b64 s[40:41], s[66:67], 6
	s_add_i32 s23, s19, 0x2000
	s_and_b32 s18, s10, 0x80
	s_movk_i32 s10, 0x7800
	v_or_b32_e32 v4, s18, v0
	v_and_or_b32 v0, v2, s10, v3
	v_lshlrev_b32_e32 v10, 4, v189
	v_and_b32_e32 v10, 0x3c0, v10
	v_or_b32_e32 v10, v10, v3
	v_mov_b32_e32 v11, 0
	s_add_u32 s10, s42, s20
	s_addc_u32 s20, s43, s21
	s_add_u32 s28, s10, s28
	s_addc_u32 s29, s20, s29
	s_add_u32 s10, s87, s40
	s_addc_u32 s21, s76, s41
	s_lshl_b32 s11, s11, 11
	s_sub_i32 s20, s19, s11
	s_mov_b32 m0, s20
	v_lshl_add_u64 v[192:193], s[28:29], 0, v[10:11]
	global_load_lds_dwordx4 v[192:193], off
	global_load_lds_dwordx4 v[192:193], off offset:1024
	s_add_u32 s28, s10, s74
	s_addc_u32 s29, s21, s75
	v_lshl_add_u64 v[194:195], s[28:29], 0, v[10:11]
	s_mov_b32 m0, s23
	s_nop 0
	global_load_lds_dwordx4 v[194:195], off
	global_load_lds_dwordx4 v[194:195], off offset:1024
	global_load_lds_dwordx4 v[194:195], off offset:2048
	global_load_lds_dwordx4 v[194:195], off offset:3072
	s_mov_b64 s[10:11], 0x10000
	s_mov_b64 s[10:11], 0x18000
	s_mov_b64 s[10:11], 0x8040
	s_add_i32 m0, s20, 0x6000
	s_mov_b32 vcc_lo, 0x480000
	s_mov_b32 vcc_hi, 0
	v_lshl_add_u64 v[2:3], v[192:193], 0, vcc
	global_load_lds_dwordx4 v[2:3], off
	global_load_lds_dwordx4 v[2:3], off offset:1024
	v_lshrrev_b32_e32 v5, 5, v189
	s_add_i32 m0, s19, 0x8000
	s_mov_b32 s100, 0x58000
	v_lshl_add_u64 v[2:3], v[194:195], 0, s[100:101]
	global_load_lds_dwordx4 v[2:3], off
	global_load_lds_dwordx4 v[2:3], off offset:1024
	global_load_lds_dwordx4 v[2:3], off offset:2048
	global_load_lds_dwordx4 v[2:3], off offset:3072
	s_mov_b64 s[10:11], 0x10040
	s_mov_b64 s[10:11], 0x18040
	v_bfe_u32 v6, v189, 2, 2
	v_bfe_u32 v196, v189, 5, 1
	s_lshl_b32 s100, s100, 1
	v_lshl_add_u64 v[194:195], v[194:195], 0, s[100:101]
	s_lshl_b32 vcc_lo, vcc_lo, 1
	v_lshl_add_u64 v[192:193], v[192:193], 0, vcc
	s_waitcnt vmcnt(6)
	s_barrier
	v_bitop3_b32 v2, v5, v6, 1 bitop3:0x6c
	v_lshlrev_b32_e32 v219, 4, v2
	v_bitop3_b32 v2, v196, v6, 2 bitop3:0x36
	v_mov_b32_e32 v66, 0
	v_lshlrev_b32_e32 v218, 6, v197
	v_lshlrev_b32_e32 v0, 6, v4
	v_lshlrev_b32_e32 v220, 4, v2
	s_mov_b32 s23, 0xc000
	s_mov_b32 s28, 0
	s_mov_b32 s21, 0
	v_mov_b32_e32 v67, v66
	v_mov_b32_e32 v68, v66
	v_mov_b32_e32 v69, v66
	v_mov_b32_e32 v70, v66
	v_mov_b32_e32 v71, v66
	v_mov_b32_e32 v72, v66
	v_mov_b32_e32 v73, v66
	v_mov_b32_e32 v74, v66
	v_mov_b32_e32 v75, v66
	v_mov_b32_e32 v76, v66
	v_mov_b32_e32 v77, v66
	v_mov_b32_e32 v78, v66
	v_mov_b32_e32 v79, v66
	v_mov_b32_e32 v80, v66
	v_mov_b32_e32 v81, v66
	v_mov_b32_e32 v82, v66
	v_mov_b32_e32 v83, v66
	v_mov_b32_e32 v84, v66
	v_mov_b32_e32 v85, v66
	v_mov_b32_e32 v86, v66
	v_mov_b32_e32 v87, v66
	v_mov_b32_e32 v88, v66
	v_mov_b32_e32 v89, v66
	s_waitcnt vmcnt(0)
	v_mov_b32_e32 v90, v66
	v_mov_b32_e32 v91, v66
	v_mov_b32_e32 v92, v66
	v_mov_b32_e32 v93, v66
	v_mov_b32_e32 v94, v66
	v_mov_b32_e32 v95, v66
	v_mov_b32_e32 v96, v66
	v_mov_b32_e32 v97, v66
	v_mov_b32_e32 v18, v66
	v_mov_b32_e32 v19, v66
	v_mov_b32_e32 v20, v66
	v_mov_b32_e32 v21, v66
	v_mov_b32_e32 v22, v66
	v_mov_b32_e32 v23, v66
	v_mov_b32_e32 v24, v66
	v_mov_b32_e32 v25, v66
	v_mov_b32_e32 v26, v66
	v_mov_b32_e32 v27, v66
	v_mov_b32_e32 v28, v66
	v_mov_b32_e32 v29, v66
	v_mov_b32_e32 v30, v66
	v_mov_b32_e32 v31, v66
	v_mov_b32_e32 v32, v66
	v_mov_b32_e32 v33, v66
	v_mov_b32_e32 v2, v66
	v_mov_b32_e32 v3, v66
	v_mov_b32_e32 v4, v66
	v_mov_b32_e32 v5, v66
	v_mov_b32_e32 v6, v66
	v_mov_b32_e32 v7, v66
	v_mov_b32_e32 v8, v66
	v_mov_b32_e32 v9, v66
	v_mov_b32_e32 v10, v66
	v_mov_b32_e32 v11, v66
	v_mov_b32_e32 v12, v66
	v_mov_b32_e32 v13, v66
	v_mov_b32_e32 v14, v66
	v_mov_b32_e32 v15, v66
	v_mov_b32_e32 v16, v66
	v_mov_b32_e32 v17, v66
	v_mov_b32_e32 v114, v66
	v_mov_b32_e32 v115, v66
	v_mov_b32_e32 v116, v66
	v_mov_b32_e32 v117, v66
	v_mov_b32_e32 v118, v66
	v_mov_b32_e32 v119, v66
	v_mov_b32_e32 v120, v66
	v_mov_b32_e32 v121, v66
	v_mov_b32_e32 v122, v66
	v_mov_b32_e32 v123, v66
	v_mov_b32_e32 v124, v66
	v_mov_b32_e32 v125, v66
	v_mov_b32_e32 v126, v66
	v_mov_b32_e32 v127, v66
	v_mov_b32_e32 v128, v66
	v_mov_b32_e32 v129, v66
	v_mov_b32_e32 v98, v66
	v_mov_b32_e32 v99, v66
	v_mov_b32_e32 v100, v66
	v_mov_b32_e32 v101, v66
	v_mov_b32_e32 v102, v66
	v_mov_b32_e32 v103, v66
	v_mov_b32_e32 v104, v66
	v_mov_b32_e32 v105, v66
	v_mov_b32_e32 v106, v66
	v_mov_b32_e32 v107, v66
	v_mov_b32_e32 v108, v66
	v_mov_b32_e32 v109, v66
	v_mov_b32_e32 v110, v66
	v_mov_b32_e32 v111, v66
	v_mov_b32_e32 v112, v66
	v_mov_b32_e32 v113, v66
	v_mov_b32_e32 v50, v66
	v_mov_b32_e32 v51, v66
	v_mov_b32_e32 v52, v66
	v_mov_b32_e32 v53, v66
	v_mov_b32_e32 v54, v66
	v_mov_b32_e32 v55, v66
	v_mov_b32_e32 v56, v66
	v_mov_b32_e32 v57, v66
	v_mov_b32_e32 v58, v66
	v_mov_b32_e32 v59, v66
	v_mov_b32_e32 v60, v66
	v_mov_b32_e32 v61, v66
	v_mov_b32_e32 v62, v66
	v_mov_b32_e32 v63, v66
	v_mov_b32_e32 v64, v66
	v_mov_b32_e32 v65, v66
	v_mov_b32_e32 v34, v66
	v_mov_b32_e32 v35, v66
	v_mov_b32_e32 v36, v66
	v_mov_b32_e32 v37, v66
	v_mov_b32_e32 v38, v66
	v_mov_b32_e32 v39, v66
	v_mov_b32_e32 v40, v66
	v_mov_b32_e32 v41, v66
	v_mov_b32_e32 v42, v66
	v_mov_b32_e32 v43, v66
	v_mov_b32_e32 v44, v66
	v_mov_b32_e32 v45, v66
	v_mov_b32_e32 v46, v66
	v_mov_b32_e32 v47, v66
	v_mov_b32_e32 v48, v66
	v_mov_b32_e32 v49, v66
	s_mov_b32 vcc_hi, 0
	v_add_u32_e32 v226, v218, v219
	v_add_u32_e32 v227, v0, v219
	v_add_u32_e32 v228, v218, v220
	v_add_u32_e32 v229, v0, v220
	v_add_u32_e32 v158, 16, v226
	v_add_u32_e32 v170, 16, v227
	ds_read_b128 v[154:157], v158
	ds_read_b128 v[182:185], v170 offset:8192
	ds_read_b128 v[178:181], v170 offset:10240
	ds_read_b128 v[158:161], v158 offset:2048
	ds_read_b128 v[174:177], v170 offset:12288
	ds_read_b128 v[170:173], v170 offset:14336
	s_setprio 1
; #define LAS __attribute__((address_space(3)))
; DI f32x16 mfma32(bf16x8 a, bf16x8 b, f32x16 c) { return __builtin_amdgcn_mfma_f32_32x32x16_bf16(a, b, c, 0, 0, 0); }
;     ...
;   for (int kt = 0; kt < nk; ++kt) {
;     const int kn = (kt + 2 < nk) ? (kt + 2) : (nk - 1);
;     const LAS char* cur = lds + s0;
;     bf16x8 af[2][2], bfr[2][4];
; #pragma unroll
;     for (int kk = 0; kk < 2; ++kk) {
;       const int xo = kk ? x1 : x0;
;       af[kk][0] = *(const LAS bf16x8*)(cur + a_rd + xo);
;       bfr[kk][0] = *(const LAS bf16x8*)(cur + b_rd + xo);
;       bfr[kk][1] = *(const LAS bf16x8*)(cur + b_rd + 2048 + xo);
;       af[kk][1] = *(const LAS bf16x8*)(cur + a_rd + 2048 + xo);
;       bfr[kk][2] = *(const LAS bf16x8*)(cur + b_rd + 4096 + xo);
;       bfr[kk][3] = *(const LAS bf16x8*)(cur + b_rd + 6144 + xo);
;     }
;     DMA_STEP_(kn, s2);
; #pragma unroll
;     for (int kk = 0; kk < 2; ++kk) {
;       acc[0][0] = mfma32(bfr[kk][0], af[kk][0], acc[0][0]); acc[0][1] = mfma32(bfr[kk][1], af[kk][0], acc[0][1]);
;       acc[1][0] = mfma32(bfr[kk][0], af[kk][1], acc[1][0]); acc[1][1] = mfma32(bfr[kk][1], af[kk][1], acc[1][1]);
;       acc[0][2] = mfma32(bfr[kk][2], af[kk][0], acc[0][2]); acc[0][3] = mfma32(bfr[kk][3], af[kk][0], acc[0][3]);
;       acc[1][2] = mfma32(bfr[kk][2], af[kk][1], acc[1][2]); acc[1][3] = mfma32(bfr[kk][3], af[kk][1], acc[1][3]);
;     }
;     __builtin_amdgcn_sched_group_barrier(0x100, 12, 0);
;     __builtin_amdgcn_sched_group_barrier(0x010, 6, 0);
;     __builtin_amdgcn_sched_group_barrier(0x008, 16, 0);
;     asm volatile("s_waitcnt vmcnt(6) lgkmcnt(0)" ::: "memory");
;     __builtin_amdgcn_s_barrier();
;     asm volatile("" ::: "memory");
;     s0 = (s0 == 2 * STG) ? 0 : s0 + STG;
;     s2 = (s2 == 2 * STG) ? 0 : s2 + STG;
;   }
.LBB0_272:
	s_add_i32 s11, s28, 16
	s_mov_b32 s10, s21
	v_add_u32_e32 v142, s11, v228
	v_add_u32_e32 v150, s11, v229
	s_min_u32 s10, s10, 29
	s_lshl_b32 s70, s10, 6
	ds_read_b128 v[138:141], v142
	ds_read_b128 v[162:165], v150 offset:8192
	ds_read_b128 v[166:169], v150 offset:10240
	ds_read_b128 v[142:145], v142 offset:2048
	ds_read_b128 v[146:149], v150 offset:12288
	ds_read_b128 v[150:153], v150 offset:14336
	s_mul_i32 vcc_lo, s70, 0x12000
	s_add_i32 s10, s20, s23
	v_lshl_add_u64 v[222:223], v[192:193], 0, vcc
	s_mov_b32 m0, s10
	s_mul_i32 s100, s70, 0x1600
	v_lshl_add_u64 v[224:225], v[194:195], 0, s[100:101]
	s_add_i32 s10, s19, s23
	s_waitcnt lgkmcnt(6)
	v_mfma_f32_32x32x16_bf16 v[66:81], v[182:185], v[154:157], v[66:81]
	global_load_lds_dwordx4 v[222:223], off
	v_mfma_f32_32x32x16_bf16 v[82:97], v[178:181], v[154:157], v[82:97]
	global_load_lds_dwordx4 v[222:223], off offset:1024
	s_add_i32 m0, s10, 0x2000
	v_mfma_f32_32x32x16_bf16 v[18:33], v[182:185], v[158:161], v[18:33]
	global_load_lds_dwordx4 v[224:225], off
	v_mfma_f32_32x32x16_bf16 v[2:17], v[178:181], v[158:161], v[2:17]
	global_load_lds_dwordx4 v[224:225], off offset:1024
	v_mfma_f32_32x32x16_bf16 v[114:129], v[174:177], v[154:157], v[114:129]
	global_load_lds_dwordx4 v[224:225], off offset:2048
	v_mfma_f32_32x32x16_bf16 v[98:113], v[170:173], v[154:157], v[98:113]
	global_load_lds_dwordx4 v[224:225], off offset:3072
	v_mfma_f32_32x32x16_bf16 v[50:65], v[174:177], v[158:161], v[50:65]
	s_add_i32 s10, s28, 0x6000
	s_cmpk_lg_u32 s28, 0xc000
	s_cselect_b32 s28, s10, 0
	s_add_i32 s10, s23, 0x6000
	s_cmpk_lg_u32 s23, 0xc000
	s_cselect_b32 s23, s10, 0
	v_mfma_f32_32x32x16_bf16 v[34:49], v[170:173], v[158:161], v[34:49]
	s_add_i32 s11, s28, 16
	s_waitcnt vmcnt(6) lgkmcnt(0)
	s_barrier
	v_add_u32_e32 v158, s11, v226
	v_add_u32_e32 v170, s11, v227
	ds_read_b128 v[154:157], v158
	ds_read_b128 v[182:185], v170 offset:8192
	ds_read_b128 v[178:181], v170 offset:10240
	ds_read_b128 v[158:161], v158 offset:2048
	ds_read_b128 v[174:177], v170 offset:12288
	ds_read_b128 v[170:173], v170 offset:14336
	v_mfma_f32_32x32x16_bf16 v[66:81], v[162:165], v[138:141], v[66:81]
	v_mfma_f32_32x32x16_bf16 v[82:97], v[166:169], v[138:141], v[82:97]
	v_mfma_f32_32x32x16_bf16 v[18:33], v[162:165], v[142:145], v[18:33]
	v_mfma_f32_32x32x16_bf16 v[2:17], v[166:169], v[142:145], v[2:17]
	v_mfma_f32_32x32x16_bf16 v[114:129], v[146:149], v[138:141], v[114:129]
	v_mfma_f32_32x32x16_bf16 v[98:113], v[150:153], v[138:141], v[98:113]
	v_mfma_f32_32x32x16_bf16 v[50:65], v[146:149], v[142:145], v[50:65]
	v_mfma_f32_32x32x16_bf16 v[34:49], v[150:153], v[142:145], v[34:49]
	s_add_i32 s11, s28, 16
	s_add_i32 s10, s21, 1
	v_add_u32_e32 v142, s11, v228
	v_add_u32_e32 v150, s11, v229
	s_min_u32 s10, s10, 29
	s_lshl_b32 s70, s10, 6
	ds_read_b128 v[138:141], v142
	ds_read_b128 v[162:165], v150 offset:8192
	ds_read_b128 v[166:169], v150 offset:10240
	ds_read_b128 v[142:145], v142 offset:2048
	ds_read_b128 v[146:149], v150 offset:12288
	ds_read_b128 v[150:153], v150 offset:14336
	s_mul_i32 vcc_lo, s70, 0x12000
	s_add_i32 s10, s20, s23
	v_lshl_add_u64 v[222:223], v[192:193], 0, vcc
	s_mov_b32 m0, s10
	s_mul_i32 s100, s70, 0x1600
	v_lshl_add_u64 v[224:225], v[194:195], 0, s[100:101]
	s_add_i32 s10, s19, s23
	s_waitcnt lgkmcnt(6)
	v_mfma_f32_32x32x16_bf16 v[66:81], v[182:185], v[154:157], v[66:81]
	global_load_lds_dwordx4 v[222:223], off
	v_mfma_f32_32x32x16_bf16 v[82:97], v[178:181], v[154:157], v[82:97]
	global_load_lds_dwordx4 v[222:223], off offset:1024
	s_add_i32 m0, s10, 0x2000
	v_mfma_f32_32x32x16_bf16 v[18:33], v[182:185], v[158:161], v[18:33]
	global_load_lds_dwordx4 v[224:225], off
	v_mfma_f32_32x32x16_bf16 v[2:17], v[178:181], v[158:161], v[2:17]
	global_load_lds_dwordx4 v[224:225], off offset:1024
	v_mfma_f32_32x32x16_bf16 v[114:129], v[174:177], v[154:157], v[114:129]
	global_load_lds_dwordx4 v[224:225], off offset:2048
	v_mfma_f32_32x32x16_bf16 v[98:113], v[170:173], v[154:157], v[98:113]
	global_load_lds_dwordx4 v[224:225], off offset:3072
	v_mfma_f32_32x32x16_bf16 v[50:65], v[174:177], v[158:161], v[50:65]
	s_add_i32 s10, s28, 0x6000
	s_cmpk_lg_u32 s28, 0xc000
	s_cselect_b32 s28, s10, 0
	s_add_i32 s10, s23, 0x6000
	s_cmpk_lg_u32 s23, 0xc000
	s_cselect_b32 s23, s10, 0
	v_mfma_f32_32x32x16_bf16 v[34:49], v[170:173], v[158:161], v[34:49]
	s_add_i32 s11, s28, 16
	s_waitcnt vmcnt(6) lgkmcnt(0)
	s_barrier
	v_add_u32_e32 v158, s11, v226
	v_add_u32_e32 v170, s11, v227
	ds_read_b128 v[154:157], v158
	ds_read_b128 v[182:185], v170 offset:8192
	ds_read_b128 v[178:181], v170 offset:10240
	ds_read_b128 v[158:161], v158 offset:2048
	ds_read_b128 v[174:177], v170 offset:12288
	ds_read_b128 v[170:173], v170 offset:14336
	v_mfma_f32_32x32x16_bf16 v[66:81], v[162:165], v[138:141], v[66:81]
	v_mfma_f32_32x32x16_bf16 v[82:97], v[166:169], v[138:141], v[82:97]
	v_mfma_f32_32x32x16_bf16 v[18:33], v[162:165], v[142:145], v[18:33]
	v_mfma_f32_32x32x16_bf16 v[2:17], v[166:169], v[142:145], v[2:17]
	v_mfma_f32_32x32x16_bf16 v[114:129], v[146:149], v[138:141], v[114:129]
	v_mfma_f32_32x32x16_bf16 v[98:113], v[150:153], v[138:141], v[98:113]
	v_mfma_f32_32x32x16_bf16 v[50:65], v[146:149], v[142:145], v[50:65]
	v_mfma_f32_32x32x16_bf16 v[34:49], v[150:153], v[142:145], v[34:49]
	s_add_i32 s21, s21, 2
	s_cmp_eq_u32 s21, 30
	s_cbranch_scc0 .LBB0_272
; #define LAS __attribute__((address_space(3)))
; DI unsigned pk2(float a, float b) { f32x2 v = {a, b}; bf2_t r = __builtin_convertvector(v, bf2_t); return __builtin_bit_cast(unsigned, r); }
;     ...
;   for (int kt = 0; kt < nk; ++kt) {
;     const int kn = (kt + 2 < nk) ? (kt + 2) : (nk - 1);
;     const LAS char* cur = lds + s0;
;     bf16x8 af[2][2], bfr[2][4];
; #pragma unroll
;     for (int kk = 0; kk < 2; ++kk) {
;       const int xo = kk ? x1 : x0;
;       af[kk][0] = *(const LAS bf16x8*)(cur + a_rd + xo);
;       bfr[kk][0] = *(const LAS bf16x8*)(cur + b_rd + xo);
;       bfr[kk][1] = *(const LAS bf16x8*)(cur + b_rd + 2048 + xo);
;       af[kk][1] = *(const LAS bf16x8*)(cur + a_rd + 2048 + xo);
;       bfr[kk][2] = *(const LAS bf16x8*)(cur + b_rd + 4096 + xo);
;       bfr[kk][3] = *(const LAS bf16x8*)(cur + b_rd + 6144 + xo);
;     }
;     DMA_STEP_(kn, s2);
; #pragma unroll
;     for (int kk = 0; kk < 2; ++kk) {
;       acc[0][0] = mfma32(bfr[kk][0], af[kk][0], acc[0][0]); acc[0][1] = mfma32(bfr[kk][1], af[kk][0], acc[0][1]);
;       acc[1][0] = mfma32(bfr[kk][0], af[kk][1], acc[1][0]); acc[1][1] = mfma32(bfr[kk][1], af[kk][1], acc[1][1]);
;       acc[0][2] = mfma32(bfr[kk][2], af[kk][0], acc[0][2]); acc[0][3] = mfma32(bfr[kk][3], af[kk][0], acc[0][3]);
;       acc[1][2] = mfma32(bfr[kk][2], af[kk][1], acc[1][2]); acc[1][3] = mfma32(bfr[kk][3], af[kk][1], acc[1][3]);
;     }
;     __builtin_amdgcn_sched_group_barrier(0x100, 12, 0);
;     __builtin_amdgcn_sched_group_barrier(0x010, 6, 0);
;     __builtin_amdgcn_sched_group_barrier(0x008, 16, 0);
;     asm volatile("s_waitcnt vmcnt(6) lgkmcnt(0)" ::: "memory");
;     __builtin_amdgcn_s_barrier();
;     asm volatile("" ::: "memory");
;     s0 = (s0 == 2 * STG) ? 0 : s0 + STG;
;     s2 = (s2 == 2 * STG) ? 0 : s2 + STG;
;   }
;   asm volatile("s_waitcnt vmcnt(0)" ::: "memory");
;   __builtin_amdgcn_s_barrier();
;   asm volatile("" ::: "memory");
;     ...
;   {
;     const int h = lane >> 5, cl = lane & 31;
; #pragma unroll
;     for (int i = 0; i < 2; ++i)
; #pragma unroll
;       for (int j = 0; j < 4; ++j)
; #pragma unroll
;         for (int g = 0; g < 4; ++g) {
;           u32x2 w; w.x = pk2(acc[i][j][4 * g], acc[i][j][4 * g + 1]); w.y = pk2(acc[i][j][4 * g + 2], acc[i][j][4 * g + 3]);
;           *(u32x2*)(smem + (wr * 64 + i * 32 + cl) * 528 + (wc * 128 + j * 32 + 8 * g + 4 * h) * 2) = w;
;         }
	s_add_i32 s11, s28, 16
	v_add_u32_e32 v142, s11, v228
	v_add_u32_e32 v150, s11, v229
	ds_read_b128 v[138:141], v142
	ds_read_b128 v[162:165], v150 offset:8192
	ds_read_b128 v[166:169], v150 offset:10240
	ds_read_b128 v[142:145], v142 offset:2048
	ds_read_b128 v[146:149], v150 offset:12288
	ds_read_b128 v[150:153], v150 offset:14336
	s_waitcnt lgkmcnt(6)
	v_mfma_f32_32x32x16_bf16 v[66:81], v[182:185], v[154:157], v[66:81]
	v_mfma_f32_32x32x16_bf16 v[82:97], v[178:181], v[154:157], v[82:97]
	v_mfma_f32_32x32x16_bf16 v[18:33], v[182:185], v[158:161], v[18:33]
	v_mfma_f32_32x32x16_bf16 v[2:17], v[178:181], v[158:161], v[2:17]
	v_mfma_f32_32x32x16_bf16 v[114:129], v[174:177], v[154:157], v[114:129]
	v_mfma_f32_32x32x16_bf16 v[98:113], v[170:173], v[154:157], v[98:113]
	v_mfma_f32_32x32x16_bf16 v[50:65], v[174:177], v[158:161], v[50:65]
	s_add_i32 s10, s28, 0x6000
	s_cmpk_lg_u32 s28, 0xc000
	s_cselect_b32 s28, s10, 0
	v_mfma_f32_32x32x16_bf16 v[34:49], v[170:173], v[158:161], v[34:49]
	s_add_i32 s11, s28, 16
	s_waitcnt vmcnt(0) lgkmcnt(0)
	s_barrier
	v_add_u32_e32 v158, s11, v226
	v_add_u32_e32 v170, s11, v227
	ds_read_b128 v[154:157], v158
	ds_read_b128 v[182:185], v170 offset:8192
	ds_read_b128 v[178:181], v170 offset:10240
	ds_read_b128 v[158:161], v158 offset:2048
	ds_read_b128 v[174:177], v170 offset:12288
	ds_read_b128 v[170:173], v170 offset:14336
	v_mfma_f32_32x32x16_bf16 v[66:81], v[162:165], v[138:141], v[66:81]
	v_mfma_f32_32x32x16_bf16 v[82:97], v[166:169], v[138:141], v[82:97]
	v_mfma_f32_32x32x16_bf16 v[18:33], v[162:165], v[142:145], v[18:33]
	v_mfma_f32_32x32x16_bf16 v[2:17], v[166:169], v[142:145], v[2:17]
	v_mfma_f32_32x32x16_bf16 v[114:129], v[146:149], v[138:141], v[114:129]
	v_mfma_f32_32x32x16_bf16 v[98:113], v[150:153], v[138:141], v[98:113]
	v_mfma_f32_32x32x16_bf16 v[50:65], v[146:149], v[142:145], v[50:65]
	v_mfma_f32_32x32x16_bf16 v[34:49], v[150:153], v[142:145], v[34:49]
	s_add_i32 s11, s28, 16
	v_add_u32_e32 v142, s11, v228
	v_add_u32_e32 v150, s11, v229
	ds_read_b128 v[138:141], v142
	ds_read_b128 v[162:165], v150 offset:8192
	ds_read_b128 v[166:169], v150 offset:10240
	ds_read_b128 v[142:145], v142 offset:2048
	ds_read_b128 v[146:149], v150 offset:12288
	ds_read_b128 v[150:153], v150 offset:14336
	s_waitcnt lgkmcnt(6)
	v_mfma_f32_32x32x16_bf16 v[66:81], v[182:185], v[154:157], v[66:81]
	v_mfma_f32_32x32x16_bf16 v[82:97], v[178:181], v[154:157], v[82:97]
	v_mfma_f32_32x32x16_bf16 v[18:33], v[182:185], v[158:161], v[18:33]
	v_mfma_f32_32x32x16_bf16 v[2:17], v[178:181], v[158:161], v[2:17]
	v_mfma_f32_32x32x16_bf16 v[114:129], v[174:177], v[154:157], v[114:129]
	v_mfma_f32_32x32x16_bf16 v[98:113], v[170:173], v[154:157], v[98:113]
	v_mfma_f32_32x32x16_bf16 v[50:65], v[174:177], v[158:161], v[50:65]
	v_mfma_f32_32x32x16_bf16 v[34:49], v[170:173], v[158:161], v[34:49]
	s_waitcnt lgkmcnt(0)
	v_mfma_f32_32x32x16_bf16 v[66:81], v[162:165], v[138:141], v[66:81]
	v_mfma_f32_32x32x16_bf16 v[82:97], v[166:169], v[138:141], v[82:97]
	v_mfma_f32_32x32x16_bf16 v[18:33], v[162:165], v[142:145], v[18:33]
	v_mfma_f32_32x32x16_bf16 v[2:17], v[166:169], v[142:145], v[2:17]
	v_mfma_f32_32x32x16_bf16 v[114:129], v[146:149], v[138:141], v[114:129]
	v_mfma_f32_32x32x16_bf16 v[98:113], v[150:153], v[138:141], v[98:113]
	v_mfma_f32_32x32x16_bf16 v[50:65], v[146:149], v[142:145], v[50:65]
	v_mfma_f32_32x32x16_bf16 v[34:49], v[150:153], v[142:145], v[34:49]
	s_waitcnt lgkmcnt(0)
	s_setprio 0
	v_mul_lo_u32 v0, v197, s55
	v_add_u32_e32 v0, 16, v0
	s_nop 1
	v_cvt_pk_bf16_f32 v66, v66, v67
	v_cvt_pk_bf16_f32 v67, v68, v69
	v_lshlrev_b32_e32 v68, 3, v196
	s_lshl_b32 s10, s18, 1
	v_add3_u32 v0, v0, v68, s10
	v_cvt_pk_bf16_f32 v68, v70, v71
	v_cvt_pk_bf16_f32 v69, v72, v73
	s_waitcnt vmcnt(0)
	s_barrier
; #define GAS __attribute__((address_space(1)))
; DI unsigned pk2(float a, float b) { f32x2 v = {a, b}; bf2_t r = __builtin_convertvector(v, bf2_t); return __builtin_bit_cast(unsigned, r); }
;     ...
; #pragma unroll
;     for (int i = 0; i < 2; ++i)
; #pragma unroll
;       for (int j = 0; j < 4; ++j)
; #pragma unroll
;         for (int g = 0; g < 4; ++g) {
;           u32x2 w; w.x = pk2(acc[i][j][4 * g], acc[i][j][4 * g + 1]); w.y = pk2(acc[i][j][4 * g + 2], acc[i][j][4 * g + 3]);
;           *(u32x2*)(smem + (wr * 64 + i * 32 + cl) * 528 + (wc * 128 + j * 32 + 8 * g + 4 * h) * 2) = w;
;         }
;   }
;   __syncthreads();
;   int tid2 = tid; asm volatile("" : "+v"(tid2));
;   if (EPI == 0) {
; #pragma unroll
;     for (int i = 0; i < 16; ++i) {
;       const int id = tid2 + 256 * i, r = id >> 5, c8 = (id & 31) * 8;
;       const u32x4 v = *(const u32x4*)(smem + r * 528 + c8 * 2);
;       *(GAS u32x4*)(ea.out + (size_t)(m0 + r) * ea.ldo + n0 + c8) = v;
;     }
;   } else {
;     const int L = (mt < 512) ? 2048 : 256;
;     const bool first = (m0 % L) == 0, last = ((m0 + 128) % L) == 0;
;     const float* cw = ea.cw; const float* cb = ea.cb;
; #pragma unroll 1
;     for (int p = 0; p < 2; ++p) {
;       const int j8 = (tid2 & 7) * 8;
;       const int ja0 = (nt * 2 + p) * 64, ja = ja0 + j8;
	ds_write2_b64 v0, v[66:67], v[68:69] offset1:2
	v_cvt_pk_bf16_f32 v66, v74, v75
	v_cvt_pk_bf16_f32 v67, v76, v77
	v_cvt_pk_bf16_f32 v68, v78, v79
	v_cvt_pk_bf16_f32 v69, v80, v81
	ds_write2_b64 v0, v[66:67], v[68:69] offset0:4 offset1:6
	v_cvt_pk_bf16_f32 v66, v82, v83
	v_cvt_pk_bf16_f32 v67, v84, v85
	v_cvt_pk_bf16_f32 v68, v86, v87
	v_cvt_pk_bf16_f32 v69, v88, v89
	ds_write2_b64 v0, v[66:67], v[68:69] offset0:8 offset1:10
	v_cvt_pk_bf16_f32 v66, v90, v91
	v_cvt_pk_bf16_f32 v67, v92, v93
	v_cvt_pk_bf16_f32 v68, v94, v95
	v_cvt_pk_bf16_f32 v69, v96, v97
	ds_write2_b64 v0, v[66:67], v[68:69] offset0:12 offset1:14
	v_cvt_pk_bf16_f32 v66, v114, v115
	v_cvt_pk_bf16_f32 v67, v116, v117
	v_cvt_pk_bf16_f32 v68, v118, v119
	v_cvt_pk_bf16_f32 v69, v120, v121
	ds_write2_b64 v0, v[66:67], v[68:69] offset0:16 offset1:18
	v_cvt_pk_bf16_f32 v66, v122, v123
	v_cvt_pk_bf16_f32 v67, v124, v125
	v_cvt_pk_bf16_f32 v68, v126, v127
	v_cvt_pk_bf16_f32 v69, v128, v129
	ds_write2_b64 v0, v[66:67], v[68:69] offset0:20 offset1:22
	v_cvt_pk_bf16_f32 v66, v98, v99
	v_cvt_pk_bf16_f32 v67, v100, v101
	v_cvt_pk_bf16_f32 v68, v102, v103
	v_cvt_pk_bf16_f32 v69, v104, v105
	ds_write2_b64 v0, v[66:67], v[68:69] offset0:24 offset1:26
	v_cvt_pk_bf16_f32 v66, v106, v107
	v_cvt_pk_bf16_f32 v67, v108, v109
	v_cvt_pk_bf16_f32 v68, v110, v111
	v_cvt_pk_bf16_f32 v69, v112, v113
	ds_write2_b64 v0, v[66:67], v[68:69] offset0:28 offset1:30
	v_add_u32_e32 v0, 0x4000, v0
	v_cvt_pk_bf16_f32 v2, v2, v3
	v_cvt_pk_bf16_f32 v3, v4, v5
	v_cvt_pk_bf16_f32 v4, v6, v7
	v_cvt_pk_bf16_f32 v5, v8, v9
	ds_write2_b64 v0, v[2:3], v[4:5] offset0:72 offset1:74
	v_cvt_pk_bf16_f32 v2, v10, v11
	v_cvt_pk_bf16_f32 v3, v12, v13
	v_cvt_pk_bf16_f32 v4, v14, v15
	v_cvt_pk_bf16_f32 v5, v16, v17
	ds_write2_b64 v0, v[2:3], v[4:5] offset0:76 offset1:78
	v_cvt_pk_bf16_f32 v2, v50, v51
	v_cvt_pk_bf16_f32 v3, v52, v53
	v_cvt_pk_bf16_f32 v4, v54, v55
	v_cvt_pk_bf16_f32 v5, v56, v57
	s_cmpk_lt_i32 s15, 0x200
	ds_write2_b64 v0, v[2:3], v[4:5] offset0:80 offset1:82
	v_cvt_pk_bf16_f32 v2, v58, v59
	v_cvt_pk_bf16_f32 v3, v60, v61
	v_cvt_pk_bf16_f32 v4, v62, v63
	v_cvt_pk_bf16_f32 v5, v64, v65
	s_cselect_b32 s10, 0x7ff, s78
	v_cvt_pk_bf16_f32 v18, v18, v19
	v_cvt_pk_bf16_f32 v19, v20, v21
	v_cvt_pk_bf16_f32 v20, v22, v23
	v_cvt_pk_bf16_f32 v21, v24, v25
	ds_write2_b64 v0, v[2:3], v[4:5] offset0:84 offset1:86
	v_cvt_pk_bf16_f32 v2, v34, v35
	v_cvt_pk_bf16_f32 v3, v36, v37
	v_cvt_pk_bf16_f32 v4, v38, v39
	v_cvt_pk_bf16_f32 v5, v40, v41
	s_and_b32 s11, s10, s46
	ds_write2_b64 v0, v[18:19], v[20:21] offset0:64 offset1:66
	v_cvt_pk_bf16_f32 v18, v26, v27
	v_cvt_pk_bf16_f32 v19, v28, v29
	v_cvt_pk_bf16_f32 v20, v30, v31
	v_cvt_pk_bf16_f32 v21, v32, v33
	ds_write2_b64 v0, v[2:3], v[4:5] offset0:88 offset1:90
	v_cvt_pk_bf16_f32 v2, v42, v43
	v_cvt_pk_bf16_f32 v3, v44, v45
	v_cvt_pk_bf16_f32 v4, v46, v47
	v_cvt_pk_bf16_f32 v5, v48, v49
	s_cmp_eq_u32 s11, 0
	ds_write2_b64 v0, v[18:19], v[20:21] offset0:68 offset1:70
	ds_write2_b64 v0, v[2:3], v[4:5] offset0:92 offset1:94
	s_waitcnt vmcnt(0) lgkmcnt(0)
	s_barrier
	s_cselect_b64 s[18:19], -1, 0
	s_add_i32 s11, s46, 0x80
	v_lshlrev_b32_e32 v0, 3, v189
	s_and_b32 s10, s11, s10
	v_and_b32_e32 v96, 56, v0
	s_cmp_eq_u32 s10, 0
	v_lshlrev_b32_e32 v0, 1, v96
	v_lshrrev_b32_e32 v98, 7, v189
	s_nop 0
	v_readfirstlane_b32 s40, v98
	s_cselect_b64 s[20:21], -1, 0
	s_lshl_b32 s47, s22, 7
	v_add_u32_e32 v97, 16, v0
	v_lshl_add_u64 v[90:91], s[44:45], 0, v[0:1]
	s_mov_b64 s[28:29], 0
	s_branch .LBB0_275
